# pre-barrier MFMA count 8 instead of 4 (all six GEMM loops)
# baseline (speedup 1.0000x reference)
; #define PG8_STAGE(bufoff, gbase, voff) do { _Pragma("unroll") for (int _i = 0; _i < 2; ++_i) \
;         __builtin_amdgcn_global_load_lds((const unsigned*)((const char*)(gbase) + (voff)[_i]), (LAS unsigned*)(lds + (bufoff) + ldsw + _i * 8192), 16, 0, 0); } while (0)
; #define PG8_LDA(dst, b, h) do { _Pragma("unroll") for (int m = 0; m < 4; ++m) _Pragma("unroll") for (int k = 0; k < 2; ++k) dst[m][k] = *(const LAS bf16x8*)(lds + PG8_SA(b, h) + aoff + m * 2048 + k * 1024); } while (0)
; #define PG8_LDB(dst, b, h) do { _Pragma("unroll") for (int n = 0; n < 2; ++n) _Pragma("unroll") for (int k = 0; k < 2; ++k) dst[n][k] = *(const LAS bf16x8*)(lds + PG8_SB(b, h) + boff + n * 2048 + k * 1024); } while (0)
; #define PG8_MMA(ai, bj, At, Bt) do { __builtin_amdgcn_s_setprio(1); _Pragma("unroll") for (int m = 0; m < 4; ++m) _Pragma("unroll") for (int n = 0; n < 2; ++n) _Pragma("unroll") for (int k = 0; k < 2; ++k) \
;         acc[ai][bj][m][n] = __builtin_amdgcn_mfma_f32_16x16x32_bf16(Bt[n][k], At[m][k], acc[ai][bj][m][n], 0, 0, 0); __builtin_amdgcn_s_setprio(0); } while (0)
; #define PG8_WAIT_L(n) asm volatile("s_waitcnt lgkmcnt(" #n ")" ::: "memory")
; #define PG8_BAR __builtin_amdgcn_s_barrier()
; #define PG8_SCHED __builtin_amdgcn_sched_barrier(0)
; template <class Epi>
; __device__ __forceinline__ void gemm_phase(LAS unsigned char* lds, const Gemm g, const Sched& S, const Epi& E) {
;     ...
;         for (int t = 0; t < nt; t += 2) {
;             const bool last = (t == nt - 2);
;             const char* a1 = cA + (size_t)(t + 1) * kstep;
;             const char* a2 = last ? nA : cA + (size_t)(t + 2) * kstep; const char* b2 = last ? nB : cB + (size_t)(t + 2) * kstep;
;             const char* a3 = a2 + kstep; const char* b3 = b2 + kstep;
;             PG8_LDB(B0, 0, 0); PG8_SCHED; PG8_LDA(At, 0, 0); PG8_STAGE(PG8_SA(1, 1), a1 + hstepA, voffA);
;             PG8_WAIT_L(8); PG8_BAR; PG8_WAIT_L(0); PG8_MMA(0, 0, At, B0); PG8_BAR; PG8_SCHED;
;             PG8_LDB(B1, 0, 1); PG8_STAGE(PG8_SB(0, 0), b2, voffB);
;             PG8_BAR; PG8_WAIT_L(0); PG8_MMA(0, 1, At, B1); PG8_BAR;
;             PG8_LDA(At, 0, 1); PG8_STAGE(PG8_SA(0, 0), a2, voffA);
;             PG8_BAR; PG8_WAIT_L(0); PG8_MMA(1, 0, At, B0); PG8_BAR; PG8_SCHED;
.LBB0_400:
	s_add_i32 s14, s66, 2
	s_add_u32 s8, s92, 0x80
	s_addc_u32 s9, s93, 0
	s_add_i32 s15, 0, 0x10000
	v_add_u32_e32 v148, s15, v152
	ds_read_b128 v[144:147], v148
	ds_read_b128 v[172:175], v148 offset:1024
	ds_read_b128 v[176:179], v148 offset:2048
	ds_read_b128 v[180:183], v148 offset:3072
	s_cmp_eq_u32 s71, s66
	s_cselect_b32 s95, s55, s9
	s_cselect_b32 s94, s57, s8
	s_cselect_b32 s97, s59, s35
	s_cselect_b32 s96, s65, s34
	v_lshl_add_u64 v[148:149], s[92:93], 0, v[138:139]
	s_add_i32 m0, s42, 0xc000
	ds_read_b128 v[184:187], v171
	ds_read_b128 v[188:191], v171 offset:1024
	ds_read_b128 v[196:199], v171 offset:2048
	ds_read_b128 v[200:203], v171 offset:3072
	ds_read_b128 v[204:207], v171 offset:4096
	ds_read_b128 v[208:211], v171 offset:5120
	ds_read_b128 v[212:215], v171 offset:6144
	ds_read_b128 v[222:225], v171 offset:7168
	global_load_lds_dwordx4 v[148:149], off
	v_lshl_add_u64 v[148:149], s[92:93], 0, v[140:141]
	s_add_i32 m0, s42, 0xe000
	s_nop 0
	global_load_lds_dwordx4 v[148:149], off
	s_add_i32 s8, 0, 0x14000
	v_add_u32_e32 v148, s8, v152
	ds_read_b128 v[226:229], v148
	ds_read_b128 v[230:233], v148 offset:1024
	ds_read_b128 v[234:237], v148 offset:2048
	ds_read_b128 v[238:241], v148 offset:3072
	s_waitcnt vmcnt(8)
	s_waitcnt lgkmcnt(0)
	v_mfma_f32_16x16x32_bf16 v[126:129], v[144:147], v[184:187], v[126:129]
	v_mfma_f32_16x16x32_bf16 v[122:125], v[176:179], v[184:187], v[122:125]
	v_mfma_f32_16x16x32_bf16 v[110:113], v[144:147], v[196:199], v[110:113]
	v_mfma_f32_16x16x32_bf16 v[106:109], v[176:179], v[196:199], v[106:109]
	v_mfma_f32_16x16x32_bf16 v[94:97], v[144:147], v[204:207], v[94:97]
	v_mfma_f32_16x16x32_bf16 v[90:93], v[176:179], v[204:207], v[90:93]
	v_mfma_f32_16x16x32_bf16 v[78:81], v[144:147], v[212:215], v[78:81]
	v_mfma_f32_16x16x32_bf16 v[74:77], v[176:179], v[212:215], v[74:77]
	s_barrier
	s_setprio 1
	v_mfma_f32_16x16x32_bf16 v[126:129], v[172:175], v[188:191], v[126:129]
	v_mfma_f32_16x16x32_bf16 v[122:125], v[180:183], v[188:191], v[122:125]
	v_mfma_f32_16x16x32_bf16 v[110:113], v[172:175], v[200:203], v[110:113]
	v_mfma_f32_16x16x32_bf16 v[106:109], v[180:183], v[200:203], v[106:109]
	v_mfma_f32_16x16x32_bf16 v[94:97], v[172:175], v[208:211], v[94:97]
	v_mfma_f32_16x16x32_bf16 v[90:93], v[180:183], v[208:211], v[90:93]
	v_mfma_f32_16x16x32_bf16 v[78:81], v[172:175], v[222:225], v[78:81]
	v_mfma_f32_16x16x32_bf16 v[74:77], v[180:183], v[222:225], v[74:77]
	v_mfma_f32_16x16x32_bf16 v[118:121], v[226:229], v[184:187], v[118:121]
	v_mfma_f32_16x16x32_bf16 v[114:117], v[234:237], v[184:187], v[114:117]
	v_mfma_f32_16x16x32_bf16 v[102:105], v[226:229], v[196:199], v[102:105]
	v_mfma_f32_16x16x32_bf16 v[98:101], v[234:237], v[196:199], v[98:101]
	v_mfma_f32_16x16x32_bf16 v[86:89], v[226:229], v[204:207], v[86:89]
	v_mfma_f32_16x16x32_bf16 v[82:85], v[234:237], v[204:207], v[82:85]
	v_mfma_f32_16x16x32_bf16 v[70:73], v[226:229], v[212:215], v[70:73]
	v_mfma_f32_16x16x32_bf16 v[66:69], v[234:237], v[212:215], v[66:69]
	v_mfma_f32_16x16x32_bf16 v[118:121], v[230:233], v[188:191], v[118:121]
	v_mfma_f32_16x16x32_bf16 v[114:117], v[238:241], v[188:191], v[114:117]
	v_mfma_f32_16x16x32_bf16 v[102:105], v[230:233], v[200:203], v[102:105]
	v_mfma_f32_16x16x32_bf16 v[98:101], v[238:241], v[200:203], v[98:101]
	v_mfma_f32_16x16x32_bf16 v[86:89], v[230:233], v[208:211], v[86:89]
	v_mfma_f32_16x16x32_bf16 v[82:85], v[238:241], v[208:211], v[82:85]
	v_mfma_f32_16x16x32_bf16 v[70:73], v[230:233], v[222:225], v[70:73]
	v_mfma_f32_16x16x32_bf16 v[66:69], v[238:241], v[222:225], v[66:69]
	s_setprio 0
	s_barrier
	s_add_i32 s9, s15, s39
	v_lshl_add_u64 v[148:149], s[96:97], 0, v[132:133]
	s_mov_b32 m0, s9
	v_lshl_add_u64 v[192:193], s[96:97], 0, v[136:137]
	global_load_lds_dwordx4 v[148:149], off
	s_add_i32 m0, s9, 0x2000
	s_nop 0
	global_load_lds_dwordx4 v[192:193], off
	s_mov_b32 m0, s42
	v_lshl_add_u64 v[194:195], s[94:95], 0, v[130:131]
	ds_read_b128 v[184:187], v171 offset:16384
	ds_read_b128 v[188:191], v171 offset:17408
	ds_read_b128 v[196:199], v171 offset:18432
	ds_read_b128 v[200:203], v171 offset:19456
	ds_read_b128 v[204:207], v171 offset:20480
	ds_read_b128 v[208:211], v171 offset:21504
	ds_read_b128 v[212:215], v171 offset:22528
	ds_read_b128 v[222:225], v171 offset:23552
	global_load_lds_dwordx4 v[194:195], off
	v_lshl_add_u64 v[216:217], s[94:95], 0, v[134:135]
	s_mov_b32 m0, s43
	s_nop 0
	global_load_lds_dwordx4 v[216:217], off
	s_add_u32 s96, s96, s78
	s_addc_u32 s97, s97, s79
	s_add_i32 s8, s8, s39
	v_lshl_add_u64 v[242:243], s[96:97], 0, v[132:133]
	s_mov_b32 m0, s8
	v_lshl_add_u64 v[244:245], s[96:97], 0, v[136:137]
	global_load_lds_dwordx4 v[242:243], off
	s_add_i32 m0, s8, 0x2000
	s_nop 0
	global_load_lds_dwordx4 v[244:245], off
	s_waitcnt vmcnt(8)
	s_waitcnt lgkmcnt(0)
	v_mfma_f32_16x16x32_bf16 v[62:65], v[144:147], v[184:187], v[62:65]
	v_mfma_f32_16x16x32_bf16 v[58:61], v[176:179], v[184:187], v[58:61]
	v_mfma_f32_16x16x32_bf16 v[50:53], v[144:147], v[196:199], v[50:53]
	v_mfma_f32_16x16x32_bf16 v[42:45], v[176:179], v[196:199], v[42:45]
	v_mfma_f32_16x16x32_bf16 v[34:37], v[144:147], v[204:207], v[34:37]
	v_mfma_f32_16x16x32_bf16 v[26:29], v[176:179], v[204:207], v[26:29]
	v_mfma_f32_16x16x32_bf16 v[18:21], v[144:147], v[212:215], v[18:21]
	v_mfma_f32_16x16x32_bf16 v[10:13], v[176:179], v[212:215], v[10:13]
	s_barrier
; #define PG8_STAGE(bufoff, gbase, voff) do { _Pragma("unroll") for (int _i = 0; _i < 2; ++_i) \
;         __builtin_amdgcn_global_load_lds((const unsigned*)((const char*)(gbase) + (voff)[_i]), (LAS unsigned*)(lds + (bufoff) + ldsw + _i * 8192), 16, 0, 0); } while (0)
; #define PG8_LDA(dst, b, h) do { _Pragma("unroll") for (int m = 0; m < 4; ++m) _Pragma("unroll") for (int k = 0; k < 2; ++k) dst[m][k] = *(const LAS bf16x8*)(lds + PG8_SA(b, h) + aoff + m * 2048 + k * 1024); } while (0)
; #define PG8_LDB(dst, b, h) do { _Pragma("unroll") for (int n = 0; n < 2; ++n) _Pragma("unroll") for (int k = 0; k < 2; ++k) dst[n][k] = *(const LAS bf16x8*)(lds + PG8_SB(b, h) + boff + n * 2048 + k * 1024); } while (0)
; #define PG8_WAIT_V(n) asm volatile("s_waitcnt vmcnt(" #n ")" ::: "memory")
; #define PG8_WAIT_L(n) asm volatile("s_waitcnt lgkmcnt(" #n ")" ::: "memory")
; #define PG8_BAR __builtin_amdgcn_s_barrier()
; #define PG8_SCHED __builtin_amdgcn_sched_barrier(0)
; template <class Epi>
; __device__ __forceinline__ void gemm_phase(LAS unsigned char* lds, const Gemm g, const Sched& S, const Epi& E) {
;     ...
;             PG8_LDB(B0, 0, 0); PG8_SCHED; PG8_LDA(At, 0, 0); PG8_STAGE(PG8_SA(1, 1), a1 + hstepA, voffA);
;             PG8_WAIT_L(8); PG8_BAR; PG8_WAIT_L(0); PG8_MMA(0, 0, At, B0); PG8_BAR; PG8_SCHED;
;             PG8_LDB(B1, 0, 1); PG8_STAGE(PG8_SB(0, 0), b2, voffB);
;             PG8_BAR; PG8_WAIT_L(0); PG8_MMA(0, 1, At, B1); PG8_BAR;
;             PG8_LDA(At, 0, 1); PG8_STAGE(PG8_SA(0, 0), a2, voffA);
;             PG8_BAR; PG8_WAIT_L(0); PG8_MMA(1, 0, At, B0); PG8_BAR; PG8_SCHED;
;             PG8_STAGE(PG8_SB(0, 1), b2 + hstepB, voffB);
;             PG8_WAIT_V(6); PG8_BAR; PG8_MMA(1, 1, At, B1); PG8_BAR;
;             PG8_LDB(B0, 1, 0); PG8_SCHED; PG8_LDA(At, 1, 0); PG8_STAGE(PG8_SA(0, 1), a2 + hstepA, voffA);
;             PG8_WAIT_L(8); PG8_BAR; PG8_WAIT_L(0); PG8_MMA(0, 0, At, B0); PG8_BAR; PG8_SCHED;
;             PG8_LDB(B1, 1, 1); PG8_STAGE(PG8_SB(1, 0), b3, voffB);
;             PG8_BAR; PG8_WAIT_L(0); PG8_MMA(0, 1, At, B1); PG8_BAR;
;             PG8_LDA(At, 1, 1); PG8_STAGE(PG8_SA(1, 0), a3, voffA);
;             PG8_BAR; PG8_WAIT_L(0); PG8_MMA(1, 0, At, B0); PG8_BAR; PG8_SCHED;
;             PG8_STAGE(PG8_SB(1, 1), b3 + hstepB, voffB);
;             PG8_WAIT_V(6); PG8_BAR; PG8_MMA(1, 1, At, B1); PG8_BAR;
	s_setprio 1
	v_mfma_f32_16x16x32_bf16 v[62:65], v[172:175], v[188:191], v[62:65]
	v_mfma_f32_16x16x32_bf16 v[58:61], v[180:183], v[188:191], v[58:61]
	v_mfma_f32_16x16x32_bf16 v[50:53], v[172:175], v[200:203], v[50:53]
	v_mfma_f32_16x16x32_bf16 v[42:45], v[180:183], v[200:203], v[42:45]
	v_mfma_f32_16x16x32_bf16 v[34:37], v[172:175], v[208:211], v[34:37]
	v_mfma_f32_16x16x32_bf16 v[26:29], v[180:183], v[208:211], v[26:29]
	v_mfma_f32_16x16x32_bf16 v[18:21], v[172:175], v[222:225], v[18:21]
	v_mfma_f32_16x16x32_bf16 v[10:13], v[180:183], v[222:225], v[10:13]
	v_mfma_f32_16x16x32_bf16 v[54:57], v[226:229], v[184:187], v[54:57]
	v_mfma_f32_16x16x32_bf16 v[46:49], v[234:237], v[184:187], v[46:49]
	v_mfma_f32_16x16x32_bf16 v[38:41], v[226:229], v[196:199], v[38:41]
	v_mfma_f32_16x16x32_bf16 v[30:33], v[234:237], v[196:199], v[30:33]
	v_mfma_f32_16x16x32_bf16 v[22:25], v[226:229], v[204:207], v[22:25]
	v_mfma_f32_16x16x32_bf16 v[14:17], v[234:237], v[204:207], v[14:17]
	v_mfma_f32_16x16x32_bf16 v[6:9], v[226:229], v[212:215], v[6:9]
	v_mfma_f32_16x16x32_bf16 v[2:5], v[234:237], v[212:215], v[2:5]
	v_mfma_f32_16x16x32_bf16 v[54:57], v[230:233], v[188:191], v[54:57]
	v_mfma_f32_16x16x32_bf16 v[46:49], v[238:241], v[188:191], v[46:49]
	v_mfma_f32_16x16x32_bf16 v[38:41], v[230:233], v[200:203], v[38:41]
	v_mfma_f32_16x16x32_bf16 v[30:33], v[238:241], v[200:203], v[30:33]
	v_mfma_f32_16x16x32_bf16 v[22:25], v[230:233], v[208:211], v[22:25]
	v_mfma_f32_16x16x32_bf16 v[14:17], v[238:241], v[208:211], v[14:17]
	v_mfma_f32_16x16x32_bf16 v[6:9], v[230:233], v[222:225], v[6:9]
	v_mfma_f32_16x16x32_bf16 v[2:5], v[238:241], v[222:225], v[2:5]
	s_setprio 0
	s_barrier
	s_add_i32 s8, 0, 0x18000
	v_add_u32_e32 v180, s8, v152
	ds_read_b128 v[144:147], v180
	ds_read_b128 v[172:175], v180 offset:1024
	ds_read_b128 v[176:179], v180 offset:2048
	ds_read_b128 v[180:183], v180 offset:3072
	s_add_u32 s94, s94, s4
	s_addc_u32 s95, s95, s5
	s_mov_b32 m0, s52
	v_lshl_add_u64 v[226:227], s[94:95], 0, v[130:131]
	ds_read_b128 v[184:187], v171 offset:32768
	ds_read_b128 v[188:191], v171 offset:33792
	ds_read_b128 v[196:199], v171 offset:34816
	ds_read_b128 v[200:203], v171 offset:35840
	ds_read_b128 v[204:207], v171 offset:36864
	ds_read_b128 v[208:211], v171 offset:37888
	ds_read_b128 v[212:215], v171 offset:38912
	ds_read_b128 v[222:225], v171 offset:39936
	global_load_lds_dwordx4 v[226:227], off
	v_lshl_add_u64 v[226:227], s[94:95], 0, v[134:135]
	s_mov_b32 m0, s53
	s_nop 0
	global_load_lds_dwordx4 v[226:227], off
	s_add_i32 s9, 0, 0x1c000
	v_add_u32_e32 v218, s9, v152
	ds_read_b128 v[226:229], v218
	ds_read_b128 v[230:233], v218 offset:1024
	ds_read_b128 v[234:237], v218 offset:2048
	ds_read_b128 v[238:241], v218 offset:3072
	s_waitcnt vmcnt(8)
	s_waitcnt lgkmcnt(0)
	v_mfma_f32_16x16x32_bf16 v[126:129], v[144:147], v[184:187], v[126:129]
	v_mfma_f32_16x16x32_bf16 v[122:125], v[176:179], v[184:187], v[122:125]
	v_mfma_f32_16x16x32_bf16 v[110:113], v[144:147], v[196:199], v[110:113]
	v_mfma_f32_16x16x32_bf16 v[106:109], v[176:179], v[196:199], v[106:109]
	v_mfma_f32_16x16x32_bf16 v[94:97], v[144:147], v[204:207], v[94:97]
	v_mfma_f32_16x16x32_bf16 v[90:93], v[176:179], v[204:207], v[90:93]
	v_mfma_f32_16x16x32_bf16 v[78:81], v[144:147], v[212:215], v[78:81]
	v_mfma_f32_16x16x32_bf16 v[74:77], v[176:179], v[212:215], v[74:77]
	s_barrier
	s_setprio 1
	v_mfma_f32_16x16x32_bf16 v[126:129], v[172:175], v[188:191], v[126:129]
	v_mfma_f32_16x16x32_bf16 v[122:125], v[180:183], v[188:191], v[122:125]
	v_mfma_f32_16x16x32_bf16 v[110:113], v[172:175], v[200:203], v[110:113]
	v_mfma_f32_16x16x32_bf16 v[106:109], v[180:183], v[200:203], v[106:109]
	v_mfma_f32_16x16x32_bf16 v[94:97], v[172:175], v[208:211], v[94:97]
	v_mfma_f32_16x16x32_bf16 v[90:93], v[180:183], v[208:211], v[90:93]
	v_mfma_f32_16x16x32_bf16 v[78:81], v[172:175], v[222:225], v[78:81]
	v_mfma_f32_16x16x32_bf16 v[74:77], v[180:183], v[222:225], v[74:77]
	v_mfma_f32_16x16x32_bf16 v[118:121], v[226:229], v[184:187], v[118:121]
	v_mfma_f32_16x16x32_bf16 v[114:117], v[234:237], v[184:187], v[114:117]
	v_mfma_f32_16x16x32_bf16 v[102:105], v[226:229], v[196:199], v[102:105]
	v_mfma_f32_16x16x32_bf16 v[98:101], v[234:237], v[196:199], v[98:101]
	v_mfma_f32_16x16x32_bf16 v[86:89], v[226:229], v[204:207], v[86:89]
	v_mfma_f32_16x16x32_bf16 v[82:85], v[234:237], v[204:207], v[82:85]
	v_mfma_f32_16x16x32_bf16 v[70:73], v[226:229], v[212:215], v[70:73]
	v_mfma_f32_16x16x32_bf16 v[66:69], v[234:237], v[212:215], v[66:69]
	v_mfma_f32_16x16x32_bf16 v[118:121], v[230:233], v[188:191], v[118:121]
	v_mfma_f32_16x16x32_bf16 v[114:117], v[238:241], v[188:191], v[114:117]
	v_mfma_f32_16x16x32_bf16 v[102:105], v[230:233], v[200:203], v[102:105]
	v_mfma_f32_16x16x32_bf16 v[98:101], v[238:241], v[200:203], v[98:101]
	v_mfma_f32_16x16x32_bf16 v[86:89], v[230:233], v[208:211], v[86:89]
	v_mfma_f32_16x16x32_bf16 v[82:85], v[238:241], v[208:211], v[82:85]
	v_mfma_f32_16x16x32_bf16 v[70:73], v[230:233], v[222:225], v[70:73]
	v_mfma_f32_16x16x32_bf16 v[66:69], v[238:241], v[222:225], v[66:69]
	s_setprio 0
	s_barrier
; __device__ __forceinline__ float pre_get(const Pre& p, int ai, int m, int fr) { return __shfl(p.v[ai], m * 16 + fr); }
; __device__ __forceinline__ float rstd_pre(const float* ss, float v) { return ss ? rsqrtf(v * (1.0f / 2048.0f) + 1e-6f) : 1.0f; }
; #define PG8_STAGE(bufoff, gbase, voff) do { _Pragma("unroll") for (int _i = 0; _i < 2; ++_i) \
;         __builtin_amdgcn_global_load_lds((const unsigned*)((const char*)(gbase) + (voff)[_i]), (LAS unsigned*)(lds + (bufoff) + ldsw + _i * 8192), 16, 0, 0); } while (0)
; #define PG8_LDA(dst, b, h) do { _Pragma("unroll") for (int m = 0; m < 4; ++m) _Pragma("unroll") for (int k = 0; k < 2; ++k) dst[m][k] = *(const LAS bf16x8*)(lds + PG8_SA(b, h) + aoff + m * 2048 + k * 1024); } while (0)
; template <class Epi>
; __device__ __forceinline__ void gemm_phase(LAS unsigned char* lds, const Gemm g, const Sched& S, const Epi& E) {
;     ...
;             PG8_WAIT_V(6); PG8_BAR; PG8_MMA(1, 1, At, B1); PG8_BAR;
;             PG8_LDB(B0, 1, 0); PG8_SCHED; PG8_LDA(At, 1, 0); PG8_STAGE(PG8_SA(0, 1), a2 + hstepA, voffA);
;             PG8_WAIT_L(8); PG8_BAR; PG8_WAIT_L(0); PG8_MMA(0, 0, At, B0); PG8_BAR; PG8_SCHED;
;             PG8_LDB(B1, 1, 1); PG8_STAGE(PG8_SB(1, 0), b3, voffB);
;             PG8_BAR; PG8_WAIT_L(0); PG8_MMA(0, 1, At, B1); PG8_BAR;
;             PG8_LDA(At, 1, 1); PG8_STAGE(PG8_SA(1, 0), a3, voffA);
;             PG8_BAR; PG8_WAIT_L(0); PG8_MMA(1, 0, At, B0); PG8_BAR; PG8_SCHED;
;             PG8_STAGE(PG8_SB(1, 1), b3 + hstepB, voffB);
;             PG8_WAIT_V(6); PG8_BAR; PG8_MMA(1, 1, At, B1); PG8_BAR;
;         }
;     __device__ __forceinline__ void operator()(const Acc& acc, const Unit& u, int wr, int wc, int fr, int fq, const Pre& pre) const {
;     ...
;             for (int m = 0; m < 4; ++m) rs[ai][m] = rstd_pre(ss, pre_get(pre, ai, m, fr));
; #pragma unroll
;         for (int ai = 0; ai < 2; ++ai)
; #pragma unroll
;             for (int m = 0; m < 4; ++m) { float mx = -INFINITY;
; #pragma unroll
;                 for (int bj = 0; bj < 2; ++bj)
; #pragma unroll
;                     for (int n = 0; n < 2; ++n) { const f32x4 a = acc[ai][bj][m][n]; mx = fmaxf(mx, fmaxf(fmaxf(a[0], a[1]), fmaxf(a[2], a[3]))); }
;                 mx *= rs[ai][m];
;                 mx = fmaxf(mx, __shfl_xor(mx, 16)); mx = fmaxf(mx, __shfl_xor(mx, 32));
;                 if (fq == 0) X[(ai * 128 + wr * 64 + m * 16 + fr) * 4 + wc] = mx; }
	s_add_i32 s8, s8, s39
	v_lshl_add_u64 v[148:149], v[148:149], 0, s[60:61]
	s_mov_b32 m0, s8
	s_nop 0
	global_load_lds_dwordx4 v[148:149], off
	v_lshl_add_u64 v[148:149], v[192:193], 0, s[60:61]
	s_add_i32 m0, s8, 0x2000
	s_nop 0
	global_load_lds_dwordx4 v[148:149], off
	s_mov_b32 m0, s67
	v_lshl_add_u64 v[148:149], v[194:195], 0, s[60:61]
	ds_read_b128 v[184:187], v171 offset:49152
	ds_read_b128 v[188:191], v171 offset:50176
	ds_read_b128 v[196:199], v171 offset:51200
	ds_read_b128 v[200:203], v171 offset:52224
	ds_read_b128 v[204:207], v171 offset:53248
	ds_read_b128 v[208:211], v171 offset:54272
	ds_read_b128 v[212:215], v171 offset:55296
	ds_read_b128 v[222:225], v171 offset:56320
	global_load_lds_dwordx4 v[148:149], off
	v_lshl_add_u64 v[148:149], v[216:217], 0, s[60:61]
	s_mov_b32 m0, s2
	s_nop 0
	global_load_lds_dwordx4 v[148:149], off
	s_add_i32 s8, s9, s39
	v_lshl_add_u64 v[148:149], v[242:243], 0, s[60:61]
	s_mov_b32 m0, s8
	s_nop 0
	global_load_lds_dwordx4 v[148:149], off
	v_lshl_add_u64 v[148:149], v[244:245], 0, s[60:61]
	s_add_i32 m0, s8, 0x2000
	s_nop 0
	global_load_lds_dwordx4 v[148:149], off
	s_waitcnt vmcnt(8)
	s_waitcnt lgkmcnt(0)
	v_mfma_f32_16x16x32_bf16 v[62:65], v[144:147], v[184:187], v[62:65]
	v_mfma_f32_16x16x32_bf16 v[58:61], v[176:179], v[184:187], v[58:61]
	v_mfma_f32_16x16x32_bf16 v[50:53], v[144:147], v[196:199], v[50:53]
	v_mfma_f32_16x16x32_bf16 v[42:45], v[176:179], v[196:199], v[42:45]
	v_mfma_f32_16x16x32_bf16 v[34:37], v[144:147], v[204:207], v[34:37]
	v_mfma_f32_16x16x32_bf16 v[26:29], v[176:179], v[204:207], v[26:29]
	v_mfma_f32_16x16x32_bf16 v[18:21], v[144:147], v[212:215], v[18:21]
	v_mfma_f32_16x16x32_bf16 v[10:13], v[176:179], v[212:215], v[10:13]
	s_barrier
	s_setprio 1
	v_mfma_f32_16x16x32_bf16 v[62:65], v[172:175], v[188:191], v[62:65]
	v_mfma_f32_16x16x32_bf16 v[58:61], v[180:183], v[188:191], v[58:61]
	v_mfma_f32_16x16x32_bf16 v[50:53], v[172:175], v[200:203], v[50:53]
	v_mfma_f32_16x16x32_bf16 v[42:45], v[180:183], v[200:203], v[42:45]
	v_mfma_f32_16x16x32_bf16 v[34:37], v[172:175], v[208:211], v[34:37]
	v_mfma_f32_16x16x32_bf16 v[26:29], v[180:183], v[208:211], v[26:29]
	v_mfma_f32_16x16x32_bf16 v[18:21], v[172:175], v[222:225], v[18:21]
	v_mfma_f32_16x16x32_bf16 v[10:13], v[180:183], v[222:225], v[10:13]
	v_mfma_f32_16x16x32_bf16 v[54:57], v[226:229], v[184:187], v[54:57]
	v_mfma_f32_16x16x32_bf16 v[46:49], v[234:237], v[184:187], v[46:49]
	v_mfma_f32_16x16x32_bf16 v[38:41], v[226:229], v[196:199], v[38:41]
	v_mfma_f32_16x16x32_bf16 v[30:33], v[234:237], v[196:199], v[30:33]
	v_mfma_f32_16x16x32_bf16 v[22:25], v[226:229], v[204:207], v[22:25]
	v_mfma_f32_16x16x32_bf16 v[14:17], v[234:237], v[204:207], v[14:17]
	v_mfma_f32_16x16x32_bf16 v[6:9], v[226:229], v[212:215], v[6:9]
	v_mfma_f32_16x16x32_bf16 v[2:5], v[234:237], v[212:215], v[2:5]
	v_mfma_f32_16x16x32_bf16 v[54:57], v[230:233], v[188:191], v[54:57]
	v_mfma_f32_16x16x32_bf16 v[46:49], v[238:241], v[188:191], v[46:49]
	v_mfma_f32_16x16x32_bf16 v[38:41], v[230:233], v[200:203], v[38:41]
	v_mfma_f32_16x16x32_bf16 v[30:33], v[238:241], v[200:203], v[30:33]
	v_mfma_f32_16x16x32_bf16 v[22:25], v[230:233], v[208:211], v[22:25]
	v_mfma_f32_16x16x32_bf16 v[14:17], v[238:241], v[208:211], v[14:17]
	v_mfma_f32_16x16x32_bf16 v[6:9], v[230:233], v[222:225], v[6:9]
	v_mfma_f32_16x16x32_bf16 v[2:5], v[238:241], v[222:225], v[2:5]
	s_setprio 0
	s_add_u32 s92, s92, 0x100
	s_addc_u32 s93, s93, 0
	s_add_u32 s34, s34, 0x100
	s_addc_u32 s35, s35, 0
	s_cmp_ge_u32 s14, s73
	s_mov_b32 s66, s14
	s_barrier
	s_cbranch_scc0 .LBB0_400
	v_and_b32_e32 v144, 64, v220
	v_or_b32_e32 v144, v144, v150
	v_lshlrev_b32_e32 v172, 2, v144
	ds_bpermute_b32 v145, v172, v143
	ds_bpermute_b32 v144, v172, v143 offset:64
	s_mov_b32 s8, 0x3a000000
	v_mov_b32_e32 v232, 0x358637bd
	s_mov_b32 s97, 0x800000
	ds_bpermute_b32 v147, v172, v143 offset:128
	s_waitcnt lgkmcnt(0)
	v_pk_fma_f32 v[148:149], v[144:145], s[8:9], v[232:233] op_sel_hi:[1,0,0]
	ds_bpermute_b32 v146, v172, v143 offset:192
	v_mul_f32_e32 v143, 0x4b800000, v149
	v_cmp_gt_f32_e32 vcc, s97, v149
	v_max_f32_e32 v174, v128, v128
	v_max_f32_e32 v175, v124, v124
	v_cndmask_b32_e32 v143, v149, v143, vcc
	v_rsq_f32_e32 v149, v143
	v_max_f32_e32 v176, v116, v116
	ds_bpermute_b32 v145, v172, v142
	ds_bpermute_b32 v144, v172, v142 offset:64
	v_mul_f32_e32 v173, 0x45800000, v149
	v_cndmask_b32_e32 v149, v149, v173, vcc
	v_max_f32_e32 v173, v129, v129
	v_max_f32_e32 v173, v174, v173
	v_max_f32_e32 v174, v125, v125
	v_max_f32_e32 v174, v175, v174
	v_max3_f32 v173, v126, v127, v173
	v_max3_f32 v174, v122, v123, v174
	v_max3_f32 v173, v173, s72, v174
	v_max_f32_e32 v174, v121, v121
	v_max_f32_e32 v175, v120, v120
	v_max_f32_e32 v174, v175, v174
	v_max_f32_e32 v175, v117, v117
	v_max_f32_e32 v175, v176, v175
	v_cmp_lt_i32_e32 vcc, v221, v247
	v_max3_f32 v174, v118, v119, v174
	v_max3_f32 v175, v114, v115, v175
	v_cndmask_b32_e64 v177, v149, 1.0, s[80:81]
	v_cndmask_b32_e32 v149, v220, v221, vcc
	v_max3_f32 v173, v173, v174, v175
	v_lshlrev_b32_e32 v149, 2, v149
	v_mul_f32_e32 v173, v173, v177
	ds_bpermute_b32 v174, v149, v173
	v_cmp_lt_i32_e32 vcc, v248, v247
	ds_bpermute_b32 v143, v172, v142 offset:128
	ds_bpermute_b32 v142, v172, v142 offset:192
	v_cndmask_b32_e32 v172, v220, v248, vcc
	s_waitcnt lgkmcnt(0)
	v_max_f32_e32 v174, v174, v174
	v_lshlrev_b32_e32 v172, 2, v172
	v_max_f32_e32 v173, v173, v174
	ds_bpermute_b32 v174, v172, v173
	v_cmp_gt_f32_e32 vcc, s97, v148
	v_add_u32_e32 v178, s51, v154
	s_and_saveexec_b64 s[92:93], s[0:1]
	s_cbranch_execz .LBB0_403
	s_waitcnt lgkmcnt(0)
	v_max_f32_e32 v174, v174, v174
	v_max_f32_e32 v173, v173, v173
	v_max_f32_e32 v173, v173, v174
	ds_write_b32 v178, v173

; #define PG8_STAGE(bufoff, gbase, voff) do { _Pragma("unroll") for (int _i = 0; _i < 2; ++_i) \
;         __builtin_amdgcn_global_load_lds((const unsigned*)((const char*)(gbase) + (voff)[_i]), (LAS unsigned*)(lds + (bufoff) + ldsw + _i * 8192), 16, 0, 0); } while (0)
; #define PG8_LDA(dst, b, h) do { _Pragma("unroll") for (int m = 0; m < 4; ++m) _Pragma("unroll") for (int k = 0; k < 2; ++k) dst[m][k] = *(const LAS bf16x8*)(lds + PG8_SA(b, h) + aoff + m * 2048 + k * 1024); } while (0)
; #define PG8_WAIT_V(n) asm volatile("s_waitcnt vmcnt(" #n ")" ::: "memory")
; #define PG8_WAIT_L(n) asm volatile("s_waitcnt lgkmcnt(" #n ")" ::: "memory")
; template <class Epi>
; __device__ __forceinline__ void gemm_phase(LAS unsigned char* lds, const Gemm g, const Sched& S, const Epi& E) {
;     ...
;         for (int t = 0; t < nt; t += 2) {
;             const bool last = (t == nt - 2);
;             const char* a1 = cA + (size_t)(t + 1) * kstep;
;             const char* a2 = last ? nA : cA + (size_t)(t + 2) * kstep; const char* b2 = last ? nB : cB + (size_t)(t + 2) * kstep;
;             const char* a3 = a2 + kstep; const char* b3 = b2 + kstep;
;             PG8_LDB(B0, 0, 0); PG8_SCHED; PG8_LDA(At, 0, 0); PG8_STAGE(PG8_SA(1, 1), a1 + hstepA, voffA);
;             PG8_WAIT_L(8); PG8_BAR; PG8_WAIT_L(0); PG8_MMA(0, 0, At, B0); PG8_BAR; PG8_SCHED;
;             PG8_LDB(B1, 0, 1); PG8_STAGE(PG8_SB(0, 0), b2, voffB);
;             PG8_BAR; PG8_WAIT_L(0); PG8_MMA(0, 1, At, B1); PG8_BAR;
;             PG8_LDA(At, 0, 1); PG8_STAGE(PG8_SA(0, 0), a2, voffA);
;             PG8_BAR; PG8_WAIT_L(0); PG8_MMA(1, 0, At, B0); PG8_BAR; PG8_SCHED;
;             PG8_STAGE(PG8_SB(0, 1), b2 + hstepB, voffB);
;             PG8_WAIT_V(6); PG8_BAR; PG8_MMA(1, 1, At, B1); PG8_BAR;
;             PG8_LDB(B0, 1, 0); PG8_SCHED; PG8_LDA(At, 1, 0); PG8_STAGE(PG8_SA(0, 1), a2 + hstepA, voffA);
;             PG8_WAIT_L(8); PG8_BAR; PG8_WAIT_L(0); PG8_MMA(0, 0, At, B0); PG8_BAR; PG8_SCHED;
;             PG8_LDB(B1, 1, 1); PG8_STAGE(PG8_SB(1, 0), b3, voffB);
;             PG8_BAR; PG8_WAIT_L(0); PG8_MMA(0, 1, At, B1); PG8_BAR;
;             PG8_LDA(At, 1, 1); PG8_STAGE(PG8_SA(1, 0), a3, voffA);
;             PG8_BAR; PG8_WAIT_L(0); PG8_MMA(1, 0, At, B0); PG8_BAR; PG8_SCHED;
;             PG8_STAGE(PG8_SB(1, 1), b3 + hstepB, voffB);
;             PG8_WAIT_V(6); PG8_BAR; PG8_MMA(1, 1, At, B1); PG8_BAR;
.LBB0_461:
	s_add_i32 s14, s88, 2
	s_add_u32 s8, s4, 0x80
	s_addc_u32 s9, s5, 0
	s_add_i32 s15, 0, 0x10000
	v_add_u32_e32 v114, s15, v211
	ds_read_b128 v[82:85], v114
	ds_read_b128 v[94:97], v114 offset:1024
	ds_read_b128 v[98:101], v114 offset:2048
	ds_read_b128 v[114:117], v114 offset:3072
	s_cmp_eq_u32 s42, s88
	s_cselect_b32 s88, s57, s8
	s_cselect_b32 s89, s71, s9
	s_cselect_b32 s91, s59, s35
	s_cselect_b32 s90, s72, s34
	v_lshl_add_u64 v[178:179], s[4:5], 0, v[202:203]
	s_add_i32 m0, s24, 0xc000
	ds_read_b128 v[122:125], v213
	ds_read_b128 v[130:133], v213 offset:1024
	ds_read_b128 v[146:149], v213 offset:2048
	ds_read_b128 v[150:153], v213 offset:3072
	ds_read_b128 v[162:165], v213 offset:4096
	ds_read_b128 v[166:169], v213 offset:5120
	ds_read_b128 v[170:173], v213 offset:6144
	ds_read_b128 v[174:177], v213 offset:7168
	global_load_lds_dwordx4 v[178:179], off
	v_lshl_add_u64 v[178:179], s[4:5], 0, v[204:205]
	s_add_i32 m0, s24, 0xe000
	s_nop 0
	global_load_lds_dwordx4 v[178:179], off
	s_add_i32 s8, 0, 0x14000
	v_add_u32_e32 v190, s8, v211
	ds_read_b128 v[178:181], v190
	ds_read_b128 v[182:185], v190 offset:1024
	ds_read_b128 v[186:189], v190 offset:2048
	ds_read_b128 v[190:193], v190 offset:3072
	s_waitcnt vmcnt(8)
	s_waitcnt lgkmcnt(0)
	v_mfma_f32_16x16x32_bf16 v[158:161], v[82:85], v[122:125], v[158:161]
	v_mfma_f32_16x16x32_bf16 v[154:157], v[98:101], v[122:125], v[154:157]
	v_mfma_f32_16x16x32_bf16 v[134:137], v[82:85], v[146:149], v[134:137]
	v_mfma_f32_16x16x32_bf16 v[126:129], v[98:101], v[146:149], v[126:129]
	v_mfma_f32_16x16x32_bf16 v[106:109], v[82:85], v[162:165], v[106:109]
	v_mfma_f32_16x16x32_bf16 v[102:105], v[98:101], v[162:165], v[102:105]
	v_mfma_f32_16x16x32_bf16 v[78:81], v[82:85], v[170:173], v[78:81]
	v_mfma_f32_16x16x32_bf16 v[74:77], v[98:101], v[170:173], v[74:77]
	s_barrier
	s_setprio 1
	v_mfma_f32_16x16x32_bf16 v[158:161], v[94:97], v[130:133], v[158:161]
	v_mfma_f32_16x16x32_bf16 v[154:157], v[114:117], v[130:133], v[154:157]
	v_mfma_f32_16x16x32_bf16 v[134:137], v[94:97], v[150:153], v[134:137]
	v_mfma_f32_16x16x32_bf16 v[126:129], v[114:117], v[150:153], v[126:129]
	v_mfma_f32_16x16x32_bf16 v[106:109], v[94:97], v[166:169], v[106:109]
	v_mfma_f32_16x16x32_bf16 v[102:105], v[114:117], v[166:169], v[102:105]
	v_mfma_f32_16x16x32_bf16 v[78:81], v[94:97], v[174:177], v[78:81]
	v_mfma_f32_16x16x32_bf16 v[74:77], v[114:117], v[174:177], v[74:77]
	v_mfma_f32_16x16x32_bf16 v[142:145], v[178:181], v[122:125], v[142:145]
	v_mfma_f32_16x16x32_bf16 v[118:121], v[178:181], v[146:149], v[118:121]
	v_mfma_f32_16x16x32_bf16 v[110:113], v[186:189], v[146:149], v[110:113]
	v_mfma_f32_16x16x32_bf16 v[90:93], v[178:181], v[162:165], v[90:93]
	v_mfma_f32_16x16x32_bf16 v[86:89], v[186:189], v[162:165], v[86:89]
	v_mfma_f32_16x16x32_bf16 v[70:73], v[178:181], v[170:173], v[70:73]
	v_mfma_f32_16x16x32_bf16 v[66:69], v[186:189], v[170:173], v[66:69]
	v_mfma_f32_16x16x32_bf16 v[142:145], v[182:185], v[130:133], v[142:145]
	v_mfma_f32_16x16x32_bf16 v[122:125], v[186:189], v[122:125], v[138:141]
	v_mfma_f32_16x16x32_bf16 v[118:121], v[182:185], v[150:153], v[118:121]
	v_mfma_f32_16x16x32_bf16 v[110:113], v[190:193], v[150:153], v[110:113]
	v_mfma_f32_16x16x32_bf16 v[90:93], v[182:185], v[166:169], v[90:93]
	v_mfma_f32_16x16x32_bf16 v[86:89], v[190:193], v[166:169], v[86:89]
	v_mfma_f32_16x16x32_bf16 v[70:73], v[182:185], v[174:177], v[70:73]
	v_mfma_f32_16x16x32_bf16 v[66:69], v[190:193], v[174:177], v[66:69]
	v_mfma_f32_16x16x32_bf16 v[122:125], v[190:193], v[130:133], v[122:125]
	s_setprio 0
	s_barrier
	s_add_i32 s9, s15, s3
	v_lshl_add_u64 v[194:195], s[90:91], 0, v[0:1]
	s_mov_b32 m0, s9
	s_nop 0
	global_load_lds_dwordx4 v[194:195], off
	v_lshl_add_u64 v[206:207], s[90:91], 0, v[200:201]
	s_add_i32 m0, s9, 0x2000
	s_nop 0
	global_load_lds_dwordx4 v[206:207], off
	s_mov_b32 m0, s24
	v_lshl_add_u64 v[208:209], s[88:89], 0, v[196:197]
	ds_read_b128 v[130:133], v213 offset:16384
	ds_read_b128 v[138:141], v213 offset:17408
	ds_read_b128 v[146:149], v213 offset:18432
	ds_read_b128 v[150:153], v213 offset:19456
	ds_read_b128 v[162:165], v213 offset:20480
	ds_read_b128 v[166:169], v213 offset:21504
	ds_read_b128 v[170:173], v213 offset:22528
	ds_read_b128 v[174:177], v213 offset:23552
	global_load_lds_dwordx4 v[208:209], off
	v_lshl_add_u64 v[214:215], s[88:89], 0, v[198:199]
	s_mov_b32 m0, s33
	s_nop 0
	global_load_lds_dwordx4 v[214:215], off
	s_add_u32 s90, s90, s78
	s_addc_u32 s91, s91, s79
	s_add_i32 s8, s8, s3
	v_lshl_add_u64 v[216:217], s[90:91], 0, v[0:1]
	s_mov_b32 m0, s8
	v_lshl_add_u64 v[222:223], s[90:91], 0, v[200:201]
	global_load_lds_dwordx4 v[216:217], off
	s_add_i32 m0, s8, 0x2000
	s_nop 0
	global_load_lds_dwordx4 v[222:223], off
	s_waitcnt vmcnt(8)
	s_waitcnt lgkmcnt(0)
	v_mfma_f32_16x16x32_bf16 v[62:65], v[82:85], v[130:133], v[62:65]
	v_mfma_f32_16x16x32_bf16 v[58:61], v[98:101], v[130:133], v[58:61]
	v_mfma_f32_16x16x32_bf16 v[46:49], v[82:85], v[146:149], v[46:49]
	v_mfma_f32_16x16x32_bf16 v[42:45], v[98:101], v[146:149], v[42:45]
	v_mfma_f32_16x16x32_bf16 v[30:33], v[82:85], v[162:165], v[30:33]
	v_mfma_f32_16x16x32_bf16 v[26:29], v[98:101], v[162:165], v[26:29]
	v_mfma_f32_16x16x32_bf16 v[14:17], v[82:85], v[170:173], v[14:17]
	v_mfma_f32_16x16x32_bf16 v[10:13], v[98:101], v[170:173], v[10:13]
	s_barrier
; #define PG8_STAGE(bufoff, gbase, voff) do { _Pragma("unroll") for (int _i = 0; _i < 2; ++_i) \
;         __builtin_amdgcn_global_load_lds((const unsigned*)((const char*)(gbase) + (voff)[_i]), (LAS unsigned*)(lds + (bufoff) + ldsw + _i * 8192), 16, 0, 0); } while (0)
; #define PG8_LDA(dst, b, h) do { _Pragma("unroll") for (int m = 0; m < 4; ++m) _Pragma("unroll") for (int k = 0; k < 2; ++k) dst[m][k] = *(const LAS bf16x8*)(lds + PG8_SA(b, h) + aoff + m * 2048 + k * 1024); } while (0)
; #define PG8_LDB(dst, b, h) do { _Pragma("unroll") for (int n = 0; n < 2; ++n) _Pragma("unroll") for (int k = 0; k < 2; ++k) dst[n][k] = *(const LAS bf16x8*)(lds + PG8_SB(b, h) + boff + n * 2048 + k * 1024); } while (0)
; #define PG8_WAIT_V(n) asm volatile("s_waitcnt vmcnt(" #n ")" ::: "memory")
; #define PG8_WAIT_L(n) asm volatile("s_waitcnt lgkmcnt(" #n ")" ::: "memory")
; #define PG8_BAR __builtin_amdgcn_s_barrier()
; #define PG8_SCHED __builtin_amdgcn_sched_barrier(0)
; template <class Epi>
; __device__ __forceinline__ void gemm_phase(LAS unsigned char* lds, const Gemm g, const Sched& S, const Epi& E) {
;     ...
;             PG8_LDB(B0, 0, 0); PG8_SCHED; PG8_LDA(At, 0, 0); PG8_STAGE(PG8_SA(1, 1), a1 + hstepA, voffA);
;             PG8_WAIT_L(8); PG8_BAR; PG8_WAIT_L(0); PG8_MMA(0, 0, At, B0); PG8_BAR; PG8_SCHED;
;             PG8_LDB(B1, 0, 1); PG8_STAGE(PG8_SB(0, 0), b2, voffB);
;             PG8_BAR; PG8_WAIT_L(0); PG8_MMA(0, 1, At, B1); PG8_BAR;
;             PG8_LDA(At, 0, 1); PG8_STAGE(PG8_SA(0, 0), a2, voffA);
;             PG8_BAR; PG8_WAIT_L(0); PG8_MMA(1, 0, At, B0); PG8_BAR; PG8_SCHED;
;             PG8_STAGE(PG8_SB(0, 1), b2 + hstepB, voffB);
;             PG8_WAIT_V(6); PG8_BAR; PG8_MMA(1, 1, At, B1); PG8_BAR;
;             PG8_LDB(B0, 1, 0); PG8_SCHED; PG8_LDA(At, 1, 0); PG8_STAGE(PG8_SA(0, 1), a2 + hstepA, voffA);
;             PG8_WAIT_L(8); PG8_BAR; PG8_WAIT_L(0); PG8_MMA(0, 0, At, B0); PG8_BAR; PG8_SCHED;
;             PG8_LDB(B1, 1, 1); PG8_STAGE(PG8_SB(1, 0), b3, voffB);
;             PG8_BAR; PG8_WAIT_L(0); PG8_MMA(0, 1, At, B1); PG8_BAR;
;             PG8_LDA(At, 1, 1); PG8_STAGE(PG8_SA(1, 0), a3, voffA);
;             PG8_BAR; PG8_WAIT_L(0); PG8_MMA(1, 0, At, B0); PG8_BAR; PG8_SCHED;
;             PG8_STAGE(PG8_SB(1, 1), b3 + hstepB, voffB);
;             PG8_WAIT_V(6); PG8_BAR; PG8_MMA(1, 1, At, B1); PG8_BAR;
	s_setprio 1
	v_mfma_f32_16x16x32_bf16 v[62:65], v[94:97], v[138:141], v[62:65]
	v_mfma_f32_16x16x32_bf16 v[58:61], v[114:117], v[138:141], v[58:61]
	v_mfma_f32_16x16x32_bf16 v[46:49], v[94:97], v[150:153], v[46:49]
	v_mfma_f32_16x16x32_bf16 v[42:45], v[114:117], v[150:153], v[42:45]
	v_mfma_f32_16x16x32_bf16 v[30:33], v[94:97], v[166:169], v[30:33]
	v_mfma_f32_16x16x32_bf16 v[26:29], v[114:117], v[166:169], v[26:29]
	v_mfma_f32_16x16x32_bf16 v[14:17], v[94:97], v[174:177], v[14:17]
	v_mfma_f32_16x16x32_bf16 v[10:13], v[114:117], v[174:177], v[10:13]
	v_mfma_f32_16x16x32_bf16 v[54:57], v[178:181], v[130:133], v[54:57]
	v_mfma_f32_16x16x32_bf16 v[50:53], v[186:189], v[130:133], v[50:53]
	v_mfma_f32_16x16x32_bf16 v[38:41], v[178:181], v[146:149], v[38:41]
	v_mfma_f32_16x16x32_bf16 v[34:37], v[186:189], v[146:149], v[34:37]
	v_mfma_f32_16x16x32_bf16 v[22:25], v[178:181], v[162:165], v[22:25]
	v_mfma_f32_16x16x32_bf16 v[18:21], v[186:189], v[162:165], v[18:21]
	v_mfma_f32_16x16x32_bf16 v[6:9], v[178:181], v[170:173], v[6:9]
	v_mfma_f32_16x16x32_bf16 v[2:5], v[186:189], v[170:173], v[2:5]
	v_mfma_f32_16x16x32_bf16 v[54:57], v[182:185], v[138:141], v[54:57]
	v_mfma_f32_16x16x32_bf16 v[50:53], v[190:193], v[138:141], v[50:53]
	v_mfma_f32_16x16x32_bf16 v[38:41], v[182:185], v[150:153], v[38:41]
	v_mfma_f32_16x16x32_bf16 v[34:37], v[190:193], v[150:153], v[34:37]
	v_mfma_f32_16x16x32_bf16 v[22:25], v[182:185], v[166:169], v[22:25]
	v_mfma_f32_16x16x32_bf16 v[18:21], v[190:193], v[166:169], v[18:21]
	v_mfma_f32_16x16x32_bf16 v[6:9], v[182:185], v[174:177], v[6:9]
	v_mfma_f32_16x16x32_bf16 v[2:5], v[190:193], v[174:177], v[2:5]
	s_setprio 0
	s_barrier
	s_add_i32 s8, 0, 0x18000
	v_add_u32_e32 v114, s8, v211
	ds_read_b128 v[82:85], v114
	ds_read_b128 v[94:97], v114 offset:1024
	ds_read_b128 v[98:101], v114 offset:2048
	ds_read_b128 v[114:117], v114 offset:3072
	s_add_u32 s88, s88, s36
	s_addc_u32 s89, s89, s37
	s_mov_b32 m0, s38
	v_lshl_add_u64 v[178:179], s[88:89], 0, v[196:197]
	ds_read_b128 v[130:133], v213 offset:32768
	ds_read_b128 v[138:141], v213 offset:33792
	ds_read_b128 v[146:149], v213 offset:34816
	ds_read_b128 v[150:153], v213 offset:35840
	ds_read_b128 v[162:165], v213 offset:36864
	ds_read_b128 v[166:169], v213 offset:37888
	ds_read_b128 v[170:173], v213 offset:38912
	ds_read_b128 v[174:177], v213 offset:39936
	global_load_lds_dwordx4 v[178:179], off
	v_lshl_add_u64 v[178:179], s[88:89], 0, v[198:199]
	s_mov_b32 m0, s39
	s_nop 0
	global_load_lds_dwordx4 v[178:179], off
	s_add_i32 s9, 0, 0x1c000
	v_add_u32_e32 v190, s9, v211
	ds_read_b128 v[178:181], v190
	ds_read_b128 v[182:185], v190 offset:1024
	ds_read_b128 v[186:189], v190 offset:2048
	ds_read_b128 v[190:193], v190 offset:3072
	s_waitcnt vmcnt(8)
	s_waitcnt lgkmcnt(0)
	v_mfma_f32_16x16x32_bf16 v[158:161], v[82:85], v[130:133], v[158:161]
	v_mfma_f32_16x16x32_bf16 v[154:157], v[98:101], v[130:133], v[154:157]
	v_mfma_f32_16x16x32_bf16 v[134:137], v[82:85], v[146:149], v[134:137]
	v_mfma_f32_16x16x32_bf16 v[126:129], v[98:101], v[146:149], v[126:129]
	v_mfma_f32_16x16x32_bf16 v[106:109], v[82:85], v[162:165], v[106:109]
	v_mfma_f32_16x16x32_bf16 v[102:105], v[98:101], v[162:165], v[102:105]
	v_mfma_f32_16x16x32_bf16 v[78:81], v[82:85], v[170:173], v[78:81]
	v_mfma_f32_16x16x32_bf16 v[74:77], v[98:101], v[170:173], v[74:77]
	s_barrier
	s_setprio 1
	v_mfma_f32_16x16x32_bf16 v[158:161], v[94:97], v[138:141], v[158:161]
	v_mfma_f32_16x16x32_bf16 v[154:157], v[114:117], v[138:141], v[154:157]
	v_mfma_f32_16x16x32_bf16 v[134:137], v[94:97], v[150:153], v[134:137]
	v_mfma_f32_16x16x32_bf16 v[126:129], v[114:117], v[150:153], v[126:129]
	v_mfma_f32_16x16x32_bf16 v[106:109], v[94:97], v[166:169], v[106:109]
	v_mfma_f32_16x16x32_bf16 v[102:105], v[114:117], v[166:169], v[102:105]
	v_mfma_f32_16x16x32_bf16 v[78:81], v[94:97], v[174:177], v[78:81]
	v_mfma_f32_16x16x32_bf16 v[74:77], v[114:117], v[174:177], v[74:77]
	v_mfma_f32_16x16x32_bf16 v[142:145], v[178:181], v[130:133], v[142:145]
	v_mfma_f32_16x16x32_bf16 v[122:125], v[186:189], v[130:133], v[122:125]
	v_mfma_f32_16x16x32_bf16 v[118:121], v[178:181], v[146:149], v[118:121]
	v_mfma_f32_16x16x32_bf16 v[110:113], v[186:189], v[146:149], v[110:113]
	v_mfma_f32_16x16x32_bf16 v[90:93], v[178:181], v[162:165], v[90:93]
	v_mfma_f32_16x16x32_bf16 v[86:89], v[186:189], v[162:165], v[86:89]
	v_mfma_f32_16x16x32_bf16 v[70:73], v[178:181], v[170:173], v[70:73]
	v_mfma_f32_16x16x32_bf16 v[66:69], v[186:189], v[170:173], v[66:69]
	v_mfma_f32_16x16x32_bf16 v[142:145], v[182:185], v[138:141], v[142:145]
	v_mfma_f32_16x16x32_bf16 v[138:141], v[190:193], v[138:141], v[122:125]
	v_mfma_f32_16x16x32_bf16 v[118:121], v[182:185], v[150:153], v[118:121]
	v_mfma_f32_16x16x32_bf16 v[110:113], v[190:193], v[150:153], v[110:113]
	v_mfma_f32_16x16x32_bf16 v[90:93], v[182:185], v[166:169], v[90:93]
	v_mfma_f32_16x16x32_bf16 v[86:89], v[190:193], v[166:169], v[86:89]
	v_mfma_f32_16x16x32_bf16 v[70:73], v[182:185], v[174:177], v[70:73]
	v_mfma_f32_16x16x32_bf16 v[66:69], v[190:193], v[174:177], v[66:69]
	s_setprio 0
	s_barrier
; #define PG8_MMA(ai, bj, At, Bt) do { __builtin_amdgcn_s_setprio(1); _Pragma("unroll") for (int m = 0; m < 4; ++m) _Pragma("unroll") for (int n = 0; n < 2; ++n) _Pragma("unroll") for (int k = 0; k < 2; ++k) \
;         acc[ai][bj][m][n] = __builtin_amdgcn_mfma_f32_16x16x32_bf16(Bt[n][k], At[m][k], acc[ai][bj][m][n], 0, 0, 0); __builtin_amdgcn_s_setprio(0); } while (0)
; #define PG8_WAIT_V(n) asm volatile("s_waitcnt vmcnt(" #n ")" ::: "memory")
; #define PG8_BAR __builtin_amdgcn_s_barrier()
; template <class Epi>
; __device__ __forceinline__ void gemm_phase(LAS unsigned char* lds, const Gemm g, const Sched& S, const Epi& E) {
;     ...
;             PG8_WAIT_V(6); PG8_BAR; PG8_MMA(1, 1, At, B1); PG8_BAR;
;         }
;     __device__ __forceinline__ void operator()(const Acc& acc, const Unit& u, int wr, int wc, int fr, int fq, const Pre& pre) const {
;         const int row0 = u.pm * 256 + wr * 64 + fr, col0 = u.pn * 256 + wc * 32 + 8 * fq;
; #pragma unroll
;         for (int ai = 0; ai < 2; ++ai) {
;             u32x4 gw[4][2], pw[4][2];
; #pragma unroll
;             for (int m = 0; m < 4; ++m)
; #pragma unroll
;                 for (int bj = 0; bj < 2; ++bj) { const size_t off = (size_t)(row0 + ai * 128 + m * 16) * ldc + col0 + bj * 128;
;                     gw[m][bj] = *(const u32x4*)(gate + off); if (add) pw[m][bj] = *(const u32x4*)(O + off); }
	s_add_i32 s8, s8, s3
	v_lshl_add_u64 v[194:195], v[194:195], 0, s[60:61]
	s_mov_b32 m0, s8
	s_nop 0
	global_load_lds_dwordx4 v[194:195], off
	v_lshl_add_u64 v[194:195], v[206:207], 0, s[60:61]
	s_add_i32 m0, s8, 0x2000
	s_nop 0
	global_load_lds_dwordx4 v[194:195], off
	s_mov_b32 m0, s40
	v_lshl_add_u64 v[194:195], v[208:209], 0, s[60:61]
	ds_read_b128 v[122:125], v213 offset:49152
	ds_read_b128 v[130:133], v213 offset:50176
	ds_read_b128 v[146:149], v213 offset:51200
	ds_read_b128 v[150:153], v213 offset:52224
	ds_read_b128 v[162:165], v213 offset:53248
	ds_read_b128 v[166:169], v213 offset:54272
	ds_read_b128 v[170:173], v213 offset:55296
	ds_read_b128 v[174:177], v213 offset:56320
	global_load_lds_dwordx4 v[194:195], off
	v_lshl_add_u64 v[194:195], v[214:215], 0, s[60:61]
	s_mov_b32 m0, s41
	s_nop 0
	global_load_lds_dwordx4 v[194:195], off
	s_add_i32 s8, s9, s3
	v_lshl_add_u64 v[194:195], v[216:217], 0, s[60:61]
	s_mov_b32 m0, s8
	s_nop 0
	global_load_lds_dwordx4 v[194:195], off
	v_lshl_add_u64 v[194:195], v[222:223], 0, s[60:61]
	s_add_i32 m0, s8, 0x2000
	s_nop 0
	global_load_lds_dwordx4 v[194:195], off
	s_waitcnt vmcnt(8)
	s_waitcnt lgkmcnt(0)
	v_mfma_f32_16x16x32_bf16 v[62:65], v[82:85], v[122:125], v[62:65]
	v_mfma_f32_16x16x32_bf16 v[58:61], v[98:101], v[122:125], v[58:61]
	v_mfma_f32_16x16x32_bf16 v[46:49], v[82:85], v[146:149], v[46:49]
	v_mfma_f32_16x16x32_bf16 v[42:45], v[98:101], v[146:149], v[42:45]
	v_mfma_f32_16x16x32_bf16 v[30:33], v[82:85], v[162:165], v[30:33]
	v_mfma_f32_16x16x32_bf16 v[26:29], v[98:101], v[162:165], v[26:29]
	v_mfma_f32_16x16x32_bf16 v[14:17], v[82:85], v[170:173], v[14:17]
	v_mfma_f32_16x16x32_bf16 v[10:13], v[98:101], v[170:173], v[10:13]
	s_barrier
	s_setprio 1
	v_mfma_f32_16x16x32_bf16 v[62:65], v[94:97], v[130:133], v[62:65]
	v_mfma_f32_16x16x32_bf16 v[58:61], v[114:117], v[130:133], v[58:61]
	v_mfma_f32_16x16x32_bf16 v[46:49], v[94:97], v[150:153], v[46:49]
	v_mfma_f32_16x16x32_bf16 v[42:45], v[114:117], v[150:153], v[42:45]
	v_mfma_f32_16x16x32_bf16 v[30:33], v[94:97], v[166:169], v[30:33]
	v_mfma_f32_16x16x32_bf16 v[26:29], v[114:117], v[166:169], v[26:29]
	v_mfma_f32_16x16x32_bf16 v[14:17], v[94:97], v[174:177], v[14:17]
	v_mfma_f32_16x16x32_bf16 v[10:13], v[114:117], v[174:177], v[10:13]
	v_mfma_f32_16x16x32_bf16 v[54:57], v[178:181], v[122:125], v[54:57]
	v_mfma_f32_16x16x32_bf16 v[50:53], v[186:189], v[122:125], v[50:53]
	v_mfma_f32_16x16x32_bf16 v[38:41], v[178:181], v[146:149], v[38:41]
	v_mfma_f32_16x16x32_bf16 v[34:37], v[186:189], v[146:149], v[34:37]
	v_mfma_f32_16x16x32_bf16 v[22:25], v[178:181], v[162:165], v[22:25]
	v_mfma_f32_16x16x32_bf16 v[18:21], v[186:189], v[162:165], v[18:21]
	v_mfma_f32_16x16x32_bf16 v[6:9], v[178:181], v[170:173], v[6:9]
	v_mfma_f32_16x16x32_bf16 v[2:5], v[186:189], v[170:173], v[2:5]
	v_mfma_f32_16x16x32_bf16 v[54:57], v[182:185], v[130:133], v[54:57]
	v_mfma_f32_16x16x32_bf16 v[50:53], v[190:193], v[130:133], v[50:53]
	v_mfma_f32_16x16x32_bf16 v[38:41], v[182:185], v[150:153], v[38:41]
	v_mfma_f32_16x16x32_bf16 v[34:37], v[190:193], v[150:153], v[34:37]
	v_mfma_f32_16x16x32_bf16 v[22:25], v[182:185], v[166:169], v[22:25]
	v_mfma_f32_16x16x32_bf16 v[18:21], v[190:193], v[166:169], v[18:21]
	v_mfma_f32_16x16x32_bf16 v[6:9], v[182:185], v[174:177], v[6:9]
	v_mfma_f32_16x16x32_bf16 v[2:5], v[190:193], v[174:177], v[2:5]
	s_setprio 0
	s_add_u32 s4, s4, 0x100
	s_addc_u32 s5, s5, 0
	s_add_u32 s34, s34, 0x100
	s_addc_u32 s35, s35, 0
	s_cmp_ge_u32 s14, s73
	s_mov_b32 s88, s14
	s_barrier
	s_cbranch_scc0 .LBB0_461
	v_lshl_add_u32 v214, s67, 8, v210
	v_lshl_or_b32 v206, s55, 8, v212
	v_ashrrev_i32_e32 v207, 31, v206
	v_ashrrev_i32_e32 v82, 31, v214
	v_mul_lo_u32 v215, s12, v82
	v_mul_lo_u32 v238, s13, v214
	v_mad_u64_u32 v[82:83], s[4:5], s12, v214, v[206:207]
	v_add3_u32 v83, v238, v83, v215
	v_lshl_add_u64 v[84:85], v[82:83], 1, s[6:7]
	global_load_dwordx4 v[190:193], v[84:85], off
	v_cndmask_b32_e64 v94, 0, 1, s[76:77]
	v_cmp_ne_u32_e64 s[4:5], 1, v94
	s_andn2_b64 vcc, exec, s[76:77]
	v_lshl_add_u64 v[82:83], v[82:83], 1, s[62:63]
	s_cbranch_vccnz .LBB0_464
	global_load_dwordx4 v[150:153], v[82:83], off

; #define PG8_STAGE(bufoff, gbase, voff) do { _Pragma("unroll") for (int _i = 0; _i < 2; ++_i) \
;         __builtin_amdgcn_global_load_lds((const unsigned*)((const char*)(gbase) + (voff)[_i]), (LAS unsigned*)(lds + (bufoff) + ldsw + _i * 8192), 16, 0, 0); } while (0)
; #define PG8_LDA(dst, b, h) do { _Pragma("unroll") for (int m = 0; m < 4; ++m) _Pragma("unroll") for (int k = 0; k < 2; ++k) dst[m][k] = *(const LAS bf16x8*)(lds + PG8_SA(b, h) + aoff + m * 2048 + k * 1024); } while (0)
; #define PG8_WAIT_V(n) asm volatile("s_waitcnt vmcnt(" #n ")" ::: "memory")
; #define PG8_WAIT_L(n) asm volatile("s_waitcnt lgkmcnt(" #n ")" ::: "memory")
; template <class Epi>
; __device__ __forceinline__ void gemm_phase(LAS unsigned char* lds, const Gemm g, const Sched& S, const Epi& E) {
;     ...
;         for (int t = 0; t < nt; t += 2) {
;             const bool last = (t == nt - 2);
;             const char* a1 = cA + (size_t)(t + 1) * kstep;
;             const char* a2 = last ? nA : cA + (size_t)(t + 2) * kstep; const char* b2 = last ? nB : cB + (size_t)(t + 2) * kstep;
;             const char* a3 = a2 + kstep; const char* b3 = b2 + kstep;
;             PG8_LDB(B0, 0, 0); PG8_SCHED; PG8_LDA(At, 0, 0); PG8_STAGE(PG8_SA(1, 1), a1 + hstepA, voffA);
;             PG8_WAIT_L(8); PG8_BAR; PG8_WAIT_L(0); PG8_MMA(0, 0, At, B0); PG8_BAR; PG8_SCHED;
;             PG8_LDB(B1, 0, 1); PG8_STAGE(PG8_SB(0, 0), b2, voffB);
;             PG8_BAR; PG8_WAIT_L(0); PG8_MMA(0, 1, At, B1); PG8_BAR;
;             PG8_LDA(At, 0, 1); PG8_STAGE(PG8_SA(0, 0), a2, voffA);
;             PG8_BAR; PG8_WAIT_L(0); PG8_MMA(1, 0, At, B0); PG8_BAR; PG8_SCHED;
;             PG8_STAGE(PG8_SB(0, 1), b2 + hstepB, voffB);
;             PG8_WAIT_V(6); PG8_BAR; PG8_MMA(1, 1, At, B1); PG8_BAR;
;             PG8_LDB(B0, 1, 0); PG8_SCHED; PG8_LDA(At, 1, 0); PG8_STAGE(PG8_SA(0, 1), a2 + hstepA, voffA);
;             PG8_WAIT_L(8); PG8_BAR; PG8_WAIT_L(0); PG8_MMA(0, 0, At, B0); PG8_BAR; PG8_SCHED;
;             PG8_LDB(B1, 1, 1); PG8_STAGE(PG8_SB(1, 0), b3, voffB);
;             PG8_BAR; PG8_WAIT_L(0); PG8_MMA(0, 1, At, B1); PG8_BAR;
;             PG8_LDA(At, 1, 1); PG8_STAGE(PG8_SA(1, 0), a3, voffA);
;             PG8_BAR; PG8_WAIT_L(0); PG8_MMA(1, 0, At, B0); PG8_BAR; PG8_SCHED;
;             PG8_STAGE(PG8_SB(1, 1), b3 + hstepB, voffB);
;             PG8_WAIT_V(6); PG8_BAR; PG8_MMA(1, 1, At, B1); PG8_BAR;
.LBB0_555:
	s_add_i32 s14, s6, 2
	s_add_u32 s8, s4, 0x80
	s_addc_u32 s7, s5, 0
	s_add_i32 s9, 0, 0x10000
	v_add_u32_e32 v160, s9, v156
	ds_read_b128 v[142:145], v160
	ds_read_b128 v[146:149], v160 offset:1024
	ds_read_b128 v[150:153], v160 offset:2048
	ds_read_b128 v[160:163], v160 offset:3072
	s_cmp_eq_u32 s43, s6
	s_cselect_b32 s6, s57, s8
	s_cselect_b32 s7, s55, s7
	s_cselect_b32 s91, s59, s35
	s_cselect_b32 s90, s95, s34
	v_lshl_add_u64 v[192:193], s[4:5], 0, v[136:137]
	s_add_i32 m0, s33, 0xc000
	ds_read_b128 v[164:167], v159
	ds_read_b128 v[168:171], v159 offset:1024
	ds_read_b128 v[172:175], v159 offset:2048
	ds_read_b128 v[176:179], v159 offset:3072
	ds_read_b128 v[180:183], v159 offset:4096
	ds_read_b128 v[184:187], v159 offset:5120
	ds_read_b128 v[188:191], v159 offset:6144
	ds_read_b128 v[196:199], v159 offset:7168
	global_load_lds_dwordx4 v[192:193], off
	v_lshl_add_u64 v[192:193], s[4:5], 0, v[138:139]
	s_add_i32 m0, s33, 0xe000
	s_nop 0
	global_load_lds_dwordx4 v[192:193], off
	s_add_i32 s8, 0, 0x14000
	v_add_u32_e32 v192, s8, v156
	ds_read_b128 v[200:203], v192
	ds_read_b128 v[204:207], v192 offset:1024
	ds_read_b128 v[208:211], v192 offset:2048
	ds_read_b128 v[212:215], v192 offset:3072
	s_waitcnt vmcnt(8)
	s_waitcnt lgkmcnt(0)
	v_mfma_f32_16x16x32_bf16 v[126:129], v[142:145], v[164:167], v[126:129]
	v_mfma_f32_16x16x32_bf16 v[122:125], v[150:153], v[164:167], v[122:125]
	v_mfma_f32_16x16x32_bf16 v[110:113], v[142:145], v[172:175], v[110:113]
	v_mfma_f32_16x16x32_bf16 v[106:109], v[150:153], v[172:175], v[106:109]
	v_mfma_f32_16x16x32_bf16 v[94:97], v[142:145], v[180:183], v[94:97]
	v_mfma_f32_16x16x32_bf16 v[90:93], v[150:153], v[180:183], v[90:93]
	v_mfma_f32_16x16x32_bf16 v[78:81], v[142:145], v[188:191], v[78:81]
	v_mfma_f32_16x16x32_bf16 v[74:77], v[150:153], v[188:191], v[74:77]
	s_barrier
	s_setprio 1
	v_mfma_f32_16x16x32_bf16 v[126:129], v[146:149], v[168:171], v[126:129]
	v_mfma_f32_16x16x32_bf16 v[122:125], v[160:163], v[168:171], v[122:125]
	v_mfma_f32_16x16x32_bf16 v[110:113], v[146:149], v[176:179], v[110:113]
	v_mfma_f32_16x16x32_bf16 v[106:109], v[160:163], v[176:179], v[106:109]
	v_mfma_f32_16x16x32_bf16 v[94:97], v[146:149], v[184:187], v[94:97]
	v_mfma_f32_16x16x32_bf16 v[90:93], v[160:163], v[184:187], v[90:93]
	v_mfma_f32_16x16x32_bf16 v[78:81], v[146:149], v[196:199], v[78:81]
	v_mfma_f32_16x16x32_bf16 v[74:77], v[160:163], v[196:199], v[74:77]
	v_mfma_f32_16x16x32_bf16 v[118:121], v[200:203], v[164:167], v[118:121]
	v_mfma_f32_16x16x32_bf16 v[114:117], v[208:211], v[164:167], v[114:117]
	v_mfma_f32_16x16x32_bf16 v[102:105], v[200:203], v[172:175], v[102:105]
	v_mfma_f32_16x16x32_bf16 v[98:101], v[208:211], v[172:175], v[98:101]
	v_mfma_f32_16x16x32_bf16 v[86:89], v[200:203], v[180:183], v[86:89]
	v_mfma_f32_16x16x32_bf16 v[82:85], v[208:211], v[180:183], v[82:85]
	v_mfma_f32_16x16x32_bf16 v[70:73], v[200:203], v[188:191], v[70:73]
	v_mfma_f32_16x16x32_bf16 v[66:69], v[208:211], v[188:191], v[66:69]
	v_mfma_f32_16x16x32_bf16 v[118:121], v[204:207], v[168:171], v[118:121]
	v_mfma_f32_16x16x32_bf16 v[114:117], v[212:215], v[168:171], v[114:117]
	v_mfma_f32_16x16x32_bf16 v[102:105], v[204:207], v[176:179], v[102:105]
	v_mfma_f32_16x16x32_bf16 v[98:101], v[212:215], v[176:179], v[98:101]
	v_mfma_f32_16x16x32_bf16 v[86:89], v[204:207], v[184:187], v[86:89]
	v_mfma_f32_16x16x32_bf16 v[82:85], v[212:215], v[184:187], v[82:85]
	v_mfma_f32_16x16x32_bf16 v[70:73], v[204:207], v[196:199], v[70:73]
	v_mfma_f32_16x16x32_bf16 v[66:69], v[212:215], v[196:199], v[66:69]
	s_setprio 0
	s_barrier
	s_add_i32 s9, s9, s3
	v_lshl_add_u64 v[192:193], s[90:91], 0, v[0:1]
	s_mov_b32 m0, s9
	v_lshl_add_u64 v[194:195], s[90:91], 0, v[134:135]
	global_load_lds_dwordx4 v[192:193], off
	s_add_i32 m0, s9, 0x2000
	s_nop 0
	global_load_lds_dwordx4 v[194:195], off
	s_mov_b32 m0, s33
	v_lshl_add_u64 v[216:217], s[6:7], 0, v[130:131]
	ds_read_b128 v[164:167], v159 offset:16384
	ds_read_b128 v[168:171], v159 offset:17408
	ds_read_b128 v[172:175], v159 offset:18432
	ds_read_b128 v[176:179], v159 offset:19456
	ds_read_b128 v[180:183], v159 offset:20480
	ds_read_b128 v[184:187], v159 offset:21504
	ds_read_b128 v[188:191], v159 offset:22528
	ds_read_b128 v[196:199], v159 offset:23552
	global_load_lds_dwordx4 v[216:217], off
	v_lshl_add_u64 v[222:223], s[6:7], 0, v[132:133]
	s_mov_b32 m0, s38
	s_nop 0
	global_load_lds_dwordx4 v[222:223], off
	s_add_u32 s90, s90, s76
	s_addc_u32 s91, s91, s77
	s_add_i32 s8, s8, s3
	v_lshl_add_u64 v[224:225], s[90:91], 0, v[0:1]
	s_mov_b32 m0, s8
	v_lshl_add_u64 v[226:227], s[90:91], 0, v[134:135]
	global_load_lds_dwordx4 v[224:225], off
	s_add_i32 m0, s8, 0x2000
	s_nop 0
	global_load_lds_dwordx4 v[226:227], off
	s_waitcnt vmcnt(8)
	s_waitcnt lgkmcnt(0)
	v_mfma_f32_16x16x32_bf16 v[62:65], v[142:145], v[164:167], v[62:65]
	v_mfma_f32_16x16x32_bf16 v[58:61], v[150:153], v[164:167], v[58:61]
	v_mfma_f32_16x16x32_bf16 v[46:49], v[142:145], v[172:175], v[46:49]
	v_mfma_f32_16x16x32_bf16 v[42:45], v[150:153], v[172:175], v[42:45]
	v_mfma_f32_16x16x32_bf16 v[30:33], v[142:145], v[180:183], v[30:33]
	v_mfma_f32_16x16x32_bf16 v[26:29], v[150:153], v[180:183], v[26:29]
	v_mfma_f32_16x16x32_bf16 v[14:17], v[142:145], v[188:191], v[14:17]
	v_mfma_f32_16x16x32_bf16 v[10:13], v[150:153], v[188:191], v[10:13]
	s_barrier
; #define PG8_STAGE(bufoff, gbase, voff) do { _Pragma("unroll") for (int _i = 0; _i < 2; ++_i) \
;         __builtin_amdgcn_global_load_lds((const unsigned*)((const char*)(gbase) + (voff)[_i]), (LAS unsigned*)(lds + (bufoff) + ldsw + _i * 8192), 16, 0, 0); } while (0)
; #define PG8_LDA(dst, b, h) do { _Pragma("unroll") for (int m = 0; m < 4; ++m) _Pragma("unroll") for (int k = 0; k < 2; ++k) dst[m][k] = *(const LAS bf16x8*)(lds + PG8_SA(b, h) + aoff + m * 2048 + k * 1024); } while (0)
; #define PG8_LDB(dst, b, h) do { _Pragma("unroll") for (int n = 0; n < 2; ++n) _Pragma("unroll") for (int k = 0; k < 2; ++k) dst[n][k] = *(const LAS bf16x8*)(lds + PG8_SB(b, h) + boff + n * 2048 + k * 1024); } while (0)
; #define PG8_WAIT_V(n) asm volatile("s_waitcnt vmcnt(" #n ")" ::: "memory")
; #define PG8_WAIT_L(n) asm volatile("s_waitcnt lgkmcnt(" #n ")" ::: "memory")
; #define PG8_BAR __builtin_amdgcn_s_barrier()
; #define PG8_SCHED __builtin_amdgcn_sched_barrier(0)
; template <class Epi>
; __device__ __forceinline__ void gemm_phase(LAS unsigned char* lds, const Gemm g, const Sched& S, const Epi& E) {
;     ...
;             PG8_LDB(B0, 0, 0); PG8_SCHED; PG8_LDA(At, 0, 0); PG8_STAGE(PG8_SA(1, 1), a1 + hstepA, voffA);
;             PG8_WAIT_L(8); PG8_BAR; PG8_WAIT_L(0); PG8_MMA(0, 0, At, B0); PG8_BAR; PG8_SCHED;
;             PG8_LDB(B1, 0, 1); PG8_STAGE(PG8_SB(0, 0), b2, voffB);
;             PG8_BAR; PG8_WAIT_L(0); PG8_MMA(0, 1, At, B1); PG8_BAR;
;             PG8_LDA(At, 0, 1); PG8_STAGE(PG8_SA(0, 0), a2, voffA);
;             PG8_BAR; PG8_WAIT_L(0); PG8_MMA(1, 0, At, B0); PG8_BAR; PG8_SCHED;
;             PG8_STAGE(PG8_SB(0, 1), b2 + hstepB, voffB);
;             PG8_WAIT_V(6); PG8_BAR; PG8_MMA(1, 1, At, B1); PG8_BAR;
;             PG8_LDB(B0, 1, 0); PG8_SCHED; PG8_LDA(At, 1, 0); PG8_STAGE(PG8_SA(0, 1), a2 + hstepA, voffA);
;             PG8_WAIT_L(8); PG8_BAR; PG8_WAIT_L(0); PG8_MMA(0, 0, At, B0); PG8_BAR; PG8_SCHED;
;             PG8_LDB(B1, 1, 1); PG8_STAGE(PG8_SB(1, 0), b3, voffB);
;             PG8_BAR; PG8_WAIT_L(0); PG8_MMA(0, 1, At, B1); PG8_BAR;
;             PG8_LDA(At, 1, 1); PG8_STAGE(PG8_SA(1, 0), a3, voffA);
;             PG8_BAR; PG8_WAIT_L(0); PG8_MMA(1, 0, At, B0); PG8_BAR; PG8_SCHED;
;             PG8_STAGE(PG8_SB(1, 1), b3 + hstepB, voffB);
;             PG8_WAIT_V(6); PG8_BAR; PG8_MMA(1, 1, At, B1); PG8_BAR;
	s_setprio 1
	v_mfma_f32_16x16x32_bf16 v[62:65], v[146:149], v[168:171], v[62:65]
	v_mfma_f32_16x16x32_bf16 v[58:61], v[160:163], v[168:171], v[58:61]
	v_mfma_f32_16x16x32_bf16 v[46:49], v[146:149], v[176:179], v[46:49]
	v_mfma_f32_16x16x32_bf16 v[42:45], v[160:163], v[176:179], v[42:45]
	v_mfma_f32_16x16x32_bf16 v[30:33], v[146:149], v[184:187], v[30:33]
	v_mfma_f32_16x16x32_bf16 v[26:29], v[160:163], v[184:187], v[26:29]
	v_mfma_f32_16x16x32_bf16 v[14:17], v[146:149], v[196:199], v[14:17]
	v_mfma_f32_16x16x32_bf16 v[10:13], v[160:163], v[196:199], v[10:13]
	v_mfma_f32_16x16x32_bf16 v[54:57], v[200:203], v[164:167], v[54:57]
	v_mfma_f32_16x16x32_bf16 v[50:53], v[208:211], v[164:167], v[50:53]
	v_mfma_f32_16x16x32_bf16 v[38:41], v[200:203], v[172:175], v[38:41]
	v_mfma_f32_16x16x32_bf16 v[34:37], v[208:211], v[172:175], v[34:37]
	v_mfma_f32_16x16x32_bf16 v[22:25], v[200:203], v[180:183], v[22:25]
	v_mfma_f32_16x16x32_bf16 v[18:21], v[208:211], v[180:183], v[18:21]
	v_mfma_f32_16x16x32_bf16 v[6:9], v[200:203], v[188:191], v[6:9]
	v_mfma_f32_16x16x32_bf16 v[2:5], v[208:211], v[188:191], v[2:5]
	v_mfma_f32_16x16x32_bf16 v[54:57], v[204:207], v[168:171], v[54:57]
	v_mfma_f32_16x16x32_bf16 v[50:53], v[212:215], v[168:171], v[50:53]
	v_mfma_f32_16x16x32_bf16 v[38:41], v[204:207], v[176:179], v[38:41]
	v_mfma_f32_16x16x32_bf16 v[34:37], v[212:215], v[176:179], v[34:37]
	v_mfma_f32_16x16x32_bf16 v[22:25], v[204:207], v[184:187], v[22:25]
	v_mfma_f32_16x16x32_bf16 v[18:21], v[212:215], v[184:187], v[18:21]
	v_mfma_f32_16x16x32_bf16 v[6:9], v[204:207], v[196:199], v[6:9]
	v_mfma_f32_16x16x32_bf16 v[2:5], v[212:215], v[196:199], v[2:5]
	s_setprio 0
	s_barrier
	s_add_i32 s8, 0, 0x18000
	v_add_u32_e32 v160, s8, v156
	ds_read_b128 v[142:145], v160
	ds_read_b128 v[146:149], v160 offset:1024
	ds_read_b128 v[150:153], v160 offset:2048
	ds_read_b128 v[160:163], v160 offset:3072
	s_add_u32 s6, s6, s36
	s_addc_u32 s7, s7, s37
	s_mov_b32 m0, s39
	v_lshl_add_u64 v[200:201], s[6:7], 0, v[130:131]
	ds_read_b128 v[164:167], v159 offset:32768
	ds_read_b128 v[168:171], v159 offset:33792
	ds_read_b128 v[172:175], v159 offset:34816
	ds_read_b128 v[176:179], v159 offset:35840
	ds_read_b128 v[180:183], v159 offset:36864
	ds_read_b128 v[184:187], v159 offset:37888
	ds_read_b128 v[188:191], v159 offset:38912
	ds_read_b128 v[196:199], v159 offset:39936
	global_load_lds_dwordx4 v[200:201], off
	v_lshl_add_u64 v[200:201], s[6:7], 0, v[132:133]
	s_mov_b32 m0, s40
	s_nop 0
	global_load_lds_dwordx4 v[200:201], off
	s_add_i32 s6, 0, 0x1c000
	v_add_u32_e32 v212, s6, v156
	ds_read_b128 v[200:203], v212
	ds_read_b128 v[204:207], v212 offset:1024
	ds_read_b128 v[208:211], v212 offset:2048
	ds_read_b128 v[212:215], v212 offset:3072
	s_waitcnt vmcnt(8)
	s_waitcnt lgkmcnt(0)
	v_mfma_f32_16x16x32_bf16 v[126:129], v[142:145], v[164:167], v[126:129]
	v_mfma_f32_16x16x32_bf16 v[122:125], v[150:153], v[164:167], v[122:125]
	v_mfma_f32_16x16x32_bf16 v[110:113], v[142:145], v[172:175], v[110:113]
	v_mfma_f32_16x16x32_bf16 v[106:109], v[150:153], v[172:175], v[106:109]
	v_mfma_f32_16x16x32_bf16 v[94:97], v[142:145], v[180:183], v[94:97]
	v_mfma_f32_16x16x32_bf16 v[90:93], v[150:153], v[180:183], v[90:93]
	v_mfma_f32_16x16x32_bf16 v[78:81], v[142:145], v[188:191], v[78:81]
	v_mfma_f32_16x16x32_bf16 v[74:77], v[150:153], v[188:191], v[74:77]
	s_barrier
	s_setprio 1
	v_mfma_f32_16x16x32_bf16 v[126:129], v[146:149], v[168:171], v[126:129]
	v_mfma_f32_16x16x32_bf16 v[122:125], v[160:163], v[168:171], v[122:125]
	v_mfma_f32_16x16x32_bf16 v[110:113], v[146:149], v[176:179], v[110:113]
	v_mfma_f32_16x16x32_bf16 v[106:109], v[160:163], v[176:179], v[106:109]
	v_mfma_f32_16x16x32_bf16 v[94:97], v[146:149], v[184:187], v[94:97]
	v_mfma_f32_16x16x32_bf16 v[90:93], v[160:163], v[184:187], v[90:93]
	v_mfma_f32_16x16x32_bf16 v[78:81], v[146:149], v[196:199], v[78:81]
	v_mfma_f32_16x16x32_bf16 v[74:77], v[160:163], v[196:199], v[74:77]
	v_mfma_f32_16x16x32_bf16 v[118:121], v[200:203], v[164:167], v[118:121]
	v_mfma_f32_16x16x32_bf16 v[114:117], v[208:211], v[164:167], v[114:117]
	v_mfma_f32_16x16x32_bf16 v[102:105], v[200:203], v[172:175], v[102:105]
	v_mfma_f32_16x16x32_bf16 v[98:101], v[208:211], v[172:175], v[98:101]
	v_mfma_f32_16x16x32_bf16 v[86:89], v[200:203], v[180:183], v[86:89]
	v_mfma_f32_16x16x32_bf16 v[82:85], v[208:211], v[180:183], v[82:85]
	v_mfma_f32_16x16x32_bf16 v[70:73], v[200:203], v[188:191], v[70:73]
	v_mfma_f32_16x16x32_bf16 v[66:69], v[208:211], v[188:191], v[66:69]
	v_mfma_f32_16x16x32_bf16 v[118:121], v[204:207], v[168:171], v[118:121]
	v_mfma_f32_16x16x32_bf16 v[114:117], v[212:215], v[168:171], v[114:117]
	v_mfma_f32_16x16x32_bf16 v[102:105], v[204:207], v[176:179], v[102:105]
	v_mfma_f32_16x16x32_bf16 v[98:101], v[212:215], v[176:179], v[98:101]
	v_mfma_f32_16x16x32_bf16 v[86:89], v[204:207], v[184:187], v[86:89]
	v_mfma_f32_16x16x32_bf16 v[82:85], v[212:215], v[184:187], v[82:85]
	v_mfma_f32_16x16x32_bf16 v[70:73], v[204:207], v[196:199], v[70:73]
	v_mfma_f32_16x16x32_bf16 v[66:69], v[212:215], v[196:199], v[66:69]
	s_setprio 0
	s_barrier
; __device__ __forceinline__ float pre_get(const Pre& p, int ai, int m, int fr) { return __shfl(p.v[ai], m * 16 + fr); }
; __device__ __forceinline__ float rstd_pre(const float* ss, float v) { return ss ? rsqrtf(v * (1.0f / 2048.0f) + 1e-6f) : 1.0f; }
; #define PG8_MMA(ai, bj, At, Bt) do { __builtin_amdgcn_s_setprio(1); _Pragma("unroll") for (int m = 0; m < 4; ++m) _Pragma("unroll") for (int n = 0; n < 2; ++n) _Pragma("unroll") for (int k = 0; k < 2; ++k) \
;         acc[ai][bj][m][n] = __builtin_amdgcn_mfma_f32_16x16x32_bf16(Bt[n][k], At[m][k], acc[ai][bj][m][n], 0, 0, 0); __builtin_amdgcn_s_setprio(0); } while (0)
; #define PG8_WAIT_V(n) asm volatile("s_waitcnt vmcnt(" #n ")" ::: "memory")
; #define PG8_BAR __builtin_amdgcn_s_barrier()
; template <class Epi>
; __device__ __forceinline__ void gemm_phase(LAS unsigned char* lds, const Gemm g, const Sched& S, const Epi& E) {
;     ...
;             PG8_WAIT_V(6); PG8_BAR; PG8_MMA(1, 1, At, B1); PG8_BAR;
;         }
;     __device__ __forceinline__ void operator()(const Acc& acc, const Unit& u, int wr, int wc, int fr, int fq, const Pre& pre) const {
;         const int colt = (u.pn < split) ? base0 + u.pn * 256 : base1 + (u.pn - split) * 256;
;         const int row0 = u.pm * 256 + wr * 64 + fr, col0 = colt + wc * 32 + 8 * fq;
;         bf16_t* Oz = O + (size_t)(u.zb * sOb + u.zh * sOh);
;         float rsq[2][4];
; #pragma unroll
;         for (int ai = 0; ai < 2; ++ai)
; #pragma unroll
;             for (int m = 0; m < 4; ++m) rsq[ai][m] = rstd_pre(ss, pre_get(pre, ai, m, fr));
; #pragma unroll
;         for (int ai = 0; ai < 2; ++ai)
; #pragma unroll
;             for (int m = 0; m < 4; ++m) { const float rs = scale * rsq[ai][m];
; #pragma unroll
;                 for (int bj = 0; bj < 2; ++bj) { f32x4 v0 = acc[ai][bj][m][0] * rs, v1 = acc[ai][bj][m][1] * rs;
	s_add_i32 s7, s8, s3
	v_lshl_add_u64 v[192:193], v[192:193], 0, s[60:61]
	s_mov_b32 m0, s7
	s_nop 0
	global_load_lds_dwordx4 v[192:193], off
	v_lshl_add_u64 v[192:193], v[194:195], 0, s[60:61]
	s_add_i32 m0, s7, 0x2000
	s_nop 0
	global_load_lds_dwordx4 v[192:193], off
	s_mov_b32 m0, s41
	v_lshl_add_u64 v[192:193], v[216:217], 0, s[60:61]
	ds_read_b128 v[164:167], v159 offset:49152
	ds_read_b128 v[168:171], v159 offset:50176
	ds_read_b128 v[172:175], v159 offset:51200
	ds_read_b128 v[176:179], v159 offset:52224
	ds_read_b128 v[180:183], v159 offset:53248
	ds_read_b128 v[184:187], v159 offset:54272
	ds_read_b128 v[188:191], v159 offset:55296
	ds_read_b128 v[196:199], v159 offset:56320
	global_load_lds_dwordx4 v[192:193], off
	v_lshl_add_u64 v[192:193], v[222:223], 0, s[60:61]
	s_mov_b32 m0, s42
	s_nop 0
	global_load_lds_dwordx4 v[192:193], off
	s_add_i32 s6, s6, s3
	v_lshl_add_u64 v[192:193], v[224:225], 0, s[60:61]
	s_mov_b32 m0, s6
	s_nop 0
	global_load_lds_dwordx4 v[192:193], off
	v_lshl_add_u64 v[192:193], v[226:227], 0, s[60:61]
	s_add_i32 m0, s6, 0x2000
	s_nop 0
	global_load_lds_dwordx4 v[192:193], off
	s_waitcnt vmcnt(8)
	s_waitcnt lgkmcnt(0)
	v_mfma_f32_16x16x32_bf16 v[62:65], v[142:145], v[164:167], v[62:65]
	v_mfma_f32_16x16x32_bf16 v[58:61], v[150:153], v[164:167], v[58:61]
	v_mfma_f32_16x16x32_bf16 v[46:49], v[142:145], v[172:175], v[46:49]
	v_mfma_f32_16x16x32_bf16 v[42:45], v[150:153], v[172:175], v[42:45]
	v_mfma_f32_16x16x32_bf16 v[30:33], v[142:145], v[180:183], v[30:33]
	v_mfma_f32_16x16x32_bf16 v[26:29], v[150:153], v[180:183], v[26:29]
	v_mfma_f32_16x16x32_bf16 v[14:17], v[142:145], v[188:191], v[14:17]
	v_mfma_f32_16x16x32_bf16 v[10:13], v[150:153], v[188:191], v[10:13]
	s_barrier
	s_setprio 1
	v_mfma_f32_16x16x32_bf16 v[62:65], v[146:149], v[168:171], v[62:65]
	v_mfma_f32_16x16x32_bf16 v[58:61], v[160:163], v[168:171], v[58:61]
	v_mfma_f32_16x16x32_bf16 v[46:49], v[146:149], v[176:179], v[46:49]
	v_mfma_f32_16x16x32_bf16 v[42:45], v[160:163], v[176:179], v[42:45]
	v_mfma_f32_16x16x32_bf16 v[30:33], v[146:149], v[184:187], v[30:33]
	v_mfma_f32_16x16x32_bf16 v[26:29], v[160:163], v[184:187], v[26:29]
	v_mfma_f32_16x16x32_bf16 v[14:17], v[146:149], v[196:199], v[14:17]
	v_mfma_f32_16x16x32_bf16 v[10:13], v[160:163], v[196:199], v[10:13]
	v_mfma_f32_16x16x32_bf16 v[54:57], v[200:203], v[164:167], v[54:57]
	v_mfma_f32_16x16x32_bf16 v[50:53], v[208:211], v[164:167], v[50:53]
	v_mfma_f32_16x16x32_bf16 v[38:41], v[200:203], v[172:175], v[38:41]
	v_mfma_f32_16x16x32_bf16 v[34:37], v[208:211], v[172:175], v[34:37]
	v_mfma_f32_16x16x32_bf16 v[22:25], v[200:203], v[180:183], v[22:25]
	v_mfma_f32_16x16x32_bf16 v[18:21], v[208:211], v[180:183], v[18:21]
	v_mfma_f32_16x16x32_bf16 v[6:9], v[200:203], v[188:191], v[6:9]
	v_mfma_f32_16x16x32_bf16 v[2:5], v[208:211], v[188:191], v[2:5]
	v_mfma_f32_16x16x32_bf16 v[54:57], v[204:207], v[168:171], v[54:57]
	v_mfma_f32_16x16x32_bf16 v[50:53], v[212:215], v[168:171], v[50:53]
	v_mfma_f32_16x16x32_bf16 v[38:41], v[204:207], v[176:179], v[38:41]
	v_mfma_f32_16x16x32_bf16 v[34:37], v[212:215], v[176:179], v[34:37]
	v_mfma_f32_16x16x32_bf16 v[22:25], v[204:207], v[184:187], v[22:25]
	v_mfma_f32_16x16x32_bf16 v[18:21], v[212:215], v[184:187], v[18:21]
	v_mfma_f32_16x16x32_bf16 v[6:9], v[204:207], v[196:199], v[6:9]
	v_mfma_f32_16x16x32_bf16 v[2:5], v[212:215], v[196:199], v[2:5]
	s_setprio 0
	s_add_u32 s4, s4, 0x100
	s_addc_u32 s5, s5, 0
	s_add_u32 s34, s34, 0x100
	s_addc_u32 s35, s35, 0
	s_cmp_ge_u32 s14, s73
	s_mov_b32 s6, s14
	s_barrier
	s_cbranch_scc0 .LBB0_555
	v_and_or_b32 v142, v220, 64, v154
	v_lshlrev_b32_e32 v148, 2, v142
	ds_bpermute_b32 v143, v148, v141
	ds_bpermute_b32 v142, v148, v141 offset:64
	s_mov_b32 s4, 0x3a000000
	ds_bpermute_b32 v145, v148, v141 offset:128
	ds_bpermute_b32 v144, v148, v141 offset:192
	v_readlane_b32 s8, v254, 29
	s_waitcnt lgkmcnt(0)
	v_pk_fma_f32 v[146:147], v[142:143], s[4:5], v[232:233] op_sel_hi:[1,0,0]
	ds_bpermute_b32 v143, v148, v140
	v_mul_f32_e32 v141, 0x4b800000, v147
	v_cmp_gt_f32_e32 vcc, s97, v147
	ds_bpermute_b32 v142, v148, v140 offset:64
	v_readlane_b32 s9, v254, 30
	v_cndmask_b32_e32 v141, v147, v141, vcc
	v_rsq_f32_e32 v141, v141
	v_cmp_gt_f32_e64 s[4:5], s97, v146
	s_mov_b64 s[90:91], -1
	v_mul_f32_e32 v147, 0x45800000, v141
	v_cndmask_b32_e32 v141, v141, v147, vcc
	v_cndmask_b32_e64 v147, v141, 1.0, s[78:79]
	ds_bpermute_b32 v141, v148, v140 offset:128
	ds_bpermute_b32 v140, v148, v140 offset:192
	v_mul_f32_e32 v148, s70, v147
	v_pk_mul_f32 v[152:153], v[122:123], v[148:149] op_sel_hi:[1,0]
	v_cndmask_b32_e64 v122, 0, 1, s[8:9]
	v_pk_mul_f32 v[128:129], v[128:129], v[148:149] op_sel_hi:[1,0]
	v_pk_mul_f32 v[150:151], v[126:127], v[148:149] op_sel_hi:[1,0]
	v_pk_mul_f32 v[126:127], v[124:125], v[148:149] op_sel_hi:[1,0]
	v_cmp_ne_u32_e64 s[6:7], 1, v122
	s_andn2_b64 vcc, exec, s[8:9]
	s_cbranch_vccnz .LBB0_558
	s_mov_b64 s[90:91], 0

; #define PG8_STAGE(bufoff, gbase, voff) do { _Pragma("unroll") for (int _i = 0; _i < 2; ++_i) \
;         __builtin_amdgcn_global_load_lds((const unsigned*)((const char*)(gbase) + (voff)[_i]), (LAS unsigned*)(lds + (bufoff) + ldsw + _i * 8192), 16, 0, 0); } while (0)
; #define PG8_LDA(dst, b, h) do { _Pragma("unroll") for (int m = 0; m < 4; ++m) _Pragma("unroll") for (int k = 0; k < 2; ++k) dst[m][k] = *(const LAS bf16x8*)(lds + PG8_SA(b, h) + aoff + m * 2048 + k * 1024); } while (0)
; #define PG8_WAIT_V(n) asm volatile("s_waitcnt vmcnt(" #n ")" ::: "memory")
; #define PG8_WAIT_L(n) asm volatile("s_waitcnt lgkmcnt(" #n ")" ::: "memory")
; template <class Epi>
; __device__ __forceinline__ void gemm_phase(LAS unsigned char* lds, const Gemm g, const Sched& S, const Epi& E) {
;     ...
;         for (int t = 0; t < nt; t += 2) {
;             const bool last = (t == nt - 2);
;             const char* a1 = cA + (size_t)(t + 1) * kstep;
;             const char* a2 = last ? nA : cA + (size_t)(t + 2) * kstep; const char* b2 = last ? nB : cB + (size_t)(t + 2) * kstep;
;             const char* a3 = a2 + kstep; const char* b3 = b2 + kstep;
;             PG8_LDB(B0, 0, 0); PG8_SCHED; PG8_LDA(At, 0, 0); PG8_STAGE(PG8_SA(1, 1), a1 + hstepA, voffA);
;             PG8_WAIT_L(8); PG8_BAR; PG8_WAIT_L(0); PG8_MMA(0, 0, At, B0); PG8_BAR; PG8_SCHED;
;             PG8_LDB(B1, 0, 1); PG8_STAGE(PG8_SB(0, 0), b2, voffB);
;             PG8_BAR; PG8_WAIT_L(0); PG8_MMA(0, 1, At, B1); PG8_BAR;
;             PG8_LDA(At, 0, 1); PG8_STAGE(PG8_SA(0, 0), a2, voffA);
;             PG8_BAR; PG8_WAIT_L(0); PG8_MMA(1, 0, At, B0); PG8_BAR; PG8_SCHED;
;             PG8_STAGE(PG8_SB(0, 1), b2 + hstepB, voffB);
;             PG8_WAIT_V(6); PG8_BAR; PG8_MMA(1, 1, At, B1); PG8_BAR;
;             PG8_LDB(B0, 1, 0); PG8_SCHED; PG8_LDA(At, 1, 0); PG8_STAGE(PG8_SA(0, 1), a2 + hstepA, voffA);
;             PG8_WAIT_L(8); PG8_BAR; PG8_WAIT_L(0); PG8_MMA(0, 0, At, B0); PG8_BAR; PG8_SCHED;
;             PG8_LDB(B1, 1, 1); PG8_STAGE(PG8_SB(1, 0), b3, voffB);
;             PG8_BAR; PG8_WAIT_L(0); PG8_MMA(0, 1, At, B1); PG8_BAR;
;             PG8_LDA(At, 1, 1); PG8_STAGE(PG8_SA(1, 0), a3, voffA);
;             PG8_BAR; PG8_WAIT_L(0); PG8_MMA(1, 0, At, B0); PG8_BAR; PG8_SCHED;
;             PG8_STAGE(PG8_SB(1, 1), b3 + hstepB, voffB);
;             PG8_WAIT_V(6); PG8_BAR; PG8_MMA(1, 1, At, B1); PG8_BAR;
.LBB0_649:
	s_add_i32 s14, s4, 2
	s_add_u32 s8, s0, 0x80
	s_addc_u32 s5, s1, 0
	s_add_i32 s9, 0, 0x10000
	v_add_u32_e32 v144, s9, v236
	ds_read_b128 v[132:135], v144
	ds_read_b128 v[136:139], v144 offset:1024
	ds_read_b128 v[140:143], v144 offset:2048
	ds_read_b128 v[144:147], v144 offset:3072
	s_cmp_eq_u32 s95, s4
	s_cselect_b32 s4, s48, s8
	s_cselect_b32 s5, s33, s5
	s_cselect_b32 s87, s51, s35
	s_cselect_b32 s86, s55, s34
	v_lshl_add_u64 v[176:177], s[0:1], 0, v[188:189]
	s_add_i32 m0, s89, 0xc000
	ds_read_b128 v[148:151], v239
	ds_read_b128 v[152:155], v239 offset:1024
	ds_read_b128 v[156:159], v239 offset:2048
	ds_read_b128 v[160:163], v239 offset:3072
	ds_read_b128 v[164:167], v239 offset:4096
	ds_read_b128 v[168:171], v239 offset:5120
	ds_read_b128 v[172:175], v239 offset:6144
	ds_read_b128 v[196:199], v239 offset:7168
	global_load_lds_dwordx4 v[176:177], off
	v_lshl_add_u64 v[176:177], s[0:1], 0, v[190:191]
	s_add_i32 m0, s89, 0xe000
	s_nop 0
	global_load_lds_dwordx4 v[176:177], off
	s_add_i32 s8, 0, 0x14000
	v_add_u32_e32 v176, s8, v236
	ds_read_b128 v[200:203], v176
	ds_read_b128 v[204:207], v176 offset:1024
	ds_read_b128 v[208:211], v176 offset:2048
	ds_read_b128 v[212:215], v176 offset:3072
	s_waitcnt vmcnt(8)
	s_waitcnt lgkmcnt(0)
	v_mfma_f32_16x16x32_bf16 v[126:129], v[132:135], v[148:151], v[126:129]
	v_mfma_f32_16x16x32_bf16 v[122:125], v[140:143], v[148:151], v[122:125]
	v_mfma_f32_16x16x32_bf16 v[110:113], v[132:135], v[156:159], v[110:113]
	v_mfma_f32_16x16x32_bf16 v[106:109], v[140:143], v[156:159], v[106:109]
	v_mfma_f32_16x16x32_bf16 v[94:97], v[132:135], v[164:167], v[94:97]
	v_mfma_f32_16x16x32_bf16 v[90:93], v[140:143], v[164:167], v[90:93]
	v_mfma_f32_16x16x32_bf16 v[78:81], v[132:135], v[172:175], v[78:81]
	v_mfma_f32_16x16x32_bf16 v[74:77], v[140:143], v[172:175], v[74:77]
	s_barrier
	s_setprio 1
	v_mfma_f32_16x16x32_bf16 v[126:129], v[136:139], v[152:155], v[126:129]
	v_mfma_f32_16x16x32_bf16 v[122:125], v[144:147], v[152:155], v[122:125]
	v_mfma_f32_16x16x32_bf16 v[110:113], v[136:139], v[160:163], v[110:113]
	v_mfma_f32_16x16x32_bf16 v[106:109], v[144:147], v[160:163], v[106:109]
	v_mfma_f32_16x16x32_bf16 v[94:97], v[136:139], v[168:171], v[94:97]
	v_mfma_f32_16x16x32_bf16 v[90:93], v[144:147], v[168:171], v[90:93]
	v_mfma_f32_16x16x32_bf16 v[78:81], v[136:139], v[196:199], v[78:81]
	v_mfma_f32_16x16x32_bf16 v[74:77], v[144:147], v[196:199], v[74:77]
	v_mfma_f32_16x16x32_bf16 v[118:121], v[200:203], v[148:151], v[118:121]
	v_mfma_f32_16x16x32_bf16 v[114:117], v[208:211], v[148:151], v[114:117]
	v_mfma_f32_16x16x32_bf16 v[102:105], v[200:203], v[156:159], v[102:105]
	v_mfma_f32_16x16x32_bf16 v[98:101], v[208:211], v[156:159], v[98:101]
	v_mfma_f32_16x16x32_bf16 v[86:89], v[200:203], v[164:167], v[86:89]
	v_mfma_f32_16x16x32_bf16 v[82:85], v[208:211], v[164:167], v[82:85]
	v_mfma_f32_16x16x32_bf16 v[70:73], v[200:203], v[172:175], v[70:73]
	v_mfma_f32_16x16x32_bf16 v[66:69], v[208:211], v[172:175], v[66:69]
	v_mfma_f32_16x16x32_bf16 v[118:121], v[204:207], v[152:155], v[118:121]
	v_mfma_f32_16x16x32_bf16 v[114:117], v[212:215], v[152:155], v[114:117]
	v_mfma_f32_16x16x32_bf16 v[102:105], v[204:207], v[160:163], v[102:105]
	v_mfma_f32_16x16x32_bf16 v[98:101], v[212:215], v[160:163], v[98:101]
	v_mfma_f32_16x16x32_bf16 v[86:89], v[204:207], v[168:171], v[86:89]
	v_mfma_f32_16x16x32_bf16 v[82:85], v[212:215], v[168:171], v[82:85]
	v_mfma_f32_16x16x32_bf16 v[70:73], v[204:207], v[196:199], v[70:73]
	v_mfma_f32_16x16x32_bf16 v[66:69], v[212:215], v[196:199], v[66:69]
	s_setprio 0
	s_barrier
	s_add_i32 s9, s9, s88
	v_lshl_add_u64 v[176:177], s[86:87], 0, v[180:181]
	s_mov_b32 m0, s9
	v_lshl_add_u64 v[192:193], s[86:87], 0, v[184:185]
	global_load_lds_dwordx4 v[176:177], off
	s_add_i32 m0, s9, 0x2000
	s_nop 0
	global_load_lds_dwordx4 v[192:193], off
	s_mov_b32 m0, s89
	v_lshl_add_u64 v[194:195], s[4:5], 0, v[178:179]
	ds_read_b128 v[148:151], v239 offset:16384
	ds_read_b128 v[152:155], v239 offset:17408
	ds_read_b128 v[156:159], v239 offset:18432
	ds_read_b128 v[160:163], v239 offset:19456
	ds_read_b128 v[164:167], v239 offset:20480
	ds_read_b128 v[168:171], v239 offset:21504
	ds_read_b128 v[172:175], v239 offset:22528
	ds_read_b128 v[196:199], v239 offset:23552
	global_load_lds_dwordx4 v[194:195], off
	v_lshl_add_u64 v[216:217], s[4:5], 0, v[182:183]
	s_mov_b32 m0, s90
	s_nop 0
	global_load_lds_dwordx4 v[216:217], off
	s_add_u32 s56, s86, s36
	s_addc_u32 s57, s87, s37
	s_add_i32 s8, s8, s88
	v_lshl_add_u64 v[222:223], s[56:57], 0, v[180:181]
	s_mov_b32 m0, s8
	v_lshl_add_u64 v[224:225], s[56:57], 0, v[184:185]
	global_load_lds_dwordx4 v[222:223], off
	s_add_i32 m0, s8, 0x2000
	s_nop 0
	global_load_lds_dwordx4 v[224:225], off
	s_waitcnt vmcnt(8)
	s_waitcnt lgkmcnt(0)
	v_mfma_f32_16x16x32_bf16 v[62:65], v[132:135], v[148:151], v[62:65]
	v_mfma_f32_16x16x32_bf16 v[58:61], v[140:143], v[148:151], v[58:61]
	v_mfma_f32_16x16x32_bf16 v[46:49], v[132:135], v[156:159], v[46:49]
	v_mfma_f32_16x16x32_bf16 v[42:45], v[140:143], v[156:159], v[42:45]
	v_mfma_f32_16x16x32_bf16 v[30:33], v[132:135], v[164:167], v[30:33]
	v_mfma_f32_16x16x32_bf16 v[26:29], v[140:143], v[164:167], v[26:29]
	v_mfma_f32_16x16x32_bf16 v[14:17], v[132:135], v[172:175], v[14:17]
	v_mfma_f32_16x16x32_bf16 v[10:13], v[140:143], v[172:175], v[10:13]
	s_barrier
; #define PG8_STAGE(bufoff, gbase, voff) do { _Pragma("unroll") for (int _i = 0; _i < 2; ++_i) \
;         __builtin_amdgcn_global_load_lds((const unsigned*)((const char*)(gbase) + (voff)[_i]), (LAS unsigned*)(lds + (bufoff) + ldsw + _i * 8192), 16, 0, 0); } while (0)
; #define PG8_LDA(dst, b, h) do { _Pragma("unroll") for (int m = 0; m < 4; ++m) _Pragma("unroll") for (int k = 0; k < 2; ++k) dst[m][k] = *(const LAS bf16x8*)(lds + PG8_SA(b, h) + aoff + m * 2048 + k * 1024); } while (0)
; #define PG8_LDB(dst, b, h) do { _Pragma("unroll") for (int n = 0; n < 2; ++n) _Pragma("unroll") for (int k = 0; k < 2; ++k) dst[n][k] = *(const LAS bf16x8*)(lds + PG8_SB(b, h) + boff + n * 2048 + k * 1024); } while (0)
; #define PG8_WAIT_V(n) asm volatile("s_waitcnt vmcnt(" #n ")" ::: "memory")
; #define PG8_WAIT_L(n) asm volatile("s_waitcnt lgkmcnt(" #n ")" ::: "memory")
; #define PG8_BAR __builtin_amdgcn_s_barrier()
; #define PG8_SCHED __builtin_amdgcn_sched_barrier(0)
; template <class Epi>
; __device__ __forceinline__ void gemm_phase(LAS unsigned char* lds, const Gemm g, const Sched& S, const Epi& E) {
;     ...
;             PG8_LDB(B0, 0, 0); PG8_SCHED; PG8_LDA(At, 0, 0); PG8_STAGE(PG8_SA(1, 1), a1 + hstepA, voffA);
;             PG8_WAIT_L(8); PG8_BAR; PG8_WAIT_L(0); PG8_MMA(0, 0, At, B0); PG8_BAR; PG8_SCHED;
;             PG8_LDB(B1, 0, 1); PG8_STAGE(PG8_SB(0, 0), b2, voffB);
;             PG8_BAR; PG8_WAIT_L(0); PG8_MMA(0, 1, At, B1); PG8_BAR;
;             PG8_LDA(At, 0, 1); PG8_STAGE(PG8_SA(0, 0), a2, voffA);
;             PG8_BAR; PG8_WAIT_L(0); PG8_MMA(1, 0, At, B0); PG8_BAR; PG8_SCHED;
;             PG8_STAGE(PG8_SB(0, 1), b2 + hstepB, voffB);
;             PG8_WAIT_V(6); PG8_BAR; PG8_MMA(1, 1, At, B1); PG8_BAR;
;             PG8_LDB(B0, 1, 0); PG8_SCHED; PG8_LDA(At, 1, 0); PG8_STAGE(PG8_SA(0, 1), a2 + hstepA, voffA);
;             PG8_WAIT_L(8); PG8_BAR; PG8_WAIT_L(0); PG8_MMA(0, 0, At, B0); PG8_BAR; PG8_SCHED;
;             PG8_LDB(B1, 1, 1); PG8_STAGE(PG8_SB(1, 0), b3, voffB);
;             PG8_BAR; PG8_WAIT_L(0); PG8_MMA(0, 1, At, B1); PG8_BAR;
;             PG8_LDA(At, 1, 1); PG8_STAGE(PG8_SA(1, 0), a3, voffA);
;             PG8_BAR; PG8_WAIT_L(0); PG8_MMA(1, 0, At, B0); PG8_BAR; PG8_SCHED;
;             PG8_STAGE(PG8_SB(1, 1), b3 + hstepB, voffB);
;             PG8_WAIT_V(6); PG8_BAR; PG8_MMA(1, 1, At, B1); PG8_BAR;
	s_setprio 1
	v_mfma_f32_16x16x32_bf16 v[62:65], v[136:139], v[152:155], v[62:65]
	v_mfma_f32_16x16x32_bf16 v[58:61], v[144:147], v[152:155], v[58:61]
	v_mfma_f32_16x16x32_bf16 v[46:49], v[136:139], v[160:163], v[46:49]
	v_mfma_f32_16x16x32_bf16 v[42:45], v[144:147], v[160:163], v[42:45]
	v_mfma_f32_16x16x32_bf16 v[30:33], v[136:139], v[168:171], v[30:33]
	v_mfma_f32_16x16x32_bf16 v[26:29], v[144:147], v[168:171], v[26:29]
	v_mfma_f32_16x16x32_bf16 v[14:17], v[136:139], v[196:199], v[14:17]
	v_mfma_f32_16x16x32_bf16 v[10:13], v[144:147], v[196:199], v[10:13]
	v_mfma_f32_16x16x32_bf16 v[54:57], v[200:203], v[148:151], v[54:57]
	v_mfma_f32_16x16x32_bf16 v[50:53], v[208:211], v[148:151], v[50:53]
	v_mfma_f32_16x16x32_bf16 v[38:41], v[200:203], v[156:159], v[38:41]
	v_mfma_f32_16x16x32_bf16 v[34:37], v[208:211], v[156:159], v[34:37]
	v_mfma_f32_16x16x32_bf16 v[22:25], v[200:203], v[164:167], v[22:25]
	v_mfma_f32_16x16x32_bf16 v[18:21], v[208:211], v[164:167], v[18:21]
	v_mfma_f32_16x16x32_bf16 v[6:9], v[200:203], v[172:175], v[6:9]
	v_mfma_f32_16x16x32_bf16 v[2:5], v[208:211], v[172:175], v[2:5]
	v_mfma_f32_16x16x32_bf16 v[54:57], v[204:207], v[152:155], v[54:57]
	v_mfma_f32_16x16x32_bf16 v[50:53], v[212:215], v[152:155], v[50:53]
	v_mfma_f32_16x16x32_bf16 v[38:41], v[204:207], v[160:163], v[38:41]
	v_mfma_f32_16x16x32_bf16 v[34:37], v[212:215], v[160:163], v[34:37]
	v_mfma_f32_16x16x32_bf16 v[22:25], v[204:207], v[168:171], v[22:25]
	v_mfma_f32_16x16x32_bf16 v[18:21], v[212:215], v[168:171], v[18:21]
	v_mfma_f32_16x16x32_bf16 v[6:9], v[204:207], v[196:199], v[6:9]
	v_mfma_f32_16x16x32_bf16 v[2:5], v[212:215], v[196:199], v[2:5]
	s_setprio 0
	s_barrier
	s_add_i32 s8, 0, 0x18000
	v_add_u32_e32 v144, s8, v236
	ds_read_b128 v[132:135], v144
	ds_read_b128 v[136:139], v144 offset:1024
	ds_read_b128 v[140:143], v144 offset:2048
	ds_read_b128 v[144:147], v144 offset:3072
	s_add_u32 s4, s4, s6
	s_addc_u32 s5, s5, s7
	s_mov_b32 m0, s91
	v_lshl_add_u64 v[200:201], s[4:5], 0, v[178:179]
	ds_read_b128 v[148:151], v239 offset:32768
	ds_read_b128 v[152:155], v239 offset:33792
	ds_read_b128 v[156:159], v239 offset:34816
	ds_read_b128 v[160:163], v239 offset:35840
	ds_read_b128 v[164:167], v239 offset:36864
	ds_read_b128 v[168:171], v239 offset:37888
	ds_read_b128 v[172:175], v239 offset:38912
	ds_read_b128 v[196:199], v239 offset:39936
	global_load_lds_dwordx4 v[200:201], off
	v_lshl_add_u64 v[200:201], s[4:5], 0, v[182:183]
	s_mov_b32 m0, s92
	s_nop 0
	global_load_lds_dwordx4 v[200:201], off
	s_add_i32 s4, 0, 0x1c000
	v_add_u32_e32 v212, s4, v236
	ds_read_b128 v[200:203], v212
	ds_read_b128 v[204:207], v212 offset:1024
	ds_read_b128 v[208:211], v212 offset:2048
	ds_read_b128 v[212:215], v212 offset:3072
	s_waitcnt vmcnt(8)
	s_waitcnt lgkmcnt(0)
	v_mfma_f32_16x16x32_bf16 v[126:129], v[132:135], v[148:151], v[126:129]
	v_mfma_f32_16x16x32_bf16 v[122:125], v[140:143], v[148:151], v[122:125]
	v_mfma_f32_16x16x32_bf16 v[110:113], v[132:135], v[156:159], v[110:113]
	v_mfma_f32_16x16x32_bf16 v[106:109], v[140:143], v[156:159], v[106:109]
	v_mfma_f32_16x16x32_bf16 v[94:97], v[132:135], v[164:167], v[94:97]
	v_mfma_f32_16x16x32_bf16 v[90:93], v[140:143], v[164:167], v[90:93]
	v_mfma_f32_16x16x32_bf16 v[78:81], v[132:135], v[172:175], v[78:81]
	v_mfma_f32_16x16x32_bf16 v[74:77], v[140:143], v[172:175], v[74:77]
	s_barrier
	s_setprio 1
	v_mfma_f32_16x16x32_bf16 v[126:129], v[136:139], v[152:155], v[126:129]
	v_mfma_f32_16x16x32_bf16 v[122:125], v[144:147], v[152:155], v[122:125]
	v_mfma_f32_16x16x32_bf16 v[110:113], v[136:139], v[160:163], v[110:113]
	v_mfma_f32_16x16x32_bf16 v[106:109], v[144:147], v[160:163], v[106:109]
	v_mfma_f32_16x16x32_bf16 v[94:97], v[136:139], v[168:171], v[94:97]
	v_mfma_f32_16x16x32_bf16 v[90:93], v[144:147], v[168:171], v[90:93]
	v_mfma_f32_16x16x32_bf16 v[78:81], v[136:139], v[196:199], v[78:81]
	v_mfma_f32_16x16x32_bf16 v[74:77], v[144:147], v[196:199], v[74:77]
	v_mfma_f32_16x16x32_bf16 v[118:121], v[200:203], v[148:151], v[118:121]
	v_mfma_f32_16x16x32_bf16 v[114:117], v[208:211], v[148:151], v[114:117]
	v_mfma_f32_16x16x32_bf16 v[102:105], v[200:203], v[156:159], v[102:105]
	v_mfma_f32_16x16x32_bf16 v[98:101], v[208:211], v[156:159], v[98:101]
	v_mfma_f32_16x16x32_bf16 v[86:89], v[200:203], v[164:167], v[86:89]
	v_mfma_f32_16x16x32_bf16 v[82:85], v[208:211], v[164:167], v[82:85]
	v_mfma_f32_16x16x32_bf16 v[70:73], v[200:203], v[172:175], v[70:73]
	v_mfma_f32_16x16x32_bf16 v[66:69], v[208:211], v[172:175], v[66:69]
	v_mfma_f32_16x16x32_bf16 v[118:121], v[204:207], v[152:155], v[118:121]
	v_mfma_f32_16x16x32_bf16 v[114:117], v[212:215], v[152:155], v[114:117]
	v_mfma_f32_16x16x32_bf16 v[102:105], v[204:207], v[160:163], v[102:105]
	v_mfma_f32_16x16x32_bf16 v[98:101], v[212:215], v[160:163], v[98:101]
	v_mfma_f32_16x16x32_bf16 v[86:89], v[204:207], v[168:171], v[86:89]
	v_mfma_f32_16x16x32_bf16 v[82:85], v[212:215], v[168:171], v[82:85]
	v_mfma_f32_16x16x32_bf16 v[70:73], v[204:207], v[196:199], v[70:73]
	v_mfma_f32_16x16x32_bf16 v[66:69], v[212:215], v[196:199], v[66:69]
	s_setprio 0
	s_barrier
; #define PG8_MMA(ai, bj, At, Bt) do { __builtin_amdgcn_s_setprio(1); _Pragma("unroll") for (int m = 0; m < 4; ++m) _Pragma("unroll") for (int n = 0; n < 2; ++n) _Pragma("unroll") for (int k = 0; k < 2; ++k) \
;         acc[ai][bj][m][n] = __builtin_amdgcn_mfma_f32_16x16x32_bf16(Bt[n][k], At[m][k], acc[ai][bj][m][n], 0, 0, 0); __builtin_amdgcn_s_setprio(0); } while (0)
; #define PG8_WAIT_V(n) asm volatile("s_waitcnt vmcnt(" #n ")" ::: "memory")
; #define PG8_BAR __builtin_amdgcn_s_barrier()
; template <class Epi>
; __device__ __forceinline__ void gemm_phase(LAS unsigned char* lds, const Gemm g, const Sched& S, const Epi& E) {
;     ...
;             PG8_WAIT_V(6); PG8_BAR; PG8_MMA(1, 1, At, B1); PG8_BAR;
;         }
;     __device__ __forceinline__ void operator()(const Acc& acc, const Unit& u, int wr, int wc, int fr, int fq, const Pre& pre) const {
;         const int tile = u.pn; int mode = 0; float scale0 = 1.f;
;         if (tile < 36) { const int tg = tile % 12; if (tg < 4) { mode = 1; scale0 = 0.08838834764831845f * LOG2E; } else if (tg < 8) mode = 1; }
;         else if (tile < 40) mode = 1;
;         else if (tile < 44) { mode = 1; scale0 = 0.08838834764831845f; }
;         else if (tile >= 52) mode = 2;
	s_add_i32 s5, s8, s88
	v_lshl_add_u64 v[176:177], v[176:177], 0, s[60:61]
	s_mov_b32 m0, s5
	s_nop 0
	global_load_lds_dwordx4 v[176:177], off
	v_lshl_add_u64 v[176:177], v[192:193], 0, s[60:61]
	s_add_i32 m0, s5, 0x2000
	s_nop 0
	global_load_lds_dwordx4 v[176:177], off
	s_mov_b32 m0, s93
	v_lshl_add_u64 v[176:177], v[194:195], 0, s[60:61]
	ds_read_b128 v[148:151], v239 offset:49152
	ds_read_b128 v[152:155], v239 offset:50176
	ds_read_b128 v[156:159], v239 offset:51200
	ds_read_b128 v[160:163], v239 offset:52224
	ds_read_b128 v[164:167], v239 offset:53248
	ds_read_b128 v[168:171], v239 offset:54272
	ds_read_b128 v[172:175], v239 offset:55296
	ds_read_b128 v[196:199], v239 offset:56320
	global_load_lds_dwordx4 v[176:177], off
	v_lshl_add_u64 v[176:177], v[216:217], 0, s[60:61]
	s_mov_b32 m0, s94
	s_nop 0
	global_load_lds_dwordx4 v[176:177], off
	s_add_i32 s4, s4, s88
	v_lshl_add_u64 v[176:177], v[222:223], 0, s[60:61]
	s_mov_b32 m0, s4
	s_nop 0
	global_load_lds_dwordx4 v[176:177], off
	v_lshl_add_u64 v[176:177], v[224:225], 0, s[60:61]
	s_add_i32 m0, s4, 0x2000
	s_nop 0
	global_load_lds_dwordx4 v[176:177], off
	s_waitcnt vmcnt(8)
	s_waitcnt lgkmcnt(0)
	v_mfma_f32_16x16x32_bf16 v[62:65], v[132:135], v[148:151], v[62:65]
	v_mfma_f32_16x16x32_bf16 v[58:61], v[140:143], v[148:151], v[58:61]
	v_mfma_f32_16x16x32_bf16 v[46:49], v[132:135], v[156:159], v[46:49]
	v_mfma_f32_16x16x32_bf16 v[42:45], v[140:143], v[156:159], v[42:45]
	v_mfma_f32_16x16x32_bf16 v[30:33], v[132:135], v[164:167], v[30:33]
	v_mfma_f32_16x16x32_bf16 v[26:29], v[140:143], v[164:167], v[26:29]
	v_mfma_f32_16x16x32_bf16 v[14:17], v[132:135], v[172:175], v[14:17]
	v_mfma_f32_16x16x32_bf16 v[10:13], v[140:143], v[172:175], v[10:13]
	s_barrier
	s_setprio 1
	v_mfma_f32_16x16x32_bf16 v[62:65], v[136:139], v[152:155], v[62:65]
	v_mfma_f32_16x16x32_bf16 v[58:61], v[144:147], v[152:155], v[58:61]
	v_mfma_f32_16x16x32_bf16 v[46:49], v[136:139], v[160:163], v[46:49]
	v_mfma_f32_16x16x32_bf16 v[42:45], v[144:147], v[160:163], v[42:45]
	v_mfma_f32_16x16x32_bf16 v[30:33], v[136:139], v[168:171], v[30:33]
	v_mfma_f32_16x16x32_bf16 v[26:29], v[144:147], v[168:171], v[26:29]
	v_mfma_f32_16x16x32_bf16 v[14:17], v[136:139], v[196:199], v[14:17]
	v_mfma_f32_16x16x32_bf16 v[10:13], v[144:147], v[196:199], v[10:13]
	v_mfma_f32_16x16x32_bf16 v[54:57], v[200:203], v[148:151], v[54:57]
	v_mfma_f32_16x16x32_bf16 v[50:53], v[208:211], v[148:151], v[50:53]
	v_mfma_f32_16x16x32_bf16 v[38:41], v[200:203], v[156:159], v[38:41]
	v_mfma_f32_16x16x32_bf16 v[34:37], v[208:211], v[156:159], v[34:37]
	v_mfma_f32_16x16x32_bf16 v[22:25], v[200:203], v[164:167], v[22:25]
	v_mfma_f32_16x16x32_bf16 v[18:21], v[208:211], v[164:167], v[18:21]
	v_mfma_f32_16x16x32_bf16 v[6:9], v[200:203], v[172:175], v[6:9]
	v_mfma_f32_16x16x32_bf16 v[2:5], v[208:211], v[172:175], v[2:5]
	v_mfma_f32_16x16x32_bf16 v[54:57], v[204:207], v[152:155], v[54:57]
	v_mfma_f32_16x16x32_bf16 v[50:53], v[212:215], v[152:155], v[50:53]
	v_mfma_f32_16x16x32_bf16 v[38:41], v[204:207], v[160:163], v[38:41]
	v_mfma_f32_16x16x32_bf16 v[34:37], v[212:215], v[160:163], v[34:37]
	v_mfma_f32_16x16x32_bf16 v[22:25], v[204:207], v[168:171], v[22:25]
	v_mfma_f32_16x16x32_bf16 v[18:21], v[212:215], v[168:171], v[18:21]
	v_mfma_f32_16x16x32_bf16 v[6:9], v[204:207], v[196:199], v[6:9]
	v_mfma_f32_16x16x32_bf16 v[2:5], v[212:215], v[196:199], v[2:5]
	s_setprio 0
	s_add_u32 s0, s0, 0x100
	s_addc_u32 s1, s1, 0
	s_add_u32 s34, s34, 0x100
	s_addc_u32 s35, s35, 0
	s_cmp_ge_u32 s14, s73
	s_mov_b32 s4, s14
	s_barrier
	s_cbranch_scc0 .LBB0_649
	s_cmp_gt_i32 s3, 35
	s_cbranch_scc0 .LBB0_652
	s_cmp_gt_u32 s3, 51
	s_cselect_b32 s8, 2, 0
	s_cmp_gt_u32 s3, 39
	s_cselect_b64 s[0:1], -1, 0
	s_cmp_lt_u32 s3, 44
	s_cselect_b64 s[14:15], -1, 0
	s_and_b64 s[4:5], s[14:15], exec
	s_cselect_b32 s4, 1, s8
	s_and_b64 vcc, s[0:1], s[14:15]
	v_mov_b32_e32 v132, 0x3db504f3
	v_cndmask_b32_e32 v240, 1.0, v132, vcc
	v_mov_b32_e32 v132, s4
	s_cbranch_execz .LBB0_653
	s_branch .LBB0_654

; #define PG8_STAGE(bufoff, gbase, voff) do { _Pragma("unroll") for (int _i = 0; _i < 2; ++_i) \
;         __builtin_amdgcn_global_load_lds((const unsigned*)((const char*)(gbase) + (voff)[_i]), (LAS unsigned*)(lds + (bufoff) + ldsw + _i * 8192), 16, 0, 0); } while (0)
; #define PG8_LDA(dst, b, h) do { _Pragma("unroll") for (int m = 0; m < 4; ++m) _Pragma("unroll") for (int k = 0; k < 2; ++k) dst[m][k] = *(const LAS bf16x8*)(lds + PG8_SA(b, h) + aoff + m * 2048 + k * 1024); } while (0)
; #define PG8_LDB(dst, b, h) do { _Pragma("unroll") for (int n = 0; n < 2; ++n) _Pragma("unroll") for (int k = 0; k < 2; ++k) dst[n][k] = *(const LAS bf16x8*)(lds + PG8_SB(b, h) + boff + n * 2048 + k * 1024); } while (0)
; #define PG8_WAIT_V(n) asm volatile("s_waitcnt vmcnt(" #n ")" ::: "memory")
; #define PG8_WAIT_L(n) asm volatile("s_waitcnt lgkmcnt(" #n ")" ::: "memory")
; #define PG8_BAR __builtin_amdgcn_s_barrier()
; #define PG8_SCHED __builtin_amdgcn_sched_barrier(0)
; template <class Epi>
; __device__ __forceinline__ void gemm_phase(LAS unsigned char* lds, const Gemm g, const Sched& S, const Epi& E) {
;     ...
;             PG8_LDB(B0, 0, 0); PG8_SCHED; PG8_LDA(At, 0, 0); PG8_STAGE(PG8_SA(1, 1), a1 + hstepA, voffA);
;             PG8_WAIT_L(8); PG8_BAR; PG8_WAIT_L(0); PG8_MMA(0, 0, At, B0); PG8_BAR; PG8_SCHED;
;             PG8_LDB(B1, 0, 1); PG8_STAGE(PG8_SB(0, 0), b2, voffB);
;             PG8_BAR; PG8_WAIT_L(0); PG8_MMA(0, 1, At, B1); PG8_BAR;
;             PG8_LDA(At, 0, 1); PG8_STAGE(PG8_SA(0, 0), a2, voffA);
;             PG8_BAR; PG8_WAIT_L(0); PG8_MMA(1, 0, At, B0); PG8_BAR; PG8_SCHED;
;             PG8_STAGE(PG8_SB(0, 1), b2 + hstepB, voffB);
;             PG8_WAIT_V(6); PG8_BAR; PG8_MMA(1, 1, At, B1); PG8_BAR;
;             PG8_LDB(B0, 1, 0); PG8_SCHED; PG8_LDA(At, 1, 0); PG8_STAGE(PG8_SA(0, 1), a2 + hstepA, voffA);
;             PG8_WAIT_L(8); PG8_BAR; PG8_WAIT_L(0); PG8_MMA(0, 0, At, B0); PG8_BAR; PG8_SCHED;
;             PG8_LDB(B1, 1, 1); PG8_STAGE(PG8_SB(1, 0), b3, voffB);
;             PG8_BAR; PG8_WAIT_L(0); PG8_MMA(0, 1, At, B1); PG8_BAR;
;             PG8_LDA(At, 1, 1); PG8_STAGE(PG8_SA(1, 0), a3, voffA);
;             PG8_BAR; PG8_WAIT_L(0); PG8_MMA(1, 0, At, B0); PG8_BAR; PG8_SCHED;
;             PG8_STAGE(PG8_SB(1, 1), b3 + hstepB, voffB);
;             PG8_WAIT_V(6); PG8_BAR; PG8_MMA(1, 1, At, B1); PG8_BAR;
.LBB0_719:
	s_add_i32 s14, s4, 2
	s_add_u32 s15, s0, 0x80
	s_addc_u32 s5, s1, 0
	s_add_i32 s8, 0, 0x10000
	v_add_u32_e32 v118, s8, v217
	ds_read_b128 v[106:109], v118
	ds_read_b128 v[110:113], v118 offset:1024
	ds_read_b128 v[114:117], v118 offset:2048
	ds_read_b128 v[118:121], v118 offset:3072
	s_cmp_eq_u32 s48, s4
	s_cselect_b32 s4, s59, s15
	s_cselect_b32 s5, s57, s5
	s_cselect_b32 s95, vcc_lo, s35
	s_cselect_b32 s94, vcc_hi, s34
	v_lshl_add_u64 v[154:155], s[0:1], 0, v[202:203]
	s_add_i32 m0, s52, 0xc000
	ds_read_b128 v[122:125], v235
	ds_read_b128 v[126:129], v235 offset:1024
	ds_read_b128 v[130:133], v235 offset:2048
	ds_read_b128 v[134:137], v235 offset:3072
	ds_read_b128 v[138:141], v235 offset:4096
	ds_read_b128 v[142:145], v235 offset:5120
	ds_read_b128 v[146:149], v235 offset:6144
	ds_read_b128 v[150:153], v235 offset:7168
	global_load_lds_dwordx4 v[154:155], off
	v_lshl_add_u64 v[154:155], s[0:1], 0, v[204:205]
	s_add_i32 m0, s52, 0xe000
	s_nop 0
	global_load_lds_dwordx4 v[154:155], off
	s_waitcnt lgkmcnt(8)
	s_waitcnt lgkmcnt(0)
	v_mfma_f32_16x16x32_bf16 v[162:165], v[114:117], v[130:133], v[162:165]
	v_mfma_f32_16x16x32_bf16 v[94:97], v[106:109], v[138:141], v[94:97]
	v_mfma_f32_16x16x32_bf16 v[90:93], v[114:117], v[138:141], v[90:93]
	v_mfma_f32_16x16x32_bf16 v[78:81], v[106:109], v[146:149], v[78:81]
	v_mfma_f32_16x16x32_bf16 v[74:77], v[114:117], v[146:149], v[74:77]
	v_mfma_f32_16x16x32_bf16 v[154:157], v[106:109], v[122:125], v[190:193]
	v_mfma_f32_16x16x32_bf16 v[158:161], v[114:117], v[122:125], v[186:189]
	v_mfma_f32_16x16x32_bf16 v[166:169], v[106:109], v[130:133], v[174:177]
	s_barrier
	s_waitcnt lgkmcnt(0)
	s_setprio 1
	s_waitcnt lgkmcnt(0)
	v_mfma_f32_16x16x32_bf16 v[162:165], v[118:121], v[134:137], v[162:165]
	v_mfma_f32_16x16x32_bf16 v[94:97], v[110:113], v[142:145], v[94:97]
	v_mfma_f32_16x16x32_bf16 v[90:93], v[118:121], v[142:145], v[90:93]
	v_mfma_f32_16x16x32_bf16 v[78:81], v[110:113], v[150:153], v[78:81]
	v_mfma_f32_16x16x32_bf16 v[74:77], v[118:121], v[150:153], v[74:77]
	v_mfma_f32_16x16x32_bf16 v[154:157], v[110:113], v[126:129], v[154:157]
	v_mfma_f32_16x16x32_bf16 v[158:161], v[118:121], v[126:129], v[158:161]
	v_mfma_f32_16x16x32_bf16 v[166:169], v[110:113], v[134:137], v[166:169]
	s_setprio 0
	s_barrier
	s_add_i32 s9, 0, 0x14000
	s_add_i32 s8, s8, s43
	v_add_u32_e32 v190, s9, v217
	v_lshl_add_u64 v[210:211], s[94:95], 0, v[0:1]
	s_mov_b32 m0, s8
	ds_read_b128 v[170:173], v190
	ds_read_b128 v[174:177], v190 offset:1024
	ds_read_b128 v[186:189], v190 offset:2048
	ds_read_b128 v[190:193], v190 offset:3072
	global_load_lds_dwordx4 v[210:211], off
	v_lshl_add_u64 v[212:213], s[94:95], 0, v[200:201]
	s_add_i32 m0, s8, 0x2000
	s_nop 0
	global_load_lds_dwordx4 v[212:213], off
	s_waitcnt lgkmcnt(0)
	v_mfma_f32_16x16x32_bf16 v[182:185], v[170:173], v[122:125], v[182:185]
	v_mfma_f32_16x16x32_bf16 v[102:105], v[170:173], v[130:133], v[102:105]
	v_mfma_f32_16x16x32_bf16 v[98:101], v[186:189], v[130:133], v[98:101]
	v_mfma_f32_16x16x32_bf16 v[86:89], v[170:173], v[138:141], v[86:89]
	v_mfma_f32_16x16x32_bf16 v[82:85], v[186:189], v[138:141], v[82:85]
	v_mfma_f32_16x16x32_bf16 v[70:73], v[170:173], v[146:149], v[70:73]
	v_mfma_f32_16x16x32_bf16 v[66:69], v[186:189], v[146:149], v[66:69]
	v_mfma_f32_16x16x32_bf16 v[182:185], v[174:177], v[126:129], v[182:185]
	s_barrier
	s_waitcnt lgkmcnt(0)
	s_setprio 1
	s_waitcnt lgkmcnt(0)
	v_mfma_f32_16x16x32_bf16 v[122:125], v[186:189], v[122:125], v[178:181]
	v_mfma_f32_16x16x32_bf16 v[102:105], v[174:177], v[134:137], v[102:105]
	v_mfma_f32_16x16x32_bf16 v[98:101], v[190:193], v[134:137], v[98:101]
	v_mfma_f32_16x16x32_bf16 v[86:89], v[174:177], v[142:145], v[86:89]
	v_mfma_f32_16x16x32_bf16 v[82:85], v[190:193], v[142:145], v[82:85]
	v_mfma_f32_16x16x32_bf16 v[70:73], v[174:177], v[150:153], v[70:73]
	v_mfma_f32_16x16x32_bf16 v[66:69], v[190:193], v[150:153], v[66:69]
	v_mfma_f32_16x16x32_bf16 v[122:125], v[190:193], v[126:129], v[122:125]
	s_setprio 0
	s_mov_b32 m0, s52
	v_lshl_add_u64 v[214:215], s[4:5], 0, v[196:197]
	s_barrier
	ds_read_b128 v[126:129], v235 offset:16384
	ds_read_b128 v[130:133], v235 offset:17408
	ds_read_b128 v[134:137], v235 offset:18432
	ds_read_b128 v[138:141], v235 offset:19456
	ds_read_b128 v[142:145], v235 offset:20480
	ds_read_b128 v[146:149], v235 offset:21504
	ds_read_b128 v[150:153], v235 offset:22528
	ds_read_b128 v[178:181], v235 offset:23552
	global_load_lds_dwordx4 v[214:215], off
	v_lshl_add_u64 v[222:223], s[4:5], 0, v[198:199]
	s_mov_b32 m0, s53
	s_nop 0
	global_load_lds_dwordx4 v[222:223], off
	s_waitcnt lgkmcnt(0)
	v_mfma_f32_16x16x32_bf16 v[62:65], v[106:109], v[126:129], v[62:65]
	v_mfma_f32_16x16x32_bf16 v[58:61], v[114:117], v[126:129], v[58:61]
	v_mfma_f32_16x16x32_bf16 v[46:49], v[106:109], v[134:137], v[46:49]
	v_mfma_f32_16x16x32_bf16 v[42:45], v[114:117], v[134:137], v[42:45]
	v_mfma_f32_16x16x32_bf16 v[30:33], v[106:109], v[142:145], v[30:33]
	v_mfma_f32_16x16x32_bf16 v[26:29], v[114:117], v[142:145], v[26:29]
	v_mfma_f32_16x16x32_bf16 v[14:17], v[106:109], v[150:153], v[14:17]
	v_mfma_f32_16x16x32_bf16 v[10:13], v[114:117], v[150:153], v[10:13]
	s_barrier
	s_waitcnt lgkmcnt(0)
	s_setprio 1
	s_waitcnt lgkmcnt(0)
	v_mfma_f32_16x16x32_bf16 v[62:65], v[110:113], v[130:133], v[62:65]
	v_mfma_f32_16x16x32_bf16 v[58:61], v[118:121], v[130:133], v[58:61]
	v_mfma_f32_16x16x32_bf16 v[46:49], v[110:113], v[138:141], v[46:49]
	v_mfma_f32_16x16x32_bf16 v[42:45], v[118:121], v[138:141], v[42:45]
	v_mfma_f32_16x16x32_bf16 v[30:33], v[110:113], v[146:149], v[30:33]
	v_mfma_f32_16x16x32_bf16 v[26:29], v[118:121], v[146:149], v[26:29]
	v_mfma_f32_16x16x32_bf16 v[14:17], v[110:113], v[178:181], v[14:17]
	v_mfma_f32_16x16x32_bf16 v[10:13], v[118:121], v[178:181], v[10:13]
	s_setprio 0
	s_barrier
; #define PG8_STAGE(bufoff, gbase, voff) do { _Pragma("unroll") for (int _i = 0; _i < 2; ++_i) \
;         __builtin_amdgcn_global_load_lds((const unsigned*)((const char*)(gbase) + (voff)[_i]), (LAS unsigned*)(lds + (bufoff) + ldsw + _i * 8192), 16, 0, 0); } while (0)
; #define PG8_LDA(dst, b, h) do { _Pragma("unroll") for (int m = 0; m < 4; ++m) _Pragma("unroll") for (int k = 0; k < 2; ++k) dst[m][k] = *(const LAS bf16x8*)(lds + PG8_SA(b, h) + aoff + m * 2048 + k * 1024); } while (0)
; #define PG8_LDB(dst, b, h) do { _Pragma("unroll") for (int n = 0; n < 2; ++n) _Pragma("unroll") for (int k = 0; k < 2; ++k) dst[n][k] = *(const LAS bf16x8*)(lds + PG8_SB(b, h) + boff + n * 2048 + k * 1024); } while (0)
; #define PG8_WAIT_V(n) asm volatile("s_waitcnt vmcnt(" #n ")" ::: "memory")
; #define PG8_WAIT_L(n) asm volatile("s_waitcnt lgkmcnt(" #n ")" ::: "memory")
; #define PG8_BAR __builtin_amdgcn_s_barrier()
; #define PG8_SCHED __builtin_amdgcn_sched_barrier(0)
; template <class Epi>
; __device__ __forceinline__ void gemm_phase(LAS unsigned char* lds, const Gemm g, const Sched& S, const Epi& E) {
;     ...
;             PG8_LDB(B0, 0, 0); PG8_SCHED; PG8_LDA(At, 0, 0); PG8_STAGE(PG8_SA(1, 1), a1 + hstepA, voffA);
;             PG8_WAIT_L(8); PG8_BAR; PG8_WAIT_L(0); PG8_MMA(0, 0, At, B0); PG8_BAR; PG8_SCHED;
;             PG8_LDB(B1, 0, 1); PG8_STAGE(PG8_SB(0, 0), b2, voffB);
;             PG8_BAR; PG8_WAIT_L(0); PG8_MMA(0, 1, At, B1); PG8_BAR;
;             PG8_LDA(At, 0, 1); PG8_STAGE(PG8_SA(0, 0), a2, voffA);
;             PG8_BAR; PG8_WAIT_L(0); PG8_MMA(1, 0, At, B0); PG8_BAR; PG8_SCHED;
;             PG8_STAGE(PG8_SB(0, 1), b2 + hstepB, voffB);
;             PG8_WAIT_V(6); PG8_BAR; PG8_MMA(1, 1, At, B1); PG8_BAR;
;             PG8_LDB(B0, 1, 0); PG8_SCHED; PG8_LDA(At, 1, 0); PG8_STAGE(PG8_SA(0, 1), a2 + hstepA, voffA);
;             PG8_WAIT_L(8); PG8_BAR; PG8_WAIT_L(0); PG8_MMA(0, 0, At, B0); PG8_BAR; PG8_SCHED;
;             PG8_LDB(B1, 1, 1); PG8_STAGE(PG8_SB(1, 0), b3, voffB);
;             PG8_BAR; PG8_WAIT_L(0); PG8_MMA(0, 1, At, B1); PG8_BAR;
;             PG8_LDA(At, 1, 1); PG8_STAGE(PG8_SA(1, 0), a3, voffA);
;             PG8_BAR; PG8_WAIT_L(0); PG8_MMA(1, 0, At, B0); PG8_BAR; PG8_SCHED;
;             PG8_STAGE(PG8_SB(1, 1), b3 + hstepB, voffB);
;             PG8_WAIT_V(6); PG8_BAR; PG8_MMA(1, 1, At, B1); PG8_BAR;
	s_add_u32 s94, s94, s76
	s_addc_u32 s95, s95, s77
	s_add_i32 s8, s9, s43
	v_lshl_add_u64 v[224:225], s[94:95], 0, v[0:1]
	s_mov_b32 m0, s8
	v_lshl_add_u64 v[226:227], s[94:95], 0, v[200:201]
	global_load_lds_dwordx4 v[224:225], off
	s_add_i32 m0, s8, 0x2000
	s_nop 0
	global_load_lds_dwordx4 v[226:227], off
	s_waitcnt vmcnt(6)
	s_waitcnt lgkmcnt(0)
	v_mfma_f32_16x16x32_bf16 v[54:57], v[170:173], v[126:129], v[54:57]
	v_mfma_f32_16x16x32_bf16 v[50:53], v[186:189], v[126:129], v[50:53]
	v_mfma_f32_16x16x32_bf16 v[38:41], v[170:173], v[134:137], v[38:41]
	v_mfma_f32_16x16x32_bf16 v[34:37], v[186:189], v[134:137], v[34:37]
	v_mfma_f32_16x16x32_bf16 v[22:25], v[170:173], v[142:145], v[22:25]
	v_mfma_f32_16x16x32_bf16 v[18:21], v[186:189], v[142:145], v[18:21]
	v_mfma_f32_16x16x32_bf16 v[6:9], v[170:173], v[150:153], v[6:9]
	v_mfma_f32_16x16x32_bf16 v[2:5], v[186:189], v[150:153], v[2:5]
	s_barrier
	s_setprio 1
	v_mfma_f32_16x16x32_bf16 v[54:57], v[174:177], v[130:133], v[54:57]
	v_mfma_f32_16x16x32_bf16 v[50:53], v[190:193], v[130:133], v[50:53]
	v_mfma_f32_16x16x32_bf16 v[38:41], v[174:177], v[138:141], v[38:41]
	v_mfma_f32_16x16x32_bf16 v[34:37], v[190:193], v[138:141], v[34:37]
	v_mfma_f32_16x16x32_bf16 v[22:25], v[174:177], v[146:149], v[22:25]
	v_mfma_f32_16x16x32_bf16 v[18:21], v[190:193], v[146:149], v[18:21]
	v_mfma_f32_16x16x32_bf16 v[6:9], v[174:177], v[178:181], v[6:9]
	v_mfma_f32_16x16x32_bf16 v[2:5], v[190:193], v[178:181], v[2:5]
	s_setprio 0
	s_add_i32 s8, 0, 0x18000
	v_add_u32_e32 v118, s8, v217
	s_barrier
	ds_read_b128 v[106:109], v118
	ds_read_b128 v[110:113], v118 offset:1024
	ds_read_b128 v[114:117], v118 offset:2048
	ds_read_b128 v[118:121], v118 offset:3072
	s_add_u32 s4, s4, s40
	s_addc_u32 s5, s5, s41
	s_mov_b32 m0, s56
	v_lshl_add_u64 v[174:175], s[4:5], 0, v[196:197]
	ds_read_b128 v[126:129], v235 offset:32768
	ds_read_b128 v[130:133], v235 offset:33792
	ds_read_b128 v[134:137], v235 offset:34816
	ds_read_b128 v[138:141], v235 offset:35840
	ds_read_b128 v[142:145], v235 offset:36864
	ds_read_b128 v[146:149], v235 offset:37888
	ds_read_b128 v[150:153], v235 offset:38912
	ds_read_b128 v[170:173], v235 offset:39936
	global_load_lds_dwordx4 v[174:175], off
	v_lshl_add_u64 v[174:175], s[4:5], 0, v[198:199]
	s_mov_b32 m0, s67
	s_nop 0
	global_load_lds_dwordx4 v[174:175], off
	s_waitcnt lgkmcnt(8)
	s_waitcnt lgkmcnt(0)
	v_mfma_f32_16x16x32_bf16 v[154:157], v[106:109], v[126:129], v[154:157]
	v_mfma_f32_16x16x32_bf16 v[190:193], v[110:113], v[130:133], v[154:157]
	v_mfma_f32_16x16x32_bf16 v[154:157], v[114:117], v[126:129], v[158:161]
	v_mfma_f32_16x16x32_bf16 v[186:189], v[118:121], v[130:133], v[154:157]
	v_mfma_f32_16x16x32_bf16 v[154:157], v[106:109], v[134:137], v[166:169]
	v_mfma_f32_16x16x32_bf16 v[174:177], v[110:113], v[138:141], v[154:157]
	v_mfma_f32_16x16x32_bf16 v[154:157], v[114:117], v[134:137], v[162:165]
	v_mfma_f32_16x16x32_bf16 v[94:97], v[106:109], v[142:145], v[94:97]
	s_barrier
	s_waitcnt lgkmcnt(0)
	s_setprio 1
	s_waitcnt lgkmcnt(0)
	v_mfma_f32_16x16x32_bf16 v[90:93], v[114:117], v[142:145], v[90:93]
	v_mfma_f32_16x16x32_bf16 v[78:81], v[106:109], v[150:153], v[78:81]
	v_mfma_f32_16x16x32_bf16 v[74:77], v[114:117], v[150:153], v[74:77]
	v_mfma_f32_16x16x32_bf16 v[162:165], v[118:121], v[138:141], v[154:157]
	v_mfma_f32_16x16x32_bf16 v[94:97], v[110:113], v[146:149], v[94:97]
	v_mfma_f32_16x16x32_bf16 v[90:93], v[118:121], v[146:149], v[90:93]
	v_mfma_f32_16x16x32_bf16 v[78:81], v[110:113], v[170:173], v[78:81]
	v_mfma_f32_16x16x32_bf16 v[74:77], v[118:121], v[170:173], v[74:77]
	s_setprio 0
	s_barrier
	s_add_i32 s4, 0, 0x1c000
	v_add_u32_e32 v178, s4, v217
	s_add_i32 s5, s8, s43
	ds_read_b128 v[154:157], v178
	ds_read_b128 v[158:161], v178 offset:1024
	ds_read_b128 v[166:169], v178 offset:2048
	ds_read_b128 v[206:209], v178 offset:3072
	v_lshl_add_u64 v[178:179], v[210:211], 0, s[60:61]
	s_mov_b32 m0, s5
	s_nop 0
	global_load_lds_dwordx4 v[178:179], off
	v_lshl_add_u64 v[178:179], v[212:213], 0, s[60:61]
	s_add_i32 m0, s5, 0x2000
	s_nop 0
	global_load_lds_dwordx4 v[178:179], off
	s_waitcnt lgkmcnt(0)
	v_mfma_f32_16x16x32_bf16 v[178:181], v[154:157], v[126:129], v[182:185]
	v_mfma_f32_16x16x32_bf16 v[122:125], v[166:169], v[126:129], v[122:125]
	v_mfma_f32_16x16x32_bf16 v[102:105], v[154:157], v[134:137], v[102:105]
	v_mfma_f32_16x16x32_bf16 v[98:101], v[166:169], v[134:137], v[98:101]
	v_mfma_f32_16x16x32_bf16 v[86:89], v[154:157], v[142:145], v[86:89]
	v_mfma_f32_16x16x32_bf16 v[82:85], v[166:169], v[142:145], v[82:85]
	v_mfma_f32_16x16x32_bf16 v[70:73], v[154:157], v[150:153], v[70:73]
	v_mfma_f32_16x16x32_bf16 v[66:69], v[166:169], v[150:153], v[66:69]
	s_barrier
	s_waitcnt lgkmcnt(0)
	s_setprio 1
	s_waitcnt lgkmcnt(0)
	v_mfma_f32_16x16x32_bf16 v[182:185], v[158:161], v[130:133], v[178:181]
	v_mfma_f32_16x16x32_bf16 v[178:181], v[206:209], v[130:133], v[122:125]
	v_mfma_f32_16x16x32_bf16 v[102:105], v[158:161], v[138:141], v[102:105]
	v_mfma_f32_16x16x32_bf16 v[98:101], v[206:209], v[138:141], v[98:101]
	v_mfma_f32_16x16x32_bf16 v[86:89], v[158:161], v[146:149], v[86:89]
	v_mfma_f32_16x16x32_bf16 v[82:85], v[206:209], v[146:149], v[82:85]
	v_mfma_f32_16x16x32_bf16 v[70:73], v[158:161], v[170:173], v[70:73]
	v_mfma_f32_16x16x32_bf16 v[66:69], v[206:209], v[170:173], v[66:69]
	s_setprio 0
	s_mov_b32 m0, s51
	v_lshl_add_u64 v[170:171], v[214:215], 0, s[60:61]
	s_barrier
; #define PG8_MMA(ai, bj, At, Bt) do { __builtin_amdgcn_s_setprio(1); _Pragma("unroll") for (int m = 0; m < 4; ++m) _Pragma("unroll") for (int n = 0; n < 2; ++n) _Pragma("unroll") for (int k = 0; k < 2; ++k) \
;         acc[ai][bj][m][n] = __builtin_amdgcn_mfma_f32_16x16x32_bf16(Bt[n][k], At[m][k], acc[ai][bj][m][n], 0, 0, 0); __builtin_amdgcn_s_setprio(0); } while (0)
; #define PG8_WAIT_V(n) asm volatile("s_waitcnt vmcnt(" #n ")" ::: "memory")
; #define PG8_BAR __builtin_amdgcn_s_barrier()
; template <class Epi>
; __device__ __forceinline__ void gemm_phase(LAS unsigned char* lds, const Gemm g, const Sched& S, const Epi& E) {
;     ...
;             PG8_WAIT_V(6); PG8_BAR; PG8_MMA(1, 1, At, B1); PG8_BAR;
;         }
;     __device__ __forceinline__ void operator()(const Acc& acc, const Unit& u, int wr, int wc, int fr, int fq, const Pre& pre) const {
;         const int row0 = u.pm * 256 + wr * 64 + fr, col0 = u.pn * 256 + wc * 32 + 8 * fq;
;         const size_t zo = (size_t)(u.zb * sOb + u.zh * sOh);
; #pragma unroll
;         for (int ai = 0; ai < 2; ++ai) {
;             f32x4 bv[4][2][2];
;             if (base) {
; #pragma unroll
;                 for (int m = 0; m < 4; ++m) { const size_t off = zo + (size_t)(row0 + ai * 128 + m * 16) * ldc + col0;
; #pragma unroll
;                     for (int bj = 0; bj < 2; ++bj)
; #pragma unroll
;                         for (int n = 0; n < 2; ++n) bv[m][bj][n] = *(const f32x4*)(base + off + bj * 128 + n * 4); }
	ds_read_b128 v[122:125], v235 offset:49152
	ds_read_b128 v[126:129], v235 offset:50176
	ds_read_b128 v[130:133], v235 offset:51200
	ds_read_b128 v[134:137], v235 offset:52224
	ds_read_b128 v[138:141], v235 offset:53248
	ds_read_b128 v[142:145], v235 offset:54272
	ds_read_b128 v[146:149], v235 offset:55296
	ds_read_b128 v[150:153], v235 offset:56320
	global_load_lds_dwordx4 v[170:171], off
	v_lshl_add_u64 v[170:171], v[222:223], 0, s[60:61]
	s_mov_b32 m0, s2
	s_nop 0
	global_load_lds_dwordx4 v[170:171], off
	s_waitcnt lgkmcnt(0)
	v_mfma_f32_16x16x32_bf16 v[62:65], v[106:109], v[122:125], v[62:65]
	v_mfma_f32_16x16x32_bf16 v[58:61], v[114:117], v[122:125], v[58:61]
	v_mfma_f32_16x16x32_bf16 v[46:49], v[106:109], v[130:133], v[46:49]
	v_mfma_f32_16x16x32_bf16 v[42:45], v[114:117], v[130:133], v[42:45]
	v_mfma_f32_16x16x32_bf16 v[30:33], v[106:109], v[138:141], v[30:33]
	v_mfma_f32_16x16x32_bf16 v[26:29], v[114:117], v[138:141], v[26:29]
	v_mfma_f32_16x16x32_bf16 v[14:17], v[106:109], v[146:149], v[14:17]
	v_mfma_f32_16x16x32_bf16 v[10:13], v[114:117], v[146:149], v[10:13]
	s_barrier
	s_waitcnt lgkmcnt(0)
	s_setprio 1
	s_waitcnt lgkmcnt(0)
	v_mfma_f32_16x16x32_bf16 v[62:65], v[110:113], v[126:129], v[62:65]
	v_mfma_f32_16x16x32_bf16 v[58:61], v[118:121], v[126:129], v[58:61]
	v_mfma_f32_16x16x32_bf16 v[46:49], v[110:113], v[134:137], v[46:49]
	v_mfma_f32_16x16x32_bf16 v[42:45], v[118:121], v[134:137], v[42:45]
	v_mfma_f32_16x16x32_bf16 v[30:33], v[110:113], v[142:145], v[30:33]
	v_mfma_f32_16x16x32_bf16 v[26:29], v[118:121], v[142:145], v[26:29]
	v_mfma_f32_16x16x32_bf16 v[14:17], v[110:113], v[150:153], v[14:17]
	v_mfma_f32_16x16x32_bf16 v[10:13], v[118:121], v[150:153], v[10:13]
	s_setprio 0
	s_barrier
	s_add_i32 s4, s4, s43
	v_lshl_add_u64 v[106:107], v[224:225], 0, s[60:61]
	s_mov_b32 m0, s4
	s_nop 0
	global_load_lds_dwordx4 v[106:107], off
	v_lshl_add_u64 v[106:107], v[226:227], 0, s[60:61]
	s_add_i32 m0, s4, 0x2000
	s_nop 0
	global_load_lds_dwordx4 v[106:107], off
	s_waitcnt vmcnt(6)
	s_waitcnt lgkmcnt(0)
	v_mfma_f32_16x16x32_bf16 v[54:57], v[154:157], v[122:125], v[54:57]
	v_mfma_f32_16x16x32_bf16 v[50:53], v[166:169], v[122:125], v[50:53]
	v_mfma_f32_16x16x32_bf16 v[38:41], v[154:157], v[130:133], v[38:41]
	v_mfma_f32_16x16x32_bf16 v[34:37], v[166:169], v[130:133], v[34:37]
	v_mfma_f32_16x16x32_bf16 v[22:25], v[154:157], v[138:141], v[22:25]
	v_mfma_f32_16x16x32_bf16 v[18:21], v[166:169], v[138:141], v[18:21]
	v_mfma_f32_16x16x32_bf16 v[6:9], v[154:157], v[146:149], v[6:9]
	v_mfma_f32_16x16x32_bf16 v[2:5], v[166:169], v[146:149], v[2:5]
	s_barrier
	s_setprio 1
	v_mfma_f32_16x16x32_bf16 v[54:57], v[158:161], v[126:129], v[54:57]
	v_mfma_f32_16x16x32_bf16 v[50:53], v[206:209], v[126:129], v[50:53]
	v_mfma_f32_16x16x32_bf16 v[38:41], v[158:161], v[134:137], v[38:41]
	v_mfma_f32_16x16x32_bf16 v[34:37], v[206:209], v[134:137], v[34:37]
	v_mfma_f32_16x16x32_bf16 v[22:25], v[158:161], v[142:145], v[22:25]
	v_mfma_f32_16x16x32_bf16 v[18:21], v[206:209], v[142:145], v[18:21]
	v_mfma_f32_16x16x32_bf16 v[6:9], v[158:161], v[150:153], v[6:9]
	v_mfma_f32_16x16x32_bf16 v[2:5], v[206:209], v[150:153], v[2:5]
	s_setprio 0
	s_add_u32 s0, s0, 0x100
	s_addc_u32 s1, s1, 0
	s_add_u32 s34, s34, 0x100
	s_addc_u32 s35, s35, 0
	s_cmp_ge_u32 s14, s73
	s_mov_b32 s4, s14
	s_barrier
	s_cbranch_scc0 .LBB0_719
	s_ashr_i32 s0, s42, 31
	s_ashr_i32 s4, s24, 31
	v_readlane_b32 s8, v253, 59
	s_mul_hi_u32 s1, s74, s42
	s_mul_i32 s0, s74, s0
	v_readlane_b32 s9, v253, 60
	s_mul_hi_u32 s5, s8, s24
	s_mul_i32 s4, s8, s4
	s_add_i32 s0, s1, s0
	s_mul_i32 s1, s75, s42
	s_add_i32 s4, s5, s4
	s_mul_i32 s5, s9, s24
	v_lshl_add_u32 v206, s97, 8, v216
	s_add_i32 s0, s0, s1
	s_mul_i32 s1, s74, s42
	s_add_i32 s4, s4, s5
	s_mul_i32 s5, s8, s24
	v_lshl_or_b32 v210, s96, 8, v234
	s_add_u32 s94, s1, s5
	v_ashrrev_i32_e32 v207, 31, v206
	s_addc_u32 s95, s0, s4
	v_ashrrev_i32_e32 v211, 31, v210
	s_mov_b64 s[0:1], -1
	s_and_b64 vcc, exec, s[78:79]
	v_mul_lo_u32 v208, s13, v206
	v_mul_lo_u32 v236, s12, v207
	v_or_b32_e32 v239, 16, v206
	v_or_b32_e32 v238, 32, v206
	v_or_b32_e32 v237, 48, v206
	s_cbranch_vccz .LBB0_722
	s_lshl_b64 s[0:1], s[94:95], 2
	v_readlane_b32 s4, v254, 7
	v_readlane_b32 s5, v254, 8
	s_add_u32 s0, s4, s0
	s_addc_u32 s1, s5, s1
	v_lshl_add_u64 v[154:155], v[210:211], 2, s[0:1]
	v_mad_u64_u32 v[212:213], s[0:1], s12, v206, 0
	v_mul_lo_u32 v124, s13, v239
	v_mad_u64_u32 v[122:123], s[0:1], s12, v239, 0
	v_mul_lo_u32 v140, s13, v238
	v_mad_u64_u32 v[138:139], s[0:1], s12, v238, 0
	v_mul_lo_u32 v158, s13, v237
	v_mad_u64_u32 v[156:157], s[0:1], s12, v237, 0
	v_add3_u32 v213, v213, v236, v208
	v_add3_u32 v123, v123, v236, v124
	v_add3_u32 v139, v139, v236, v140
	v_add3_u32 v157, v157, v236, v158
	v_lshl_add_u64 v[118:119], v[212:213], 2, v[154:155]
	v_lshl_add_u64 v[134:135], v[122:123], 2, v[154:155]
	v_lshl_add_u64 v[150:151], v[138:139], 2, v[154:155]
	v_lshl_add_u64 v[170:171], v[156:157], 2, v[154:155]
	flat_load_dwordx4 v[106:109], v[118:119]
	flat_load_dwordx4 v[110:113], v[118:119] offset:16
	flat_load_dwordx4 v[114:117], v[118:119] offset:512
	s_nop 0
	flat_load_dwordx4 v[118:121], v[118:119] offset:528
	s_nop 0
	flat_load_dwordx4 v[122:125], v[134:135]
	flat_load_dwordx4 v[126:129], v[134:135] offset:16
	flat_load_dwordx4 v[130:133], v[134:135] offset:512
	s_nop 0
	flat_load_dwordx4 v[134:137], v[134:135] offset:528
	s_nop 0
	flat_load_dwordx4 v[138:141], v[150:151]
	flat_load_dwordx4 v[142:145], v[150:151] offset:16
	flat_load_dwordx4 v[146:149], v[150:151] offset:512
	s_nop 0
	flat_load_dwordx4 v[150:153], v[150:151] offset:528
	s_nop 0
	flat_load_dwordx4 v[154:157], v[170:171]
	flat_load_dwordx4 v[158:161], v[170:171] offset:16
	flat_load_dwordx4 v[166:169], v[170:171] offset:512
	s_nop 0
	flat_load_dwordx4 v[170:173], v[170:171] offset:528
	s_mov_b64 s[0:1], 0

; #define PG8_STAGE(bufoff, gbase, voff) do { _Pragma("unroll") for (int _i = 0; _i < 2; ++_i) \
;         __builtin_amdgcn_global_load_lds((const unsigned*)((const char*)(gbase) + (voff)[_i]), (LAS unsigned*)(lds + (bufoff) + ldsw + _i * 8192), 16, 0, 0); } while (0)
; #define PG8_LDA(dst, b, h) do { _Pragma("unroll") for (int m = 0; m < 4; ++m) _Pragma("unroll") for (int k = 0; k < 2; ++k) dst[m][k] = *(const LAS bf16x8*)(lds + PG8_SA(b, h) + aoff + m * 2048 + k * 1024); } while (0)
; #define PG8_WAIT_V(n) asm volatile("s_waitcnt vmcnt(" #n ")" ::: "memory")
; #define PG8_WAIT_L(n) asm volatile("s_waitcnt lgkmcnt(" #n ")" ::: "memory")
; template <class Epi>
; __device__ __forceinline__ void gemm_phase(LAS unsigned char* lds, const Gemm g, const Sched& S, const Epi& E) {
;     ...
;         for (int t = 0; t < nt; t += 2) {
;             const bool last = (t == nt - 2);
;             const char* a1 = cA + (size_t)(t + 1) * kstep;
;             const char* a2 = last ? nA : cA + (size_t)(t + 2) * kstep; const char* b2 = last ? nB : cB + (size_t)(t + 2) * kstep;
;             const char* a3 = a2 + kstep; const char* b3 = b2 + kstep;
;             PG8_LDB(B0, 0, 0); PG8_SCHED; PG8_LDA(At, 0, 0); PG8_STAGE(PG8_SA(1, 1), a1 + hstepA, voffA);
;             PG8_WAIT_L(8); PG8_BAR; PG8_WAIT_L(0); PG8_MMA(0, 0, At, B0); PG8_BAR; PG8_SCHED;
;             PG8_LDB(B1, 0, 1); PG8_STAGE(PG8_SB(0, 0), b2, voffB);
;             PG8_BAR; PG8_WAIT_L(0); PG8_MMA(0, 1, At, B1); PG8_BAR;
;             PG8_LDA(At, 0, 1); PG8_STAGE(PG8_SA(0, 0), a2, voffA);
;             PG8_BAR; PG8_WAIT_L(0); PG8_MMA(1, 0, At, B0); PG8_BAR; PG8_SCHED;
;             PG8_STAGE(PG8_SB(0, 1), b2 + hstepB, voffB);
;             PG8_WAIT_V(6); PG8_BAR; PG8_MMA(1, 1, At, B1); PG8_BAR;
;             PG8_LDB(B0, 1, 0); PG8_SCHED; PG8_LDA(At, 1, 0); PG8_STAGE(PG8_SA(0, 1), a2 + hstepA, voffA);
;             PG8_WAIT_L(8); PG8_BAR; PG8_WAIT_L(0); PG8_MMA(0, 0, At, B0); PG8_BAR; PG8_SCHED;
;             PG8_LDB(B1, 1, 1); PG8_STAGE(PG8_SB(1, 0), b3, voffB);
;             PG8_BAR; PG8_WAIT_L(0); PG8_MMA(0, 1, At, B1); PG8_BAR;
;             PG8_LDA(At, 1, 1); PG8_STAGE(PG8_SA(1, 0), a3, voffA);
;             PG8_BAR; PG8_WAIT_L(0); PG8_MMA(1, 0, At, B0); PG8_BAR; PG8_SCHED;
;             PG8_STAGE(PG8_SB(1, 1), b3 + hstepB, voffB);
;             PG8_WAIT_V(6); PG8_BAR; PG8_MMA(1, 1, At, B1); PG8_BAR;
.LBB0_825:
	s_add_i32 s86, s68, 2
	s_add_u32 s70, s4, 0x80
	s_addc_u32 s69, s5, 0
	s_add_i32 s87, 0, 0x10000
	v_add_u32_e32 v144, s87, v145
	ds_read_b128 v[152:155], v144
	ds_read_b128 v[156:159], v144 offset:1024
	ds_read_b128 v[160:163], v144 offset:2048
	ds_read_b128 v[164:167], v144 offset:3072
	s_cmp_eq_u32 s77, s68
	s_cselect_b32 s68, s59, s70
	s_cselect_b32 s69, s57, s69
	s_cselect_b32 s71, s82, s85
	s_cselect_b32 s70, s83, s84
	v_lshl_add_u64 v[192:193], s[4:5], 0, v[136:137]
	s_add_i32 m0, s33, 0xc000
	ds_read_b128 v[168:171], v151
	ds_read_b128 v[172:175], v151 offset:1024
	ds_read_b128 v[176:179], v151 offset:2048
	ds_read_b128 v[180:183], v151 offset:3072
	ds_read_b128 v[184:187], v151 offset:4096
	ds_read_b128 v[188:191], v151 offset:5120
	ds_read_b128 v[196:199], v151 offset:6144
	ds_read_b128 v[200:203], v151 offset:7168
	global_load_lds_dwordx4 v[192:193], off
	v_lshl_add_u64 v[192:193], s[4:5], 0, v[138:139]
	s_add_i32 m0, s33, 0xe000
	s_nop 0
	global_load_lds_dwordx4 v[192:193], off
	s_add_i32 s88, 0, 0x14000
	v_add_u32_e32 v144, s88, v145
	ds_read_b128 v[204:207], v144
	ds_read_b128 v[208:211], v144 offset:1024
	ds_read_b128 v[212:215], v144 offset:2048
	ds_read_b128 v[234:237], v144 offset:3072
	s_waitcnt vmcnt(8)
	s_waitcnt lgkmcnt(0)
	v_mfma_f32_16x16x32_bf16 v[126:129], v[152:155], v[168:171], v[126:129]
	v_mfma_f32_16x16x32_bf16 v[122:125], v[160:163], v[168:171], v[122:125]
	v_mfma_f32_16x16x32_bf16 v[110:113], v[152:155], v[176:179], v[110:113]
	v_mfma_f32_16x16x32_bf16 v[106:109], v[160:163], v[176:179], v[106:109]
	v_mfma_f32_16x16x32_bf16 v[94:97], v[152:155], v[184:187], v[94:97]
	v_mfma_f32_16x16x32_bf16 v[90:93], v[160:163], v[184:187], v[90:93]
	v_mfma_f32_16x16x32_bf16 v[78:81], v[152:155], v[196:199], v[78:81]
	v_mfma_f32_16x16x32_bf16 v[74:77], v[160:163], v[196:199], v[74:77]
	s_barrier
	s_setprio 1
	v_mfma_f32_16x16x32_bf16 v[126:129], v[156:159], v[172:175], v[126:129]
	v_mfma_f32_16x16x32_bf16 v[122:125], v[164:167], v[172:175], v[122:125]
	v_mfma_f32_16x16x32_bf16 v[110:113], v[156:159], v[180:183], v[110:113]
	v_mfma_f32_16x16x32_bf16 v[106:109], v[164:167], v[180:183], v[106:109]
	v_mfma_f32_16x16x32_bf16 v[94:97], v[156:159], v[188:191], v[94:97]
	v_mfma_f32_16x16x32_bf16 v[90:93], v[164:167], v[188:191], v[90:93]
	v_mfma_f32_16x16x32_bf16 v[78:81], v[156:159], v[200:203], v[78:81]
	v_mfma_f32_16x16x32_bf16 v[74:77], v[164:167], v[200:203], v[74:77]
	v_mfma_f32_16x16x32_bf16 v[118:121], v[204:207], v[168:171], v[118:121]
	v_mfma_f32_16x16x32_bf16 v[114:117], v[212:215], v[168:171], v[114:117]
	v_mfma_f32_16x16x32_bf16 v[102:105], v[204:207], v[176:179], v[102:105]
	v_mfma_f32_16x16x32_bf16 v[98:101], v[212:215], v[176:179], v[98:101]
	v_mfma_f32_16x16x32_bf16 v[86:89], v[204:207], v[184:187], v[86:89]
	v_mfma_f32_16x16x32_bf16 v[82:85], v[212:215], v[184:187], v[82:85]
	v_mfma_f32_16x16x32_bf16 v[70:73], v[204:207], v[196:199], v[70:73]
	v_mfma_f32_16x16x32_bf16 v[66:69], v[212:215], v[196:199], v[66:69]
	v_mfma_f32_16x16x32_bf16 v[118:121], v[208:211], v[172:175], v[118:121]
	v_mfma_f32_16x16x32_bf16 v[114:117], v[234:237], v[172:175], v[114:117]
	v_mfma_f32_16x16x32_bf16 v[102:105], v[208:211], v[180:183], v[102:105]
	v_mfma_f32_16x16x32_bf16 v[98:101], v[234:237], v[180:183], v[98:101]
	v_mfma_f32_16x16x32_bf16 v[86:89], v[208:211], v[188:191], v[86:89]
	v_mfma_f32_16x16x32_bf16 v[82:85], v[234:237], v[188:191], v[82:85]
	v_mfma_f32_16x16x32_bf16 v[70:73], v[208:211], v[200:203], v[70:73]
	v_mfma_f32_16x16x32_bf16 v[66:69], v[234:237], v[200:203], v[66:69]
	s_setprio 0
	s_barrier
	s_add_i32 s87, s87, s51
	v_lshl_add_u64 v[192:193], s[70:71], 0, v[0:1]
	s_mov_b32 m0, s87
	s_nop 0
	global_load_lds_dwordx4 v[192:193], off
	v_lshl_add_u64 v[216:217], s[70:71], 0, v[134:135]
	s_add_i32 m0, s87, 0x2000
	s_nop 0
	global_load_lds_dwordx4 v[216:217], off
	s_mov_b32 m0, s33
	v_lshl_add_u64 v[222:223], s[68:69], 0, v[130:131]
	ds_read_b128 v[168:171], v151 offset:16384
	ds_read_b128 v[172:175], v151 offset:17408
	ds_read_b128 v[176:179], v151 offset:18432
	ds_read_b128 v[180:183], v151 offset:19456
	ds_read_b128 v[184:187], v151 offset:20480
	ds_read_b128 v[188:191], v151 offset:21504
	ds_read_b128 v[196:199], v151 offset:22528
	ds_read_b128 v[200:203], v151 offset:23552
	global_load_lds_dwordx4 v[222:223], off
	v_lshl_add_u64 v[224:225], s[68:69], 0, v[132:133]
	s_mov_b32 m0, s48
	s_nop 0
	global_load_lds_dwordx4 v[224:225], off
	s_add_u32 s70, s70, s14
	s_addc_u32 s71, s71, s15
	s_add_i32 s87, s88, s51
	v_lshl_add_u64 v[226:227], s[70:71], 0, v[0:1]
	s_mov_b32 m0, s87
	v_lshl_add_u64 v[228:229], s[70:71], 0, v[134:135]
	global_load_lds_dwordx4 v[226:227], off
	s_add_i32 m0, s87, 0x2000
	s_nop 0
	global_load_lds_dwordx4 v[228:229], off
	s_waitcnt vmcnt(8)
	s_waitcnt lgkmcnt(0)
	v_mfma_f32_16x16x32_bf16 v[62:65], v[152:155], v[168:171], v[62:65]
	v_mfma_f32_16x16x32_bf16 v[58:61], v[160:163], v[168:171], v[58:61]
	v_mfma_f32_16x16x32_bf16 v[46:49], v[152:155], v[176:179], v[46:49]
	v_mfma_f32_16x16x32_bf16 v[42:45], v[160:163], v[176:179], v[42:45]
	v_mfma_f32_16x16x32_bf16 v[30:33], v[152:155], v[184:187], v[30:33]
	v_mfma_f32_16x16x32_bf16 v[26:29], v[160:163], v[184:187], v[26:29]
	v_mfma_f32_16x16x32_bf16 v[14:17], v[152:155], v[196:199], v[14:17]
	v_mfma_f32_16x16x32_bf16 v[10:13], v[160:163], v[196:199], v[10:13]
	s_barrier
; #define PG8_STAGE(bufoff, gbase, voff) do { _Pragma("unroll") for (int _i = 0; _i < 2; ++_i) \
;         __builtin_amdgcn_global_load_lds((const unsigned*)((const char*)(gbase) + (voff)[_i]), (LAS unsigned*)(lds + (bufoff) + ldsw + _i * 8192), 16, 0, 0); } while (0)
; #define PG8_LDA(dst, b, h) do { _Pragma("unroll") for (int m = 0; m < 4; ++m) _Pragma("unroll") for (int k = 0; k < 2; ++k) dst[m][k] = *(const LAS bf16x8*)(lds + PG8_SA(b, h) + aoff + m * 2048 + k * 1024); } while (0)
; #define PG8_LDB(dst, b, h) do { _Pragma("unroll") for (int n = 0; n < 2; ++n) _Pragma("unroll") for (int k = 0; k < 2; ++k) dst[n][k] = *(const LAS bf16x8*)(lds + PG8_SB(b, h) + boff + n * 2048 + k * 1024); } while (0)
; #define PG8_WAIT_V(n) asm volatile("s_waitcnt vmcnt(" #n ")" ::: "memory")
; #define PG8_WAIT_L(n) asm volatile("s_waitcnt lgkmcnt(" #n ")" ::: "memory")
; #define PG8_BAR __builtin_amdgcn_s_barrier()
; #define PG8_SCHED __builtin_amdgcn_sched_barrier(0)
; template <class Epi>
; __device__ __forceinline__ void gemm_phase(LAS unsigned char* lds, const Gemm g, const Sched& S, const Epi& E) {
;     ...
;             PG8_LDB(B0, 0, 0); PG8_SCHED; PG8_LDA(At, 0, 0); PG8_STAGE(PG8_SA(1, 1), a1 + hstepA, voffA);
;             PG8_WAIT_L(8); PG8_BAR; PG8_WAIT_L(0); PG8_MMA(0, 0, At, B0); PG8_BAR; PG8_SCHED;
;             PG8_LDB(B1, 0, 1); PG8_STAGE(PG8_SB(0, 0), b2, voffB);
;             PG8_BAR; PG8_WAIT_L(0); PG8_MMA(0, 1, At, B1); PG8_BAR;
;             PG8_LDA(At, 0, 1); PG8_STAGE(PG8_SA(0, 0), a2, voffA);
;             PG8_BAR; PG8_WAIT_L(0); PG8_MMA(1, 0, At, B0); PG8_BAR; PG8_SCHED;
;             PG8_STAGE(PG8_SB(0, 1), b2 + hstepB, voffB);
;             PG8_WAIT_V(6); PG8_BAR; PG8_MMA(1, 1, At, B1); PG8_BAR;
;             PG8_LDB(B0, 1, 0); PG8_SCHED; PG8_LDA(At, 1, 0); PG8_STAGE(PG8_SA(0, 1), a2 + hstepA, voffA);
;             PG8_WAIT_L(8); PG8_BAR; PG8_WAIT_L(0); PG8_MMA(0, 0, At, B0); PG8_BAR; PG8_SCHED;
;             PG8_LDB(B1, 1, 1); PG8_STAGE(PG8_SB(1, 0), b3, voffB);
;             PG8_BAR; PG8_WAIT_L(0); PG8_MMA(0, 1, At, B1); PG8_BAR;
;             PG8_LDA(At, 1, 1); PG8_STAGE(PG8_SA(1, 0), a3, voffA);
;             PG8_BAR; PG8_WAIT_L(0); PG8_MMA(1, 0, At, B0); PG8_BAR; PG8_SCHED;
;             PG8_STAGE(PG8_SB(1, 1), b3 + hstepB, voffB);
;             PG8_WAIT_V(6); PG8_BAR; PG8_MMA(1, 1, At, B1); PG8_BAR;
	s_setprio 1
	v_mfma_f32_16x16x32_bf16 v[62:65], v[156:159], v[172:175], v[62:65]
	v_mfma_f32_16x16x32_bf16 v[58:61], v[164:167], v[172:175], v[58:61]
	v_mfma_f32_16x16x32_bf16 v[46:49], v[156:159], v[180:183], v[46:49]
	v_mfma_f32_16x16x32_bf16 v[42:45], v[164:167], v[180:183], v[42:45]
	v_mfma_f32_16x16x32_bf16 v[30:33], v[156:159], v[188:191], v[30:33]
	v_mfma_f32_16x16x32_bf16 v[26:29], v[164:167], v[188:191], v[26:29]
	v_mfma_f32_16x16x32_bf16 v[14:17], v[156:159], v[200:203], v[14:17]
	v_mfma_f32_16x16x32_bf16 v[10:13], v[164:167], v[200:203], v[10:13]
	v_mfma_f32_16x16x32_bf16 v[54:57], v[204:207], v[168:171], v[54:57]
	v_mfma_f32_16x16x32_bf16 v[50:53], v[212:215], v[168:171], v[50:53]
	v_mfma_f32_16x16x32_bf16 v[38:41], v[204:207], v[176:179], v[38:41]
	v_mfma_f32_16x16x32_bf16 v[34:37], v[212:215], v[176:179], v[34:37]
	v_mfma_f32_16x16x32_bf16 v[22:25], v[204:207], v[184:187], v[22:25]
	v_mfma_f32_16x16x32_bf16 v[18:21], v[212:215], v[184:187], v[18:21]
	v_mfma_f32_16x16x32_bf16 v[6:9], v[204:207], v[196:199], v[6:9]
	v_mfma_f32_16x16x32_bf16 v[2:5], v[212:215], v[196:199], v[2:5]
	v_mfma_f32_16x16x32_bf16 v[54:57], v[208:211], v[172:175], v[54:57]
	v_mfma_f32_16x16x32_bf16 v[50:53], v[234:237], v[172:175], v[50:53]
	v_mfma_f32_16x16x32_bf16 v[38:41], v[208:211], v[180:183], v[38:41]
	v_mfma_f32_16x16x32_bf16 v[34:37], v[234:237], v[180:183], v[34:37]
	v_mfma_f32_16x16x32_bf16 v[22:25], v[208:211], v[188:191], v[22:25]
	v_mfma_f32_16x16x32_bf16 v[18:21], v[234:237], v[188:191], v[18:21]
	v_mfma_f32_16x16x32_bf16 v[6:9], v[208:211], v[200:203], v[6:9]
	v_mfma_f32_16x16x32_bf16 v[2:5], v[234:237], v[200:203], v[2:5]
	s_setprio 0
	s_barrier
	s_add_i32 s70, 0, 0x18000
	v_add_u32_e32 v144, s70, v145
	ds_read_b128 v[152:155], v144
	ds_read_b128 v[156:159], v144 offset:1024
	ds_read_b128 v[160:163], v144 offset:2048
	ds_read_b128 v[164:167], v144 offset:3072
	s_add_u32 s68, s68, s6
	s_addc_u32 s69, s69, s7
	s_mov_b32 m0, s58
	v_lshl_add_u64 v[204:205], s[68:69], 0, v[130:131]
	ds_read_b128 v[168:171], v151 offset:32768
	ds_read_b128 v[172:175], v151 offset:33792
	ds_read_b128 v[176:179], v151 offset:34816
	ds_read_b128 v[180:183], v151 offset:35840
	ds_read_b128 v[184:187], v151 offset:36864
	ds_read_b128 v[188:191], v151 offset:37888
	ds_read_b128 v[196:199], v151 offset:38912
	ds_read_b128 v[200:203], v151 offset:39936
	global_load_lds_dwordx4 v[204:205], off
	v_lshl_add_u64 v[204:205], s[68:69], 0, v[132:133]
	s_mov_b32 m0, s72
	s_nop 0
	global_load_lds_dwordx4 v[204:205], off
	s_add_i32 s68, 0, 0x1c000
	v_add_u32_e32 v144, s68, v145
	ds_read_b128 v[204:207], v144
	ds_read_b128 v[208:211], v144 offset:1024
	ds_read_b128 v[212:215], v144 offset:2048
	ds_read_b128 v[234:237], v144 offset:3072
	s_waitcnt vmcnt(8)
	s_waitcnt lgkmcnt(0)
	v_mfma_f32_16x16x32_bf16 v[126:129], v[152:155], v[168:171], v[126:129]
	v_mfma_f32_16x16x32_bf16 v[122:125], v[160:163], v[168:171], v[122:125]
	v_mfma_f32_16x16x32_bf16 v[110:113], v[152:155], v[176:179], v[110:113]
	v_mfma_f32_16x16x32_bf16 v[106:109], v[160:163], v[176:179], v[106:109]
	v_mfma_f32_16x16x32_bf16 v[94:97], v[152:155], v[184:187], v[94:97]
	v_mfma_f32_16x16x32_bf16 v[90:93], v[160:163], v[184:187], v[90:93]
	v_mfma_f32_16x16x32_bf16 v[78:81], v[152:155], v[196:199], v[78:81]
	v_mfma_f32_16x16x32_bf16 v[74:77], v[160:163], v[196:199], v[74:77]
	s_barrier
	s_setprio 1
	v_mfma_f32_16x16x32_bf16 v[126:129], v[156:159], v[172:175], v[126:129]
	v_mfma_f32_16x16x32_bf16 v[122:125], v[164:167], v[172:175], v[122:125]
	v_mfma_f32_16x16x32_bf16 v[110:113], v[156:159], v[180:183], v[110:113]
	v_mfma_f32_16x16x32_bf16 v[106:109], v[164:167], v[180:183], v[106:109]
	v_mfma_f32_16x16x32_bf16 v[94:97], v[156:159], v[188:191], v[94:97]
	v_mfma_f32_16x16x32_bf16 v[90:93], v[164:167], v[188:191], v[90:93]
	v_mfma_f32_16x16x32_bf16 v[78:81], v[156:159], v[200:203], v[78:81]
	v_mfma_f32_16x16x32_bf16 v[74:77], v[164:167], v[200:203], v[74:77]
	v_mfma_f32_16x16x32_bf16 v[118:121], v[204:207], v[168:171], v[118:121]
	v_mfma_f32_16x16x32_bf16 v[114:117], v[212:215], v[168:171], v[114:117]
	v_mfma_f32_16x16x32_bf16 v[102:105], v[204:207], v[176:179], v[102:105]
	v_mfma_f32_16x16x32_bf16 v[98:101], v[212:215], v[176:179], v[98:101]
	v_mfma_f32_16x16x32_bf16 v[86:89], v[204:207], v[184:187], v[86:89]
	v_mfma_f32_16x16x32_bf16 v[82:85], v[212:215], v[184:187], v[82:85]
	v_mfma_f32_16x16x32_bf16 v[70:73], v[204:207], v[196:199], v[70:73]
	v_mfma_f32_16x16x32_bf16 v[66:69], v[212:215], v[196:199], v[66:69]
	v_mfma_f32_16x16x32_bf16 v[118:121], v[208:211], v[172:175], v[118:121]
	v_mfma_f32_16x16x32_bf16 v[114:117], v[234:237], v[172:175], v[114:117]
	v_mfma_f32_16x16x32_bf16 v[102:105], v[208:211], v[180:183], v[102:105]
	v_mfma_f32_16x16x32_bf16 v[98:101], v[234:237], v[180:183], v[98:101]
	v_mfma_f32_16x16x32_bf16 v[86:89], v[208:211], v[188:191], v[86:89]
	v_mfma_f32_16x16x32_bf16 v[82:85], v[234:237], v[188:191], v[82:85]
	v_mfma_f32_16x16x32_bf16 v[70:73], v[208:211], v[200:203], v[70:73]
	v_mfma_f32_16x16x32_bf16 v[66:69], v[234:237], v[200:203], v[66:69]
	s_setprio 0
	s_barrier
; __device__ __forceinline__ float pre_get(const Pre& p, int ai, int m, int fr) { return __shfl(p.v[ai], m * 16 + fr); }
; __device__ __forceinline__ float rstd_pre(const float* ss, float v) { return ss ? rsqrtf(v * (1.0f / 2048.0f) + 1e-6f) : 1.0f; }
; #define PG8_MMA(ai, bj, At, Bt) do { __builtin_amdgcn_s_setprio(1); _Pragma("unroll") for (int m = 0; m < 4; ++m) _Pragma("unroll") for (int n = 0; n < 2; ++n) _Pragma("unroll") for (int k = 0; k < 2; ++k) \
;         acc[ai][bj][m][n] = __builtin_amdgcn_mfma_f32_16x16x32_bf16(Bt[n][k], At[m][k], acc[ai][bj][m][n], 0, 0, 0); __builtin_amdgcn_s_setprio(0); } while (0)
; #define PG8_WAIT_V(n) asm volatile("s_waitcnt vmcnt(" #n ")" ::: "memory")
; #define PG8_BAR __builtin_amdgcn_s_barrier()
; template <class Epi>
; __device__ __forceinline__ void gemm_phase(LAS unsigned char* lds, const Gemm g, const Sched& S, const Epi& E) {
;     ...
;             PG8_WAIT_V(6); PG8_BAR; PG8_MMA(1, 1, At, B1); PG8_BAR;
;         }
;     __device__ __forceinline__ void operator()(const Acc& acc, const Unit& u, int wr, int wc, int fr, int fq, const Pre& pre) const {
;         const int row0 = u.pm * 256 + wr * 64 + fr, col0 = u.pn * 128 + wc * 32 + 8 * fq;
;         float rsq[2][4];
; #pragma unroll
;         for (int ai = 0; ai < 2; ++ai)
; #pragma unroll
;             for (int m = 0; m < 4; ++m) rsq[ai][m] = rstd_pre(ss, pre_get(pre, ai, m, fr));
	s_add_i32 s69, s70, s51
	v_lshl_add_u64 v[192:193], v[192:193], 0, s[60:61]
	s_mov_b32 m0, s69
	s_nop 0
	global_load_lds_dwordx4 v[192:193], off
	v_lshl_add_u64 v[192:193], v[216:217], 0, s[60:61]
	s_add_i32 m0, s69, 0x2000
	s_nop 0
	global_load_lds_dwordx4 v[192:193], off
	s_mov_b32 m0, s75
	v_lshl_add_u64 v[192:193], v[222:223], 0, s[60:61]
	ds_read_b128 v[168:171], v151 offset:49152
	ds_read_b128 v[172:175], v151 offset:50176
	ds_read_b128 v[176:179], v151 offset:51200
	ds_read_b128 v[180:183], v151 offset:52224
	ds_read_b128 v[184:187], v151 offset:53248
	ds_read_b128 v[188:191], v151 offset:54272
	ds_read_b128 v[196:199], v151 offset:55296
	ds_read_b128 v[200:203], v151 offset:56320
	global_load_lds_dwordx4 v[192:193], off
	v_lshl_add_u64 v[192:193], v[224:225], 0, s[60:61]
	s_mov_b32 m0, s76
	s_nop 0
	global_load_lds_dwordx4 v[192:193], off
	s_add_i32 s68, s68, s51
	v_lshl_add_u64 v[192:193], v[226:227], 0, s[60:61]
	s_mov_b32 m0, s68
	s_nop 0
	global_load_lds_dwordx4 v[192:193], off
	v_lshl_add_u64 v[192:193], v[228:229], 0, s[60:61]
	s_add_i32 m0, s68, 0x2000
	s_nop 0
	global_load_lds_dwordx4 v[192:193], off
	s_waitcnt vmcnt(8)
	s_waitcnt lgkmcnt(0)
	v_mfma_f32_16x16x32_bf16 v[62:65], v[152:155], v[168:171], v[62:65]
	v_mfma_f32_16x16x32_bf16 v[58:61], v[160:163], v[168:171], v[58:61]
	v_mfma_f32_16x16x32_bf16 v[46:49], v[152:155], v[176:179], v[46:49]
	v_mfma_f32_16x16x32_bf16 v[42:45], v[160:163], v[176:179], v[42:45]
	v_mfma_f32_16x16x32_bf16 v[30:33], v[152:155], v[184:187], v[30:33]
	v_mfma_f32_16x16x32_bf16 v[26:29], v[160:163], v[184:187], v[26:29]
	v_mfma_f32_16x16x32_bf16 v[14:17], v[152:155], v[196:199], v[14:17]
	v_mfma_f32_16x16x32_bf16 v[10:13], v[160:163], v[196:199], v[10:13]
	s_barrier
	s_setprio 1
	v_mfma_f32_16x16x32_bf16 v[62:65], v[156:159], v[172:175], v[62:65]
	v_mfma_f32_16x16x32_bf16 v[58:61], v[164:167], v[172:175], v[58:61]
	v_mfma_f32_16x16x32_bf16 v[46:49], v[156:159], v[180:183], v[46:49]
	v_mfma_f32_16x16x32_bf16 v[42:45], v[164:167], v[180:183], v[42:45]
	v_mfma_f32_16x16x32_bf16 v[30:33], v[156:159], v[188:191], v[30:33]
	v_mfma_f32_16x16x32_bf16 v[26:29], v[164:167], v[188:191], v[26:29]
	v_mfma_f32_16x16x32_bf16 v[14:17], v[156:159], v[200:203], v[14:17]
	v_mfma_f32_16x16x32_bf16 v[10:13], v[164:167], v[200:203], v[10:13]
	v_mfma_f32_16x16x32_bf16 v[54:57], v[204:207], v[168:171], v[54:57]
	v_mfma_f32_16x16x32_bf16 v[50:53], v[212:215], v[168:171], v[50:53]
	v_mfma_f32_16x16x32_bf16 v[38:41], v[204:207], v[176:179], v[38:41]
	v_mfma_f32_16x16x32_bf16 v[34:37], v[212:215], v[176:179], v[34:37]
	v_mfma_f32_16x16x32_bf16 v[22:25], v[204:207], v[184:187], v[22:25]
	v_mfma_f32_16x16x32_bf16 v[18:21], v[212:215], v[184:187], v[18:21]
	v_mfma_f32_16x16x32_bf16 v[6:9], v[204:207], v[196:199], v[6:9]
	v_mfma_f32_16x16x32_bf16 v[2:5], v[212:215], v[196:199], v[2:5]
	v_mfma_f32_16x16x32_bf16 v[54:57], v[208:211], v[172:175], v[54:57]
	v_mfma_f32_16x16x32_bf16 v[50:53], v[234:237], v[172:175], v[50:53]
	v_mfma_f32_16x16x32_bf16 v[38:41], v[208:211], v[180:183], v[38:41]
	v_mfma_f32_16x16x32_bf16 v[34:37], v[234:237], v[180:183], v[34:37]
	v_mfma_f32_16x16x32_bf16 v[22:25], v[208:211], v[188:191], v[22:25]
	v_mfma_f32_16x16x32_bf16 v[18:21], v[234:237], v[188:191], v[18:21]
	v_mfma_f32_16x16x32_bf16 v[6:9], v[208:211], v[200:203], v[6:9]
	v_mfma_f32_16x16x32_bf16 v[2:5], v[234:237], v[200:203], v[2:5]
	s_setprio 0
	s_add_u32 s4, s4, 0x100
	s_addc_u32 s5, s5, 0
	s_add_u32 s84, s84, 0x100
	s_addc_u32 s85, s85, 0
	s_cmp_ge_u32 s86, s73
	s_mov_b32 s68, s86
	s_barrier
	s_cbranch_scc0 .LBB0_825
	v_and_or_b32 v144, v220, 64, v141
	v_lshlrev_b32_e32 v160, 2, v144
	ds_bpermute_b32 v155, v160, v142
	ds_bpermute_b32 v154, v160, v142 offset:64
	s_mov_b32 s4, 0x358637bd
	v_mov_b64_e32 v[156:157], s[4:5]
	s_mov_b32 s8, 0x3a000000
	v_lshl_add_u32 v153, s81, 8, v143
	s_waitcnt lgkmcnt(0)
	v_pk_fma_f32 v[158:159], v[154:155], s[8:9], v[156:157] op_sel_hi:[1,0,0]
	s_mov_b32 s81, s80
	v_mul_f32_e32 v144, 0x4b800000, v159
	v_cmp_gt_f32_e64 s[4:5], s97, v159
	v_cmp_gt_f32_e32 vcc, s97, v158
	s_mov_b64 s[68:69], s[66:67]
	v_cndmask_b32_e64 v144, v159, v144, s[4:5]
	v_rsq_f32_e32 v144, v144
	ds_bpermute_b32 v159, v160, v142 offset:128
	v_mul_f32_e32 v146, 0x45800000, v144
	v_cndmask_b32_e64 v144, v144, v146, s[4:5]
	v_cndmask_b32_e64 v154, v144, 1.0, s[34:35]
	v_mul_f32_e32 v144, 0x4b800000, v158
	v_cndmask_b32_e32 v144, v158, v144, vcc
	ds_bpermute_b32 v158, v160, v142 offset:192
	v_rsq_f32_e32 v144, v144
	s_waitcnt lgkmcnt(0)
	v_pk_fma_f32 v[158:159], v[158:159], s[8:9], v[156:157] op_sel_hi:[1,0,0]
	s_nop 0
	v_mul_f32_e32 v142, 0x4b800000, v159
	v_cmp_gt_f32_e64 s[4:5], s97, v159
	v_mul_f32_e32 v146, 0x45800000, v144
	v_cndmask_b32_e32 v144, v144, v146, vcc
	v_cndmask_b32_e64 v142, v159, v142, s[4:5]
	v_rsq_f32_e32 v142, v142
	v_cndmask_b32_e64 v152, v144, 1.0, s[34:35]
	v_cmp_gt_f32_e32 vcc, s97, v158
	ds_bpermute_b32 v159, v160, v140
	v_mul_f32_e32 v144, 0x45800000, v142
	v_cndmask_b32_e64 v142, v142, v144, s[4:5]
	v_cndmask_b32_e64 v150, v142, 1.0, s[34:35]
	v_mul_f32_e32 v142, 0x4b800000, v158
	v_cndmask_b32_e32 v142, v158, v142, vcc
	v_rsq_f32_e32 v142, v142
	ds_bpermute_b32 v158, v160, v140 offset:64
	v_pk_mul_f32 v[110:111], v[110:111], v[152:153] op_sel_hi:[1,0]
	v_pk_mul_f32 v[102:103], v[102:103], v[152:153] op_sel_hi:[1,0]
	v_mul_f32_e32 v144, 0x45800000, v142
	v_cndmask_b32_e32 v142, v142, v144, vcc
	s_waitcnt lgkmcnt(0)
; __device__ __forceinline__ float silu_f(float x) { return x * __builtin_amdgcn_rcpf(1.f + __builtin_amdgcn_exp2f(-LOG2E * x)); }
; __device__ __forceinline__ u32x4 pk8(const f32x4 a, const f32x4 b) { u32x4 w; w.x = pk2(a[0], a[1]); w.y = pk2(a[2], a[3]); w.z = pk2(b[0], b[1]); w.w = pk2(b[2], b[3]); return w; }
; __device__ __forceinline__ float pre_get(const Pre& p, int ai, int m, int fr) { return __shfl(p.v[ai], m * 16 + fr); }
; __device__ __forceinline__ float rstd_pre(const float* ss, float v) { return ss ? rsqrtf(v * (1.0f / 2048.0f) + 1e-6f) : 1.0f; }
;     __device__ __forceinline__ void operator()(const Acc& acc, const Unit& u, int wr, int wc, int fr, int fq, const Pre& pre) const {
;     ...
;         for (int ai = 0; ai < 2; ++ai)
; #pragma unroll
;             for (int m = 0; m < 4; ++m) rsq[ai][m] = rstd_pre(ss, pre_get(pre, ai, m, fr));
; #pragma unroll
;         for (int ai = 0; ai < 2; ++ai)
; #pragma unroll
;             for (int m = 0; m < 4; ++m) {
;                 f32x4 v0, v1; const float rs = rsq[ai][m];
; #pragma unroll
;                 for (int e = 0; e < 4; ++e) { v0[e] = silu_f(acc[ai][0][m][0][e] * rs) * (acc[ai][1][m][0][e] * rs); v1[e] = silu_f(acc[ai][0][m][1][e] * rs) * (acc[ai][1][m][1][e] * rs); }
;                 *(u32x4*)(O + (size_t)(row0 + ai * 128 + m * 16) * ldc + col0) = pk8(v0, v1);
	v_pk_fma_f32 v[158:159], v[158:159], s[8:9], v[156:157] op_sel_hi:[1,0,0]
	v_cndmask_b32_e64 v148, v142, 1.0, s[34:35]
	v_mul_f32_e32 v142, 0x4b800000, v159
	v_cmp_gt_f32_e64 s[4:5], s97, v159
	v_cmp_gt_f32_e32 vcc, s97, v158
	v_pk_mul_f32 v[106:107], v[106:107], v[152:153] op_sel_hi:[1,0]
	v_cndmask_b32_e64 v142, v159, v142, s[4:5]
	v_rsq_f32_e32 v142, v142
	ds_bpermute_b32 v159, v160, v140 offset:128
	v_pk_mul_f32 v[98:99], v[98:99], v[152:153] op_sel_hi:[1,0]
	v_pk_mul_f32 v[104:105], v[104:105], v[152:153] op_sel_hi:[1,0]
	v_mul_f32_e32 v144, 0x45800000, v142
	v_cndmask_b32_e64 v142, v142, v144, s[4:5]
	v_cndmask_b32_e64 v146, v142, 1.0, s[34:35]
	v_mul_f32_e32 v142, 0x4b800000, v158
	v_cndmask_b32_e32 v142, v158, v142, vcc
	ds_bpermute_b32 v158, v160, v140 offset:192
	v_rsq_f32_e32 v142, v142
	v_pk_mul_f32 v[100:101], v[100:101], v[152:153] op_sel_hi:[1,0]
	v_pk_mul_f32 v[94:95], v[94:95], v[150:151] op_sel_hi:[1,0]
	v_pk_mul_f32 v[86:87], v[86:87], v[150:151] op_sel_hi:[1,0]
	s_waitcnt lgkmcnt(0)
	v_pk_fma_f32 v[156:157], v[158:159], s[8:9], v[156:157] op_sel_hi:[1,0,0]
	v_mul_f32_e32 v144, 0x45800000, v142
	v_mul_f32_e32 v140, 0x4b800000, v157
	v_cmp_gt_f32_e64 s[4:5], s97, v157
	v_cndmask_b32_e32 v142, v142, v144, vcc
	v_cndmask_b32_e64 v144, v142, 1.0, s[34:35]
	v_cndmask_b32_e64 v140, v157, v140, s[4:5]
	v_rsq_f32_e32 v140, v140
	v_cmp_gt_f32_e32 vcc, s97, v156
	v_pk_mul_f32 v[90:91], v[90:91], v[150:151] op_sel_hi:[1,0]
	v_pk_mul_f32 v[82:83], v[82:83], v[150:151] op_sel_hi:[1,0]
	v_mul_f32_e32 v142, 0x45800000, v140
	v_cndmask_b32_e64 v140, v140, v142, s[4:5]
	v_cndmask_b32_e64 v142, v140, 1.0, s[34:35]
	v_mul_f32_e32 v140, 0x4b800000, v156
	v_cndmask_b32_e32 v140, v156, v140, vcc
	v_rsq_f32_e32 v140, v140
	v_lshl_or_b32 v156, s55, 7, v149
	v_ashrrev_i32_e32 v157, 31, v156
	v_pk_mul_f32 v[88:89], v[88:89], v[150:151] op_sel_hi:[1,0]
	v_mul_f32_e32 v155, 0x45800000, v140
	v_pk_mul_f32 v[126:127], v[126:127], v[154:155] op_sel_hi:[1,0]
	v_cndmask_b32_e32 v140, v140, v155, vcc
	v_mul_f32_e32 v155, 0xbfb8aa3b, v126
	v_exp_f32_e32 v155, v155
	v_pk_mul_f32 v[84:85], v[84:85], v[150:151] op_sel_hi:[1,0]
	v_pk_mul_f32 v[78:79], v[78:79], v[148:149] op_sel_hi:[1,0]
	v_pk_mul_f32 v[70:71], v[70:71], v[148:149] op_sel_hi:[1,0]
	v_add_f32_e32 v155, 1.0, v155
	v_rcp_f32_e32 v158, v155
	v_mul_f32_e32 v155, 0xbfb8aa3b, v127
	v_exp_f32_e32 v155, v155
	v_pk_mul_f32 v[74:75], v[74:75], v[148:149] op_sel_hi:[1,0]
	v_pk_mul_f32 v[66:67], v[66:67], v[148:149] op_sel_hi:[1,0]
	v_pk_mul_f32 v[72:73], v[72:73], v[148:149] op_sel_hi:[1,0]
	v_add_f32_e32 v155, 1.0, v155
	v_rcp_f32_e32 v159, v155
	v_pk_mul_f32 v[118:119], v[118:119], v[154:155] op_sel_hi:[1,0]
	v_pk_mul_f32 v[122:123], v[122:123], v[154:155] op_sel_hi:[1,0]
	v_pk_mul_f32 v[114:115], v[114:115], v[154:155] op_sel_hi:[1,0]
	v_pk_mul_f32 v[126:127], v[126:127], v[158:159]
	v_pk_mul_f32 v[120:121], v[120:121], v[154:155] op_sel_hi:[1,0]
	v_pk_mul_f32 v[118:119], v[118:119], v[126:127]
	v_mul_f32_e32 v126, 0xbfb8aa3b, v122
	v_mul_f32_e32 v127, 0xbfb8aa3b, v123
	v_exp_f32_e32 v126, v126
	v_exp_f32_e32 v127, v127
	v_pk_mul_f32 v[116:117], v[116:117], v[154:155] op_sel_hi:[1,0]
	v_cvt_pk_bf16_f32 v118, v118, v119
	v_add_f32_e32 v126, 1.0, v126
	v_add_f32_e32 v127, 1.0, v127
	v_rcp_f32_e32 v126, v126
	v_rcp_f32_e32 v127, v127
	v_pk_mul_f32 v[68:69], v[68:69], v[148:149] op_sel_hi:[1,0]
	v_pk_mul_f32 v[62:63], v[62:63], v[146:147] op_sel_hi:[1,0]
	v_pk_mul_f32 v[54:55], v[54:55], v[146:147] op_sel_hi:[1,0]
	v_pk_mul_f32 v[122:123], v[122:123], v[126:127]
	v_pk_mul_f32 v[58:59], v[58:59], v[146:147] op_sel_hi:[1,0]
	v_pk_mul_f32 v[114:115], v[114:115], v[122:123]
	v_pk_mul_f32 v[122:123], v[128:129], v[154:155] op_sel_hi:[1,0]
	v_pk_mul_f32 v[50:51], v[50:51], v[146:147] op_sel_hi:[1,0]
	v_mul_f32_e32 v126, 0xbfb8aa3b, v122
	v_mul_f32_e32 v127, 0xbfb8aa3b, v123
	v_exp_f32_e32 v126, v126
	v_exp_f32_e32 v127, v127
	v_pk_mul_f32 v[56:57], v[56:57], v[146:147] op_sel_hi:[1,0]
	v_pk_mul_f32 v[52:53], v[52:53], v[146:147] op_sel_hi:[1,0]
	v_add_f32_e32 v126, 1.0, v126
	v_add_f32_e32 v127, 1.0, v127
	v_rcp_f32_e32 v126, v126
	v_rcp_f32_e32 v127, v127
	v_pk_mul_f32 v[46:47], v[46:47], v[144:145] op_sel_hi:[1,0]
	v_pk_mul_f32 v[38:39], v[38:39], v[144:145] op_sel_hi:[1,0]
	v_pk_mul_f32 v[42:43], v[42:43], v[144:145] op_sel_hi:[1,0]
	v_pk_mul_f32 v[122:123], v[122:123], v[126:127]
	v_pk_mul_f32 v[34:35], v[34:35], v[144:145] op_sel_hi:[1,0]
	v_pk_mul_f32 v[120:121], v[120:121], v[122:123]
	v_pk_mul_f32 v[122:123], v[124:125], v[154:155] op_sel_hi:[1,0]
	v_cvt_pk_bf16_f32 v119, v120, v121
	v_mul_f32_e32 v124, 0xbfb8aa3b, v122
	v_mul_f32_e32 v125, 0xbfb8aa3b, v123
	v_exp_f32_e32 v124, v124
	v_exp_f32_e32 v125, v125
	v_cvt_pk_bf16_f32 v120, v114, v115
	v_ashrrev_i32_e32 v114, 31, v153
	v_add_f32_e32 v124, 1.0, v124
	v_add_f32_e32 v125, 1.0, v125
	v_rcp_f32_e32 v124, v124
	v_rcp_f32_e32 v125, v125
	v_pk_mul_f32 v[40:41], v[40:41], v[144:145] op_sel_hi:[1,0]
	v_pk_mul_f32 v[36:37], v[36:37], v[144:145] op_sel_hi:[1,0]
	v_pk_mul_f32 v[30:31], v[30:31], v[142:143] op_sel_hi:[1,0]
	v_pk_mul_f32 v[122:123], v[122:123], v[124:125]
	v_pk_mul_f32 v[22:23], v[22:23], v[142:143] op_sel_hi:[1,0]
	v_pk_mul_f32 v[116:117], v[116:117], v[122:123]
	v_pk_mul_f32 v[26:27], v[26:27], v[142:143] op_sel_hi:[1,0]
	v_cvt_pk_bf16_f32 v121, v116, v117
	v_mul_lo_u32 v116, s12, v114
	v_mul_lo_u32 v117, s13, v153
	v_mad_u64_u32 v[114:115], s[4:5], s12, v153, 0
	v_add3_u32 v115, v115, v116, v117
	v_mul_f32_e32 v117, 0xbfb8aa3b, v110
	v_exp_f32_e32 v117, v117
	v_lshl_add_u64 v[122:123], v[114:115], 1, s[62:63]
	v_lshlrev_b64 v[114:115], 1, v[156:157]
; __device__ __forceinline__ float silu_f(float x) { return x * __builtin_amdgcn_rcpf(1.f + __builtin_amdgcn_exp2f(-LOG2E * x)); }
; __device__ __forceinline__ u32x4 pk8(const f32x4 a, const f32x4 b) { u32x4 w; w.x = pk2(a[0], a[1]); w.y = pk2(a[2], a[3]); w.z = pk2(b[0], b[1]); w.w = pk2(b[2], b[3]); return w; }
;     __device__ __forceinline__ void operator()(const Acc& acc, const Unit& u, int wr, int wc, int fr, int fq, const Pre& pre) const {
;     ...
;             for (int m = 0; m < 4; ++m) {
;                 f32x4 v0, v1; const float rs = rsq[ai][m];
; #pragma unroll
;                 for (int e = 0; e < 4; ++e) { v0[e] = silu_f(acc[ai][0][m][0][e] * rs) * (acc[ai][1][m][0][e] * rs); v1[e] = silu_f(acc[ai][0][m][1][e] * rs) * (acc[ai][1][m][1][e] * rs); }
;                 *(u32x4*)(O + (size_t)(row0 + ai * 128 + m * 16) * ldc + col0) = pk8(v0, v1);
	v_lshl_add_u64 v[122:123], v[122:123], 0, v[114:115]
	v_add_f32_e32 v117, 1.0, v117
	global_store_dwordx4 v[122:123], v[118:121], off
	v_pk_mul_f32 v[18:19], v[18:19], v[142:143] op_sel_hi:[1,0]
	v_pk_mul_f32 v[24:25], v[24:25], v[142:143] op_sel_hi:[1,0]
	v_rcp_f32_e32 v118, v117
	v_mul_f32_e32 v117, 0xbfb8aa3b, v111
	v_exp_f32_e32 v117, v117
	v_pk_mul_f32 v[20:21], v[20:21], v[142:143] op_sel_hi:[1,0]
	v_cndmask_b32_e64 v140, v140, 1.0, s[34:35]
	v_pk_mul_f32 v[14:15], v[14:15], v[140:141] op_sel_hi:[1,0]
	v_add_f32_e32 v117, 1.0, v117
	v_rcp_f32_e32 v119, v117
	v_pk_mul_f32 v[6:7], v[6:7], v[140:141] op_sel_hi:[1,0]
	v_pk_mul_f32 v[10:11], v[10:11], v[140:141] op_sel_hi:[1,0]
	v_pk_mul_f32 v[2:3], v[2:3], v[140:141] op_sel_hi:[1,0]
	v_pk_mul_f32 v[110:111], v[110:111], v[118:119]
	v_pk_mul_f32 v[8:9], v[8:9], v[140:141] op_sel_hi:[1,0]
	v_pk_mul_f32 v[102:103], v[102:103], v[110:111]
	v_mul_f32_e32 v110, 0xbfb8aa3b, v106
	v_mul_f32_e32 v111, 0xbfb8aa3b, v107
	v_exp_f32_e32 v110, v110
	v_exp_f32_e32 v111, v111
	v_pk_mul_f32 v[4:5], v[4:5], v[140:141] op_sel_hi:[1,0]
	s_and_b64 vcc, exec, s[0:1]
	v_add_f32_e32 v110, 1.0, v110
	v_add_f32_e32 v111, 1.0, v111
	v_rcp_f32_e32 v110, v110
	v_rcp_f32_e32 v111, v111
	s_mov_b32 s55, s79
	v_pk_mul_f32 v[106:107], v[106:107], v[110:111]
	s_nop 0
	v_pk_mul_f32 v[106:107], v[98:99], v[106:107]
	v_pk_mul_f32 v[98:99], v[112:113], v[152:153] op_sel_hi:[1,0]
	s_nop 0
	v_mul_f32_e32 v110, 0xbfb8aa3b, v98
	v_mul_f32_e32 v111, 0xbfb8aa3b, v99
	v_exp_f32_e32 v110, v110
	v_exp_f32_e32 v111, v111
	v_add_f32_e32 v110, 1.0, v110
	v_add_f32_e32 v111, 1.0, v111
	v_rcp_f32_e32 v110, v110
	v_rcp_f32_e32 v111, v111
	s_nop 0
	v_pk_mul_f32 v[98:99], v[98:99], v[110:111]
	s_nop 0
	v_pk_mul_f32 v[104:105], v[104:105], v[98:99]
	v_pk_mul_f32 v[98:99], v[108:109], v[152:153] op_sel_hi:[1,0]
	s_nop 0
	v_mul_f32_e32 v108, 0xbfb8aa3b, v98
	v_mul_f32_e32 v109, 0xbfb8aa3b, v99
	v_exp_f32_e32 v108, v108
	v_exp_f32_e32 v109, v109
	v_add_f32_e32 v108, 1.0, v108
	v_add_f32_e32 v109, 1.0, v109
	v_rcp_f32_e32 v108, v108
	v_rcp_f32_e32 v109, v109
	s_nop 0
	v_pk_mul_f32 v[98:99], v[98:99], v[108:109]
	s_nop 0
	v_pk_mul_f32 v[108:109], v[100:101], v[98:99]
	v_cvt_pk_bf16_f32 v98, v102, v103
	v_or_b32_e32 v102, 16, v153
	v_cvt_pk_bf16_f32 v99, v104, v105
	v_mul_lo_u32 v104, s13, v102
	v_mad_u64_u32 v[102:103], s[4:5], s12, v102, 0
	v_add3_u32 v103, v103, v116, v104
	v_lshl_add_u64 v[102:103], v[102:103], 1, s[62:63]
	v_cvt_pk_bf16_f32 v100, v106, v107
	v_cvt_pk_bf16_f32 v101, v108, v109
	v_lshl_add_u64 v[102:103], v[102:103], 0, v[114:115]
	global_store_dwordx4 v[102:103], v[98:101], off
	s_nop 1
	v_mul_f32_e32 v98, 0xbfb8aa3b, v94
	v_mul_f32_e32 v99, 0xbfb8aa3b, v95
	v_exp_f32_e32 v98, v98
	v_exp_f32_e32 v99, v99
	v_add_f32_e32 v98, 1.0, v98
	v_add_f32_e32 v99, 1.0, v99
	v_rcp_f32_e32 v98, v98
	v_rcp_f32_e32 v99, v99
	s_nop 0
	v_pk_mul_f32 v[94:95], v[94:95], v[98:99]
	s_nop 0
	v_pk_mul_f32 v[86:87], v[86:87], v[94:95]
	v_mul_f32_e32 v94, 0xbfb8aa3b, v90
	v_mul_f32_e32 v95, 0xbfb8aa3b, v91
	v_exp_f32_e32 v94, v94
	v_exp_f32_e32 v95, v95
	v_add_f32_e32 v94, 1.0, v94
	v_add_f32_e32 v95, 1.0, v95
	v_rcp_f32_e32 v94, v94
	v_rcp_f32_e32 v95, v95
	s_nop 0
	v_pk_mul_f32 v[90:91], v[90:91], v[94:95]
	s_nop 0
	v_pk_mul_f32 v[90:91], v[82:83], v[90:91]
	v_pk_mul_f32 v[82:83], v[96:97], v[150:151] op_sel_hi:[1,0]
	s_nop 0
	v_mul_f32_e32 v94, 0xbfb8aa3b, v82
	v_mul_f32_e32 v95, 0xbfb8aa3b, v83
	v_exp_f32_e32 v94, v94
	v_exp_f32_e32 v95, v95
	v_add_f32_e32 v94, 1.0, v94
	v_add_f32_e32 v95, 1.0, v95
	v_rcp_f32_e32 v94, v94
	v_rcp_f32_e32 v95, v95
	s_nop 0
	v_pk_mul_f32 v[82:83], v[82:83], v[94:95]
	s_nop 0
	v_pk_mul_f32 v[88:89], v[88:89], v[82:83]
	v_pk_mul_f32 v[82:83], v[92:93], v[150:151] op_sel_hi:[1,0]
	s_nop 0
	v_mul_f32_e32 v92, 0xbfb8aa3b, v82
	v_mul_f32_e32 v93, 0xbfb8aa3b, v83
	v_exp_f32_e32 v92, v92
	v_exp_f32_e32 v93, v93
	v_add_f32_e32 v92, 1.0, v92
	v_add_f32_e32 v93, 1.0, v93
	v_rcp_f32_e32 v92, v92
	v_rcp_f32_e32 v93, v93
	s_nop 0
	v_pk_mul_f32 v[82:83], v[82:83], v[92:93]
	s_nop 0
	v_pk_mul_f32 v[92:93], v[84:85], v[82:83]
	v_cvt_pk_bf16_f32 v82, v86, v87
	v_or_b32_e32 v86, 32, v153
	v_cvt_pk_bf16_f32 v83, v88, v89
	v_mul_lo_u32 v88, s13, v86
	v_mad_u64_u32 v[86:87], s[4:5], s12, v86, 0
	v_add3_u32 v87, v87, v116, v88
	v_lshl_add_u64 v[86:87], v[86:87], 1, s[62:63]
	v_cvt_pk_bf16_f32 v84, v90, v91
	v_cvt_pk_bf16_f32 v85, v92, v93
	v_lshl_add_u64 v[86:87], v[86:87], 0, v[114:115]
	global_store_dwordx4 v[86:87], v[82:85], off
	s_nop 1
	v_mul_f32_e32 v82, 0xbfb8aa3b, v78
	v_mul_f32_e32 v83, 0xbfb8aa3b, v79
	v_exp_f32_e32 v82, v82
	v_exp_f32_e32 v83, v83
	v_add_f32_e32 v82, 1.0, v82
	v_add_f32_e32 v83, 1.0, v83
	v_rcp_f32_e32 v82, v82
	v_rcp_f32_e32 v83, v83
	s_nop 0
	v_pk_mul_f32 v[78:79], v[78:79], v[82:83]
	s_nop 0
	v_pk_mul_f32 v[70:71], v[70:71], v[78:79]
	v_mul_f32_e32 v78, 0xbfb8aa3b, v74
	v_mul_f32_e32 v79, 0xbfb8aa3b, v75
	v_exp_f32_e32 v78, v78
	v_exp_f32_e32 v79, v79
	v_add_f32_e32 v78, 1.0, v78
	v_add_f32_e32 v79, 1.0, v79
	v_rcp_f32_e32 v78, v78
	v_rcp_f32_e32 v79, v79
	s_nop 0
	v_pk_mul_f32 v[74:75], v[74:75], v[78:79]
	s_nop 0
	v_pk_mul_f32 v[74:75], v[66:67], v[74:75]
	v_pk_mul_f32 v[66:67], v[80:81], v[148:149] op_sel_hi:[1,0]
	s_nop 0
	v_mul_f32_e32 v78, 0xbfb8aa3b, v66
	v_mul_f32_e32 v79, 0xbfb8aa3b, v67
	v_exp_f32_e32 v78, v78
	v_exp_f32_e32 v79, v79
	v_add_f32_e32 v78, 1.0, v78
	v_add_f32_e32 v79, 1.0, v79
	v_rcp_f32_e32 v78, v78
	v_rcp_f32_e32 v79, v79
	s_nop 0
	v_pk_mul_f32 v[66:67], v[66:67], v[78:79]
	s_nop 0
	v_pk_mul_f32 v[72:73], v[72:73], v[66:67]
	v_pk_mul_f32 v[66:67], v[76:77], v[148:149] op_sel_hi:[1,0]
; __device__ __forceinline__ float silu_f(float x) { return x * __builtin_amdgcn_rcpf(1.f + __builtin_amdgcn_exp2f(-LOG2E * x)); }
; __device__ __forceinline__ u32x4 pk8(const f32x4 a, const f32x4 b) { u32x4 w; w.x = pk2(a[0], a[1]); w.y = pk2(a[2], a[3]); w.z = pk2(b[0], b[1]); w.w = pk2(b[2], b[3]); return w; }
;     __device__ __forceinline__ void operator()(const Acc& acc, const Unit& u, int wr, int wc, int fr, int fq, const Pre& pre) const {
;     ...
;             for (int m = 0; m < 4; ++m) {
;                 f32x4 v0, v1; const float rs = rsq[ai][m];
; #pragma unroll
;                 for (int e = 0; e < 4; ++e) { v0[e] = silu_f(acc[ai][0][m][0][e] * rs) * (acc[ai][1][m][0][e] * rs); v1[e] = silu_f(acc[ai][0][m][1][e] * rs) * (acc[ai][1][m][1][e] * rs); }
;                 *(u32x4*)(O + (size_t)(row0 + ai * 128 + m * 16) * ldc + col0) = pk8(v0, v1);
	s_nop 0
	v_mul_f32_e32 v76, 0xbfb8aa3b, v66
	v_mul_f32_e32 v77, 0xbfb8aa3b, v67
	v_exp_f32_e32 v76, v76
	v_exp_f32_e32 v77, v77
	v_add_f32_e32 v76, 1.0, v76
	v_add_f32_e32 v77, 1.0, v77
	v_rcp_f32_e32 v76, v76
	v_rcp_f32_e32 v77, v77
	s_nop 0
	v_pk_mul_f32 v[66:67], v[66:67], v[76:77]
	s_nop 0
	v_pk_mul_f32 v[76:77], v[68:69], v[66:67]
	v_cvt_pk_bf16_f32 v66, v70, v71
	v_or_b32_e32 v70, 48, v153
	v_cvt_pk_bf16_f32 v67, v72, v73
	v_mul_lo_u32 v72, s13, v70
	v_mad_u64_u32 v[70:71], s[4:5], s12, v70, 0
	v_add3_u32 v71, v71, v116, v72
	v_lshl_add_u64 v[70:71], v[70:71], 1, s[62:63]
	v_cvt_pk_bf16_f32 v68, v74, v75
	v_cvt_pk_bf16_f32 v69, v76, v77
	v_lshl_add_u64 v[70:71], v[70:71], 0, v[114:115]
	global_store_dwordx4 v[70:71], v[66:69], off
	s_nop 1
	v_mul_f32_e32 v66, 0xbfb8aa3b, v62
	v_mul_f32_e32 v67, 0xbfb8aa3b, v63
	v_exp_f32_e32 v66, v66
	v_exp_f32_e32 v67, v67
	v_add_u32_e32 v68, 0x80, v153
	v_add_f32_e32 v66, 1.0, v66
	v_add_f32_e32 v67, 1.0, v67
	v_rcp_f32_e32 v66, v66
	v_rcp_f32_e32 v67, v67
	s_nop 0
	v_pk_mul_f32 v[62:63], v[62:63], v[66:67]
	s_nop 0
	v_pk_mul_f32 v[54:55], v[54:55], v[62:63]
	v_mul_f32_e32 v62, 0xbfb8aa3b, v58
	v_mul_f32_e32 v63, 0xbfb8aa3b, v59
	v_exp_f32_e32 v62, v62
	v_exp_f32_e32 v63, v63
	v_add_f32_e32 v62, 1.0, v62
	v_add_f32_e32 v63, 1.0, v63
	v_rcp_f32_e32 v62, v62
	v_rcp_f32_e32 v63, v63
	s_nop 0
	v_pk_mul_f32 v[58:59], v[58:59], v[62:63]
	s_nop 0
	v_pk_mul_f32 v[58:59], v[50:51], v[58:59]
	v_pk_mul_f32 v[50:51], v[64:65], v[146:147] op_sel_hi:[1,0]
	s_nop 0
	v_mul_f32_e32 v62, 0xbfb8aa3b, v50
	v_mul_f32_e32 v63, 0xbfb8aa3b, v51
	v_exp_f32_e32 v62, v62
	v_exp_f32_e32 v63, v63
	v_add_f32_e32 v62, 1.0, v62
	v_add_f32_e32 v63, 1.0, v63
	v_rcp_f32_e32 v62, v62
	v_rcp_f32_e32 v63, v63
	s_nop 0
	v_pk_mul_f32 v[50:51], v[50:51], v[62:63]
	s_nop 0
	v_pk_mul_f32 v[56:57], v[56:57], v[50:51]
	v_pk_mul_f32 v[50:51], v[60:61], v[146:147] op_sel_hi:[1,0]
	s_nop 0
	v_mul_f32_e32 v60, 0xbfb8aa3b, v50
	v_mul_f32_e32 v61, 0xbfb8aa3b, v51
	v_exp_f32_e32 v60, v60
	v_exp_f32_e32 v61, v61
	v_add_f32_e32 v60, 1.0, v60
	v_add_f32_e32 v61, 1.0, v61
	v_rcp_f32_e32 v60, v60
	v_rcp_f32_e32 v61, v61
	s_nop 0
	v_pk_mul_f32 v[50:51], v[50:51], v[60:61]
	s_nop 0
	v_pk_mul_f32 v[60:61], v[52:53], v[50:51]
	v_cvt_pk_bf16_f32 v50, v54, v55
	v_ashrrev_i32_e32 v54, 31, v68
	v_cvt_pk_bf16_f32 v51, v56, v57
	v_mul_lo_u32 v56, s12, v54
	v_mul_lo_u32 v57, s13, v68
	v_mad_u64_u32 v[54:55], s[4:5], s12, v68, 0
	v_add3_u32 v55, v55, v56, v57
	v_lshl_add_u64 v[54:55], v[54:55], 1, s[62:63]
	v_cvt_pk_bf16_f32 v52, v58, v59
	v_cvt_pk_bf16_f32 v53, v60, v61
	v_lshl_add_u64 v[54:55], v[54:55], 0, v[114:115]
	global_store_dwordx4 v[54:55], v[50:53], off
	s_nop 1
	v_mul_f32_e32 v50, 0xbfb8aa3b, v46
	v_mul_f32_e32 v51, 0xbfb8aa3b, v47
	v_exp_f32_e32 v50, v50
	v_exp_f32_e32 v51, v51
	v_add_f32_e32 v50, 1.0, v50
	v_add_f32_e32 v51, 1.0, v51
	v_rcp_f32_e32 v50, v50
	v_rcp_f32_e32 v51, v51
	s_nop 0
	v_pk_mul_f32 v[46:47], v[46:47], v[50:51]
	s_nop 0
	v_pk_mul_f32 v[38:39], v[38:39], v[46:47]
	v_mul_f32_e32 v46, 0xbfb8aa3b, v42
	v_mul_f32_e32 v47, 0xbfb8aa3b, v43
	v_exp_f32_e32 v46, v46
	v_exp_f32_e32 v47, v47
	v_add_f32_e32 v46, 1.0, v46
	v_add_f32_e32 v47, 1.0, v47
	v_rcp_f32_e32 v46, v46
	v_rcp_f32_e32 v47, v47
	s_nop 0
	v_pk_mul_f32 v[42:43], v[42:43], v[46:47]
	s_nop 0
	v_pk_mul_f32 v[42:43], v[34:35], v[42:43]
	v_pk_mul_f32 v[34:35], v[48:49], v[144:145] op_sel_hi:[1,0]
	s_nop 0
	v_mul_f32_e32 v46, 0xbfb8aa3b, v34
	v_mul_f32_e32 v47, 0xbfb8aa3b, v35
	v_exp_f32_e32 v46, v46
	v_exp_f32_e32 v47, v47
	v_add_f32_e32 v46, 1.0, v46
	v_add_f32_e32 v47, 1.0, v47
	v_rcp_f32_e32 v46, v46
	v_rcp_f32_e32 v47, v47
	s_nop 0
	v_pk_mul_f32 v[34:35], v[34:35], v[46:47]
	s_nop 0
	v_pk_mul_f32 v[40:41], v[40:41], v[34:35]
	v_pk_mul_f32 v[34:35], v[44:45], v[144:145] op_sel_hi:[1,0]
	s_nop 0
	v_mul_f32_e32 v44, 0xbfb8aa3b, v34
	v_mul_f32_e32 v45, 0xbfb8aa3b, v35
	v_exp_f32_e32 v44, v44
	v_exp_f32_e32 v45, v45
	v_add_f32_e32 v44, 1.0, v44
	v_add_f32_e32 v45, 1.0, v45
	v_rcp_f32_e32 v44, v44
	v_rcp_f32_e32 v45, v45
	s_nop 0
	v_pk_mul_f32 v[34:35], v[34:35], v[44:45]
	s_nop 0
	v_pk_mul_f32 v[44:45], v[36:37], v[34:35]
	v_cvt_pk_bf16_f32 v34, v38, v39
	v_add_u32_e32 v38, 0x90, v153
	v_ashrrev_i32_e32 v39, 31, v38
; __device__ __forceinline__ float silu_f(float x) { return x * __builtin_amdgcn_rcpf(1.f + __builtin_amdgcn_exp2f(-LOG2E * x)); }
; __device__ __forceinline__ u32x4 pk8(const f32x4 a, const f32x4 b) { u32x4 w; w.x = pk2(a[0], a[1]); w.y = pk2(a[2], a[3]); w.z = pk2(b[0], b[1]); w.w = pk2(b[2], b[3]); return w; }
; template <class Epi>
; __device__ __forceinline__ void gemm_phase(LAS unsigned char* lds, const Gemm g, const Sched& S, const Epi& E) {
;     ...
;         if (!has_next) break;
;     __device__ __forceinline__ void operator()(const Acc& acc, const Unit& u, int wr, int wc, int fr, int fq, const Pre& pre) const {
;     ...
;             for (int m = 0; m < 4; ++m) {
;                 f32x4 v0, v1; const float rs = rsq[ai][m];
; #pragma unroll
;                 for (int e = 0; e < 4; ++e) { v0[e] = silu_f(acc[ai][0][m][0][e] * rs) * (acc[ai][1][m][0][e] * rs); v1[e] = silu_f(acc[ai][0][m][1][e] * rs) * (acc[ai][1][m][1][e] * rs); }
;                 *(u32x4*)(O + (size_t)(row0 + ai * 128 + m * 16) * ldc + col0) = pk8(v0, v1);
	v_cvt_pk_bf16_f32 v35, v40, v41
	v_mul_lo_u32 v40, s12, v39
	v_mul_lo_u32 v41, s13, v38
	v_mad_u64_u32 v[38:39], s[4:5], s12, v38, 0
	v_add3_u32 v39, v39, v40, v41
	v_lshl_add_u64 v[38:39], v[38:39], 1, s[62:63]
	v_cvt_pk_bf16_f32 v36, v42, v43
	v_cvt_pk_bf16_f32 v37, v44, v45
	v_lshl_add_u64 v[38:39], v[38:39], 0, v[114:115]
	global_store_dwordx4 v[38:39], v[34:37], off
	s_nop 1
	v_mul_f32_e32 v34, 0xbfb8aa3b, v30
	v_mul_f32_e32 v35, 0xbfb8aa3b, v31
	v_exp_f32_e32 v34, v34
	v_exp_f32_e32 v35, v35
	v_add_f32_e32 v34, 1.0, v34
	v_add_f32_e32 v35, 1.0, v35
	v_rcp_f32_e32 v34, v34
	v_rcp_f32_e32 v35, v35
	s_nop 0
	v_pk_mul_f32 v[30:31], v[30:31], v[34:35]
	s_nop 0
	v_pk_mul_f32 v[22:23], v[22:23], v[30:31]
	v_mul_f32_e32 v30, 0xbfb8aa3b, v26
	v_mul_f32_e32 v31, 0xbfb8aa3b, v27
	v_exp_f32_e32 v30, v30
	v_exp_f32_e32 v31, v31
	v_add_f32_e32 v30, 1.0, v30
	v_add_f32_e32 v31, 1.0, v31
	v_rcp_f32_e32 v30, v30
	v_rcp_f32_e32 v31, v31
	s_nop 0
	v_pk_mul_f32 v[26:27], v[26:27], v[30:31]
	s_nop 0
	v_pk_mul_f32 v[26:27], v[18:19], v[26:27]
	v_pk_mul_f32 v[18:19], v[32:33], v[142:143] op_sel_hi:[1,0]
	s_nop 0
	v_mul_f32_e32 v30, 0xbfb8aa3b, v18
	v_mul_f32_e32 v31, 0xbfb8aa3b, v19
	v_exp_f32_e32 v30, v30
	v_exp_f32_e32 v31, v31
	v_add_f32_e32 v30, 1.0, v30
	v_add_f32_e32 v31, 1.0, v31
	v_rcp_f32_e32 v30, v30
	v_rcp_f32_e32 v31, v31
	s_nop 0
	v_pk_mul_f32 v[18:19], v[18:19], v[30:31]
	s_nop 0
	v_pk_mul_f32 v[24:25], v[24:25], v[18:19]
	v_pk_mul_f32 v[18:19], v[28:29], v[142:143] op_sel_hi:[1,0]
	s_nop 0
	v_mul_f32_e32 v28, 0xbfb8aa3b, v18
	v_mul_f32_e32 v29, 0xbfb8aa3b, v19
	v_exp_f32_e32 v28, v28
	v_exp_f32_e32 v29, v29
	v_add_f32_e32 v28, 1.0, v28
	v_add_f32_e32 v29, 1.0, v29
	v_rcp_f32_e32 v28, v28
	v_rcp_f32_e32 v29, v29
	s_nop 0
	v_pk_mul_f32 v[18:19], v[18:19], v[28:29]
	s_nop 0
	v_pk_mul_f32 v[28:29], v[20:21], v[18:19]
	v_cvt_pk_bf16_f32 v18, v22, v23
	v_add_u32_e32 v22, 0xa0, v153
	v_ashrrev_i32_e32 v23, 31, v22
	v_cvt_pk_bf16_f32 v19, v24, v25
	v_mul_lo_u32 v24, s12, v23
	v_mul_lo_u32 v25, s13, v22
	v_mad_u64_u32 v[22:23], s[4:5], s12, v22, 0
	v_add3_u32 v23, v23, v24, v25
	v_lshl_add_u64 v[22:23], v[22:23], 1, s[62:63]
	v_cvt_pk_bf16_f32 v20, v26, v27
	v_cvt_pk_bf16_f32 v21, v28, v29
	v_lshl_add_u64 v[22:23], v[22:23], 0, v[114:115]
	global_store_dwordx4 v[22:23], v[18:21], off
	s_nop 1
	v_mul_f32_e32 v18, 0xbfb8aa3b, v14
	v_mul_f32_e32 v19, 0xbfb8aa3b, v15
	v_exp_f32_e32 v18, v18
	v_exp_f32_e32 v19, v19
	v_add_f32_e32 v18, 1.0, v18
	v_add_f32_e32 v19, 1.0, v19
	v_rcp_f32_e32 v18, v18
	v_rcp_f32_e32 v19, v19
	s_nop 0
	v_pk_mul_f32 v[14:15], v[14:15], v[18:19]
	s_nop 0
	v_pk_mul_f32 v[6:7], v[6:7], v[14:15]
	v_mul_f32_e32 v14, 0xbfb8aa3b, v10
	v_mul_f32_e32 v15, 0xbfb8aa3b, v11
	v_exp_f32_e32 v14, v14
	v_exp_f32_e32 v15, v15
	v_add_f32_e32 v14, 1.0, v14
	v_add_f32_e32 v15, 1.0, v15
	v_rcp_f32_e32 v14, v14
	v_rcp_f32_e32 v15, v15
	s_nop 0
	v_pk_mul_f32 v[10:11], v[10:11], v[14:15]
	s_nop 0
	v_pk_mul_f32 v[10:11], v[2:3], v[10:11]
	v_pk_mul_f32 v[2:3], v[16:17], v[140:141] op_sel_hi:[1,0]
	s_nop 0
	v_mul_f32_e32 v14, 0xbfb8aa3b, v2
	v_mul_f32_e32 v15, 0xbfb8aa3b, v3
	v_exp_f32_e32 v14, v14
	v_exp_f32_e32 v15, v15
	v_add_f32_e32 v14, 1.0, v14
	v_add_f32_e32 v15, 1.0, v15
	v_rcp_f32_e32 v14, v14
	v_rcp_f32_e32 v15, v15
	s_nop 0
	v_pk_mul_f32 v[2:3], v[2:3], v[14:15]
	s_nop 0
	v_pk_mul_f32 v[8:9], v[8:9], v[2:3]
	v_pk_mul_f32 v[2:3], v[12:13], v[140:141] op_sel_hi:[1,0]
	s_nop 0
	v_mul_f32_e32 v12, 0xbfb8aa3b, v2
	v_mul_f32_e32 v13, 0xbfb8aa3b, v3
	v_exp_f32_e32 v12, v12
	v_exp_f32_e32 v13, v13
	v_add_f32_e32 v12, 1.0, v12
	v_add_f32_e32 v13, 1.0, v13
	v_rcp_f32_e32 v12, v12
	v_rcp_f32_e32 v13, v13
	s_nop 0
	v_pk_mul_f32 v[2:3], v[2:3], v[12:13]
	s_nop 0
	v_pk_mul_f32 v[12:13], v[4:5], v[2:3]
	v_cvt_pk_bf16_f32 v2, v6, v7
	v_add_u32_e32 v6, 0xb0, v153
	v_ashrrev_i32_e32 v7, 31, v6
	v_cvt_pk_bf16_f32 v3, v8, v9
	v_mul_lo_u32 v8, s12, v7
	v_mul_lo_u32 v9, s13, v6
	v_mad_u64_u32 v[6:7], s[4:5], s12, v6, 0
	v_add3_u32 v7, v7, v8, v9
	v_lshl_add_u64 v[6:7], v[6:7], 1, s[62:63]
	v_cvt_pk_bf16_f32 v4, v10, v11
	v_cvt_pk_bf16_f32 v5, v12, v13
	v_lshl_add_u64 v[6:7], v[6:7], 0, v[114:115]
	s_mov_b64 s[4:5], s[64:65]
	global_store_dwordx4 v[6:7], v[2:5], off
	s_cbranch_vccz .LBB0_813
	s_branch .LBB0_828
